# LN1 and LN2 wave sums without LDS (DPP quad_perm/mirror + permlane16/32 swap, same pairing); stale waits before the gamma/beta preload dropped
# speedup vs baseline: 1.0068x; 1.0024x over previous
.LBB0_596:
	v_lshl_add_u64 v[38:39], s[72:73], 0, v[32:33]
	global_load_dwordx4 v[2:5], v[18:19], off offset:16
	global_load_dwordx4 v[6:9], v[18:19], off
	global_load_dwordx4 v[10:13], v[20:21], off offset:16
	global_load_dwordx4 v[14:17], v[20:21], off
	v_add_co_u32_e32 v72, vcc, 0xeb00000, v38
	v_add_co_u32_e64 v34, s[0:1], s7, v38
	s_nop 0
	v_addc_co_u32_e32 v73, vcc, 0, v39, vcc
	global_load_dwordx4 v[56:59], v[72:73], off
	global_load_dwordx4 v[60:63], v[72:73], off offset:1024
	global_load_dwordx4 v[64:67], v[72:73], off offset:2048
	global_load_dwordx4 v[68:71], v[72:73], off offset:3072
	v_addc_co_u32_e64 v35, s[0:1], 0, v39, s[0:1]
	v_lshl_add_u64 v[36:37], s[72:73], 0, v[30:31]
	v_add_co_u32_e64 v36, s[0:1], s13, v36
	v_mov_b32_e32 v40, 0
	s_nop 0
	v_addc_co_u32_e64 v37, s[0:1], 0, v37, s[0:1]
	v_mov_b32_e32 v41, 0
	v_mov_b32_e32 v42, 0
	v_mov_b32_e32 v43, 0
	v_mov_b32_e32 v44, 0
	v_mov_b32_e32 v45, 0
	s_add_i32 s4, s4, s6
	v_lshl_add_u64 v[30:31], v[30:31], 0, s[8:9]
	v_lshl_add_u64 v[32:33], v[32:33], 0, s[10:11]
	s_cmpk_lt_i32 s4, 0x4000
	s_waitcnt vmcnt(0)
	v_mov_b32_e32 v76, v3
	v_mov_b32_e32 v3, v5
	v_mov_b32_e32 v79, v12
	v_mov_b32_e32 v75, v16
	v_mov_b32_e32 v74, v15
	v_mov_b32_e32 v15, v17
	v_mov_b32_e32 v78, v11
	v_lshlrev_b32_e32 v12, 16, v56
	v_and_b32_e32 v16, 0xffff0000, v56
	v_add_f32_e32 v5, 0, v12
	v_lshlrev_b32_e32 v17, 16, v57
	v_add_f32_e32 v5, v5, v16
	v_mov_b32_e32 v11, v13
	v_and_b32_e32 v13, 0xffff0000, v57
	v_add_f32_e32 v5, v5, v17
	v_lshlrev_b32_e32 v38, 16, v58
	v_add_f32_e32 v5, v5, v13
	v_and_b32_e32 v56, 0xffff0000, v58
	v_add_f32_e32 v5, v5, v38
	v_lshlrev_b32_e32 v57, 16, v59
	v_add_f32_e32 v5, v5, v56
	v_and_b32_e32 v39, 0xffff0000, v59
	v_add_f32_e32 v5, v5, v57
	v_lshlrev_b32_e32 v58, 16, v60
	v_add_f32_e32 v5, v5, v39
	v_and_b32_e32 v80, 0xffff0000, v60
	v_add_f32_e32 v5, v5, v58
	v_lshlrev_b32_e32 v81, 16, v61
	v_add_f32_e32 v5, v5, v80
	v_and_b32_e32 v59, 0xffff0000, v61
	v_add_f32_e32 v5, v5, v81
	v_lshlrev_b32_e32 v60, 16, v62
	v_add_f32_e32 v5, v5, v59
	v_and_b32_e32 v82, 0xffff0000, v62
	v_add_f32_e32 v5, v5, v60
	v_lshlrev_b32_e32 v83, 16, v63
	v_add_f32_e32 v5, v5, v82
	v_and_b32_e32 v61, 0xffff0000, v63
	v_add_f32_e32 v5, v5, v83
	v_lshlrev_b32_e32 v62, 16, v64
	v_add_f32_e32 v5, v5, v61
	v_and_b32_e32 v84, 0xffff0000, v64
	v_add_f32_e32 v5, v5, v62
	v_lshlrev_b32_e32 v85, 16, v65
	v_add_f32_e32 v5, v5, v84
	v_and_b32_e32 v63, 0xffff0000, v65
	v_add_f32_e32 v5, v5, v85
	v_lshlrev_b32_e32 v64, 16, v66
	v_add_f32_e32 v5, v5, v63
	v_and_b32_e32 v86, 0xffff0000, v66
	v_add_f32_e32 v5, v5, v64
	v_lshlrev_b32_e32 v87, 16, v67
	v_add_f32_e32 v5, v5, v86
	v_and_b32_e32 v65, 0xffff0000, v67
	v_add_f32_e32 v5, v5, v87
	v_lshlrev_b32_e32 v66, 16, v68
	v_add_f32_e32 v5, v5, v65
	v_and_b32_e32 v88, 0xffff0000, v68
	v_add_f32_e32 v5, v5, v66
	v_lshlrev_b32_e32 v89, 16, v69
	v_add_f32_e32 v5, v5, v88
	v_and_b32_e32 v67, 0xffff0000, v69
	v_add_f32_e32 v5, v5, v89
	v_mov_b32_e32 v77, v4
	v_lshlrev_b32_e32 v4, 16, v70
	v_add_f32_e32 v5, v5, v67
	v_mov_b32_e32 v73, v8
	v_and_b32_e32 v8, 0xffff0000, v70
	v_add_f32_e32 v5, v5, v4
	v_lshlrev_b32_e32 v69, 16, v71
	v_add_f32_e32 v5, v5, v8
	v_and_b32_e32 v68, 0xffff0000, v71
	v_add_f32_e32 v5, v5, v69
	v_add_f32_e32 v5, v5, v68
	v_mov_b32_e32 v72, v7
	v_mov_b32_e32 v7, v9
	s_nop 1
	v_mov_b32_dpp v9, v5 quad_perm:[1,0,3,2] row_mask:0xf bank_mask:0xf
	s_waitcnt lgkmcnt(0)
	v_add_f32_e32 v5, v5, v9
	s_nop 1
	v_mov_b32_dpp v9, v5 quad_perm:[2,3,0,1] row_mask:0xf bank_mask:0xf
	s_waitcnt lgkmcnt(0)
	v_add_f32_e32 v5, v5, v9
	s_nop 1
	v_mov_b32_dpp v9, v5 row_half_mirror row_mask:0xf bank_mask:0xf
	s_waitcnt lgkmcnt(0)
	v_add_f32_e32 v5, v5, v9
	s_nop 1
	v_mov_b32_dpp v9, v5 row_mirror row_mask:0xf bank_mask:0xf
	s_waitcnt lgkmcnt(0)
	v_add_f32_e32 v5, v5, v9
	v_mov_b32_e32 v9, v5
	v_mov_b32_e32 v244, v5
	s_nop 1
	v_permlane16_swap_b32 v9, v244
	s_nop 1
	s_waitcnt lgkmcnt(0)
	v_add_f32_e32 v5, v9, v244
	v_mov_b32_e32 v9, v5
	v_mov_b32_e32 v244, v5
	s_nop 1
	v_permlane32_swap_b32 v9, v244
	s_nop 1
	s_waitcnt lgkmcnt(0)
	v_add_f32_e32 v5, v9, v244
	v_mul_f32_e32 v46, 0x3a000000, v5
	v_pk_add_f32 v[70:71], v[12:13], v[46:47] op_sel_hi:[1,0] neg_lo:[0,1] neg_hi:[0,1]
	v_pk_add_f32 v[90:91], v[16:17], v[46:47] op_sel_hi:[1,0] neg_lo:[0,1] neg_hi:[0,1]
	v_pk_add_f32 v[92:93], v[38:39], v[46:47] op_sel_hi:[1,0] neg_lo:[0,1] neg_hi:[0,1]
	v_pk_add_f32 v[12:13], v[66:67], v[46:47] op_sel_hi:[1,0] neg_lo:[0,1] neg_hi:[0,1]
	v_pk_add_f32 v[38:39], v[68:69], v[46:47] op_sel_hi:[1,0] neg_lo:[0,1] neg_hi:[0,1]
	v_pk_mul_f32 v[66:67], v[70:71], v[70:71]
	v_pk_mul_f32 v[68:69], v[90:91], v[90:91]
	v_fmac_f32_e32 v4, 0xba000000, v5
	v_fmac_f32_e32 v8, 0xba000000, v5
	v_add_f32_e32 v5, v66, v68
	v_add_f32_e32 v5, v69, v5
	v_pk_add_f32 v[56:57], v[56:57], v[46:47] op_sel_hi:[1,0] neg_lo:[0,1] neg_hi:[0,1]
	v_pk_add_f32 v[16:17], v[88:89], v[46:47] op_sel_hi:[1,0] neg_lo:[0,1] neg_hi:[0,1]
	v_pk_mul_f32 v[88:89], v[92:93], v[92:93]
	v_add_f32_e32 v5, v67, v5
	v_pk_mul_f32 v[94:95], v[56:57], v[56:57]
	v_add_f32_e32 v5, v88, v5
	v_add_f32_e32 v5, v94, v5
	v_pk_add_f32 v[58:59], v[58:59], v[46:47] op_sel_hi:[1,0] neg_lo:[0,1] neg_hi:[0,1]
	v_add_f32_e32 v5, v95, v5
	v_pk_add_f32 v[80:81], v[80:81], v[46:47] op_sel_hi:[1,0] neg_lo:[0,1] neg_hi:[0,1]
	v_pk_mul_f32 v[96:97], v[58:59], v[58:59]
	v_add_f32_e32 v5, v89, v5
	v_pk_mul_f32 v[98:99], v[80:81], v[80:81]
	v_add_f32_e32 v5, v96, v5
	v_add_f32_e32 v5, v98, v5
	v_pk_add_f32 v[60:61], v[60:61], v[46:47] op_sel_hi:[1,0] neg_lo:[0,1] neg_hi:[0,1]
	v_add_f32_e32 v5, v99, v5
	v_pk_add_f32 v[82:83], v[82:83], v[46:47] op_sel_hi:[1,0] neg_lo:[0,1] neg_hi:[0,1]
	v_pk_mul_f32 v[100:101], v[60:61], v[60:61]
	v_add_f32_e32 v5, v97, v5
	v_pk_mul_f32 v[102:103], v[82:83], v[82:83]
	v_add_f32_e32 v5, v100, v5
	v_add_f32_e32 v5, v102, v5
	v_pk_add_f32 v[62:63], v[62:63], v[46:47] op_sel_hi:[1,0] neg_lo:[0,1] neg_hi:[0,1]
	v_add_f32_e32 v5, v103, v5
	v_pk_add_f32 v[84:85], v[84:85], v[46:47] op_sel_hi:[1,0] neg_lo:[0,1] neg_hi:[0,1]
	v_pk_mul_f32 v[104:105], v[62:63], v[62:63]
	v_add_f32_e32 v5, v101, v5
	v_pk_mul_f32 v[106:107], v[84:85], v[84:85]
	v_add_f32_e32 v5, v104, v5
	v_add_f32_e32 v5, v106, v5
	v_pk_add_f32 v[64:65], v[64:65], v[46:47] op_sel_hi:[1,0] neg_lo:[0,1] neg_hi:[0,1]
	v_add_f32_e32 v5, v107, v5
	v_pk_add_f32 v[86:87], v[86:87], v[46:47] op_sel_hi:[1,0] neg_lo:[0,1] neg_hi:[0,1]
	v_pk_mul_f32 v[108:109], v[64:65], v[64:65]
	v_add_f32_e32 v5, v105, v5
	v_pk_mul_f32 v[110:111], v[86:87], v[86:87]
	v_add_f32_e32 v5, v108, v5
	v_add_f32_e32 v5, v110, v5
	v_add_f32_e32 v5, v111, v5
	v_pk_mul_f32 v[112:113], v[12:13], v[12:13]
	v_add_f32_e32 v5, v109, v5
	v_pk_mul_f32 v[114:115], v[16:17], v[16:17]
	v_add_f32_e32 v5, v112, v5
	v_add_f32_e32 v5, v114, v5
	v_add_f32_e32 v5, v115, v5
	v_add_f32_e32 v5, v113, v5
	v_fmac_f32_e32 v5, v4, v4
	v_pk_mul_f32 v[116:117], v[38:39], v[38:39]
	v_fmac_f32_e32 v5, v8, v8
	v_add_f32_e32 v5, v117, v5
	v_add_f32_e32 v5, v116, v5
	s_nop 1
	v_mov_b32_dpp v9, v5 quad_perm:[1,0,3,2] row_mask:0xf bank_mask:0xf
	s_waitcnt lgkmcnt(0)
	v_add_f32_e32 v5, v5, v9
	s_nop 1
	v_mov_b32_dpp v9, v5 quad_perm:[2,3,0,1] row_mask:0xf bank_mask:0xf
	s_waitcnt lgkmcnt(0)
	v_add_f32_e32 v5, v5, v9
	s_nop 1
	v_mov_b32_dpp v9, v5 row_half_mirror row_mask:0xf bank_mask:0xf
	s_waitcnt lgkmcnt(0)
	v_add_f32_e32 v5, v5, v9
	s_nop 1
	v_mov_b32_dpp v9, v5 row_mirror row_mask:0xf bank_mask:0xf
	s_waitcnt lgkmcnt(0)
	v_add_f32_e32 v5, v5, v9
	v_mov_b32_e32 v9, v5
	v_mov_b32_e32 v244, v5
	s_nop 1
	v_permlane16_swap_b32 v9, v244
	s_nop 1
	s_waitcnt lgkmcnt(0)
	v_add_f32_e32 v5, v9, v244
	v_mov_b32_e32 v9, v5
	v_mov_b32_e32 v244, v5
	s_nop 1
	v_permlane32_swap_b32 v9, v244
	s_nop 1
	s_waitcnt lgkmcnt(0)
	v_add_f32_e32 v5, v9, v244
	v_fmamk_f32 v5, v5, 0x3a000000, v52
	v_mul_f32_e32 v9, 0x4f800000, v5
	v_cmp_gt_f32_e32 vcc, s3, v5
	s_nop 1
	v_cndmask_b32_e32 v5, v5, v9, vcc
	v_sqrt_f32_e32 v9, v5
	s_nop 0
	v_add_u32_e32 v46, -1, v9
	v_add_u32_e32 v66, 1, v9
	v_fma_f32 v67, -v46, v9, v5
	v_fma_f32 v68, -v66, v9, v5
	v_cmp_ge_f32_e64 s[0:1], 0, v67
	s_nop 1
	v_cndmask_b32_e64 v9, v9, v46, s[0:1]
	v_cmp_lt_f32_e64 s[0:1], 0, v68
	s_nop 1
	v_cndmask_b32_e64 v9, v9, v66, s[0:1]
	v_mul_f32_e32 v46, 0x37800000, v9
	v_cndmask_b32_e32 v9, v9, v46, vcc
	v_cmp_class_f32_e32 vcc, v5, v53
	s_nop 1
	v_cndmask_b32_e32 v5, v9, v5, vcc
	v_div_scale_f32 v9, s[0:1], v5, v5, 1.0
	v_rcp_f32_e32 v66, v9
	v_div_scale_f32 v46, vcc, 1.0, v5, 1.0
	v_fma_f32 v67, -v9, v66, 1.0
	v_fmac_f32_e32 v66, v67, v66
	v_mul_f32_e32 v67, v46, v66
	v_fma_f32 v68, -v9, v67, v46
	v_fmac_f32_e32 v67, v68, v66
	v_fma_f32 v9, -v9, v67, v46
	v_div_fmas_f32 v9, v9, v66, v67
	v_div_fixup_f32 v46, v9, v5, 1.0
	v_pk_mul_f32 v[66:67], v[90:91], v[46:47] op_sel_hi:[1,0]
	v_pk_mul_f32 v[68:69], v[70:71], v[46:47] op_sel_hi:[1,0]
	v_pk_mul_f32 v[56:57], v[56:57], v[46:47] op_sel_hi:[1,0]
	v_pk_mul_f32 v[70:71], v[92:93], v[46:47] op_sel_hi:[1,0]
	v_pk_mul_f32 v[88:89], v[58:59], v[46:47] op_sel_hi:[1,0]
	v_pk_fma_f32 v[58:59], v[72:73], v[66:67], v[74:75]
	v_pk_fma_f32 v[6:7], v[6:7], v[68:69], v[14:15]
	v_pk_fma_f32 v[14:15], v[76:77], v[56:57], v[78:79]
	v_pk_fma_f32 v[2:3], v[2:3], v[70:71], v[10:11]
	v_pk_mul_f32 v[90:91], v[60:61], v[46:47] op_sel_hi:[1,0]
	v_and_b32_sdwa v9, v58, v55 dst_sel:DWORD dst_unused:UNUSED_PAD src0_sel:WORD_1 src1_sel:DWORD
	v_and_b32_sdwa v10, v7, v55 dst_sel:DWORD dst_unused:UNUSED_PAD src0_sel:WORD_1 src1_sel:DWORD
	v_and_b32_sdwa v11, v6, v55 dst_sel:DWORD dst_unused:UNUSED_PAD src0_sel:WORD_1 src1_sel:DWORD
	v_and_b32_sdwa v57, v14, v55 dst_sel:DWORD dst_unused:UNUSED_PAD src0_sel:WORD_1 src1_sel:DWORD
	v_and_b32_sdwa v60, v3, v55 dst_sel:DWORD dst_unused:UNUSED_PAD src0_sel:WORD_1 src1_sel:DWORD
	v_and_b32_sdwa v61, v2, v55 dst_sel:DWORD dst_unused:UNUSED_PAD src0_sel:WORD_1 src1_sel:DWORD
	v_and_b32_sdwa v5, v59, v55 dst_sel:DWORD dst_unused:UNUSED_PAD src0_sel:WORD_1 src1_sel:DWORD
	v_and_b32_sdwa v56, v15, v55 dst_sel:DWORD dst_unused:UNUSED_PAD src0_sel:WORD_1 src1_sel:DWORD
	v_add3_u32 v9, v58, v9, s5
	v_add3_u32 v7, v7, v10, s5
	v_add3_u32 v6, v6, v11, s5
	v_add3_u32 v11, v14, v57, s5
	v_add3_u32 v3, v3, v60, s5
	v_add3_u32 v2, v2, v61, s5
	v_add3_u32 v5, v59, v5, s5
	v_add3_u32 v10, v15, v56, s5
	v_and_b32_e32 v9, 0xffff0000, v9
	v_and_b32_e32 v7, 0xffff0000, v7
	v_and_b32_e32 v11, 0xffff0000, v11
	v_and_b32_e32 v3, 0xffff0000, v3
	v_and_b32_e32 v14, 0xffff0000, v6
	v_and_b32_e32 v60, 0xffff0000, v2
	v_and_b32_e32 v15, 0xffff0000, v5
	v_and_b32_e32 v61, 0xffff0000, v10
	v_or_b32_sdwa v57, v7, v5 dst_sel:DWORD dst_unused:UNUSED_PAD src0_sel:DWORD src1_sel:WORD_1
	v_or_b32_sdwa v56, v6, v9 dst_sel:DWORD dst_unused:UNUSED_PAD src0_sel:WORD_1 src1_sel:DWORD
	v_or_b32_sdwa v59, v3, v10 dst_sel:DWORD dst_unused:UNUSED_PAD src0_sel:DWORD src1_sel:WORD_1
	v_or_b32_sdwa v58, v2, v11 dst_sel:DWORD dst_unused:UNUSED_PAD src0_sel:WORD_1 src1_sel:DWORD
	v_mul_f32_e32 v2, 0x42000000, v14
	v_mul_f32_e32 v5, 0x42000000, v9
	v_mul_f32_e32 v9, 0x42000000, v60
	v_mul_f32_e32 v10, 0x42000000, v11
	v_med3_f32 v2, v2, s12, v54
	v_med3_f32 v5, v5, s12, v54
	v_med3_f32 v9, v9, s12, v54
	v_med3_f32 v10, v10, s12, v54
	v_cvt_pk_fp8_f32 v40, v2, v5
	v_cvt_pk_fp8_f32 v41, v9, v10
	v_mul_f32_e32 v6, 0x42000000, v15
	v_mul_f32_e32 v7, 0x42000000, v7
	v_mul_f32_e32 v11, 0x42000000, v61
	v_mul_f32_e32 v3, 0x42000000, v3
	v_med3_f32 v6, v6, s12, v54
	v_med3_f32 v7, v7, s12, v54
	v_med3_f32 v11, v11, s12, v54
	v_med3_f32 v3, v3, s12, v54
	v_cvt_pk_fp8_f32 v40, v6, v7 op_sel:[0,0,1]
	v_cvt_pk_fp8_f32 v41, v11, v3 op_sel:[0,0,1]
	global_store_dwordx4 v[34:35], v[56:59], off
	v_pk_mul_f32 v[92:93], v[62:63], v[46:47] op_sel_hi:[1,0]
	v_pk_mul_f32 v[94:95], v[64:65], v[46:47] op_sel_hi:[1,0]
	global_store_dwordx2 v[36:37], v[40:41], off
	global_load_dwordx4 v[56:59], v[18:19], off offset:2048
	global_load_dwordx4 v[60:63], v[20:21], off offset:2048
	global_load_dwordx4 v[64:67], v[18:19], off offset:2064
	global_load_dwordx4 v[68:71], v[20:21], off offset:2064
	v_pk_mul_f32 v[80:81], v[80:81], v[46:47] op_sel_hi:[1,0]
	v_pk_mul_f32 v[82:83], v[82:83], v[46:47] op_sel_hi:[1,0]
	v_pk_mul_f32 v[84:85], v[84:85], v[46:47] op_sel_hi:[1,0]
	v_pk_mul_f32 v[86:87], v[86:87], v[46:47] op_sel_hi:[1,0]
	s_waitcnt vmcnt(3)
	v_mov_b32_e32 v2, v57
	v_mov_b32_e32 v3, v58
	s_waitcnt vmcnt(2)
	v_mov_b32_e32 v6, v61
	v_mov_b32_e32 v7, v62
	v_mov_b32_e32 v57, v59
	v_mov_b32_e32 v61, v63
	s_waitcnt vmcnt(1)
	v_mov_b32_e32 v10, v65
	v_mov_b32_e32 v11, v66
	s_waitcnt vmcnt(0)
	v_mov_b32_e32 v14, v69
	v_mov_b32_e32 v15, v70
	v_mov_b32_e32 v65, v67
	v_mov_b32_e32 v69, v71
	v_pk_fma_f32 v[2:3], v[2:3], v[80:81], v[6:7]
	v_pk_fma_f32 v[6:7], v[56:57], v[88:89], v[60:61]
	v_pk_fma_f32 v[10:11], v[10:11], v[82:83], v[14:15]
	v_pk_fma_f32 v[14:15], v[64:65], v[90:91], v[68:69]
	v_and_b32_sdwa v5, v3, v55 dst_sel:DWORD dst_unused:UNUSED_PAD src0_sel:WORD_1 src1_sel:DWORD
	v_and_b32_sdwa v9, v2, v55 dst_sel:DWORD dst_unused:UNUSED_PAD src0_sel:WORD_1 src1_sel:DWORD
	v_and_b32_sdwa v40, v7, v55 dst_sel:DWORD dst_unused:UNUSED_PAD src0_sel:WORD_1 src1_sel:DWORD
	v_and_b32_sdwa v41, v6, v55 dst_sel:DWORD dst_unused:UNUSED_PAD src0_sel:WORD_1 src1_sel:DWORD
	v_and_b32_sdwa v56, v11, v55 dst_sel:DWORD dst_unused:UNUSED_PAD src0_sel:WORD_1 src1_sel:DWORD
	v_and_b32_sdwa v57, v10, v55 dst_sel:DWORD dst_unused:UNUSED_PAD src0_sel:WORD_1 src1_sel:DWORD
	v_and_b32_sdwa v58, v15, v55 dst_sel:DWORD dst_unused:UNUSED_PAD src0_sel:WORD_1 src1_sel:DWORD
	v_and_b32_sdwa v59, v14, v55 dst_sel:DWORD dst_unused:UNUSED_PAD src0_sel:WORD_1 src1_sel:DWORD
	v_add3_u32 v3, v3, v5, s5
	v_add3_u32 v2, v2, v9, s5
	v_add3_u32 v5, v7, v40, s5
	v_add3_u32 v6, v6, v41, s5
	v_add3_u32 v7, v11, v56, s5
	v_add3_u32 v9, v10, v57, s5
	v_add3_u32 v10, v15, v58, s5
	v_add3_u32 v11, v14, v59, s5
	v_and_b32_e32 v2, 0xffff0000, v2
	v_and_b32_e32 v5, 0xffff0000, v5
	v_and_b32_e32 v9, 0xffff0000, v9
	v_and_b32_e32 v10, 0xffff0000, v10
	v_and_b32_e32 v14, 0xffff0000, v6
	v_and_b32_e32 v40, 0xffff0000, v11
	v_and_b32_e32 v15, 0xffff0000, v3
	v_and_b32_e32 v41, 0xffff0000, v7
	v_or_b32_sdwa v57, v5, v3 dst_sel:DWORD dst_unused:UNUSED_PAD src0_sel:DWORD src1_sel:WORD_1
	v_or_b32_sdwa v56, v6, v2 dst_sel:DWORD dst_unused:UNUSED_PAD src0_sel:WORD_1 src1_sel:DWORD
	v_or_b32_sdwa v59, v10, v7 dst_sel:DWORD dst_unused:UNUSED_PAD src0_sel:DWORD src1_sel:WORD_1
	v_or_b32_sdwa v58, v11, v9 dst_sel:DWORD dst_unused:UNUSED_PAD src0_sel:WORD_1 src1_sel:DWORD
	v_mul_f32_e32 v3, 0x42000000, v14
	v_mul_f32_e32 v2, 0x42000000, v2
	v_mul_f32_e32 v7, 0x42000000, v40
	v_mul_f32_e32 v9, 0x42000000, v9
	v_med3_f32 v3, v3, s12, v54
	v_med3_f32 v2, v2, s12, v54
	v_med3_f32 v7, v7, s12, v54
	v_med3_f32 v9, v9, s12, v54
	v_cvt_pk_fp8_f32 v42, v3, v2
	v_cvt_pk_fp8_f32 v43, v7, v9
	v_mul_f32_e32 v6, 0x42000000, v15
	v_mul_f32_e32 v5, 0x42000000, v5
	v_mul_f32_e32 v11, 0x42000000, v41
	v_mul_f32_e32 v10, 0x42000000, v10
	v_med3_f32 v6, v6, s12, v54
	v_med3_f32 v5, v5, s12, v54
	v_med3_f32 v11, v11, s12, v54
	v_med3_f32 v10, v10, s12, v54
	v_cvt_pk_fp8_f32 v42, v6, v5 op_sel:[0,0,1]
	v_cvt_pk_fp8_f32 v43, v11, v10 op_sel:[0,0,1]
	global_store_dwordx4 v[34:35], v[56:59], off offset:1024
	global_store_dwordx2 v[36:37], v[42:43], off offset:512
	global_load_dwordx4 v[40:43], v[22:23], off
	s_nop 0
	global_load_dwordx4 v[56:59], v[24:25], off
	global_load_dwordx4 v[60:63], v[22:23], off offset:16
	global_load_dwordx4 v[64:67], v[24:25], off offset:16
	s_waitcnt vmcnt(3)
	v_mov_b32_e32 v2, v41
	v_mov_b32_e32 v3, v42
	s_waitcnt vmcnt(2)
	v_mov_b32_e32 v6, v57
	v_mov_b32_e32 v7, v58
	v_mov_b32_e32 v41, v43
	v_mov_b32_e32 v57, v59
	s_waitcnt vmcnt(1)
	v_mov_b32_e32 v10, v61
	v_mov_b32_e32 v11, v62
	s_waitcnt vmcnt(0)
	v_mov_b32_e32 v14, v65
	v_mov_b32_e32 v15, v66
	v_mov_b32_e32 v61, v63
	v_mov_b32_e32 v65, v67
	v_pk_fma_f32 v[2:3], v[2:3], v[84:85], v[6:7]
	v_pk_fma_f32 v[6:7], v[40:41], v[92:93], v[56:57]
	v_pk_fma_f32 v[10:11], v[10:11], v[86:87], v[14:15]
	v_pk_fma_f32 v[14:15], v[60:61], v[94:95], v[64:65]
	v_and_b32_sdwa v5, v3, v55 dst_sel:DWORD dst_unused:UNUSED_PAD src0_sel:WORD_1 src1_sel:DWORD
	v_and_b32_sdwa v9, v2, v55 dst_sel:DWORD dst_unused:UNUSED_PAD src0_sel:WORD_1 src1_sel:DWORD
	v_and_b32_sdwa v40, v7, v55 dst_sel:DWORD dst_unused:UNUSED_PAD src0_sel:WORD_1 src1_sel:DWORD
	v_and_b32_sdwa v41, v6, v55 dst_sel:DWORD dst_unused:UNUSED_PAD src0_sel:WORD_1 src1_sel:DWORD
	v_and_b32_sdwa v42, v11, v55 dst_sel:DWORD dst_unused:UNUSED_PAD src0_sel:WORD_1 src1_sel:DWORD
	v_and_b32_sdwa v43, v10, v55 dst_sel:DWORD dst_unused:UNUSED_PAD src0_sel:WORD_1 src1_sel:DWORD
	v_and_b32_sdwa v56, v15, v55 dst_sel:DWORD dst_unused:UNUSED_PAD src0_sel:WORD_1 src1_sel:DWORD
	v_and_b32_sdwa v57, v14, v55 dst_sel:DWORD dst_unused:UNUSED_PAD src0_sel:WORD_1 src1_sel:DWORD
	v_add3_u32 v3, v3, v5, s5
	v_add3_u32 v2, v2, v9, s5
	v_add3_u32 v5, v7, v40, s5
	v_add3_u32 v6, v6, v41, s5
	v_add3_u32 v7, v11, v42, s5
	v_add3_u32 v9, v10, v43, s5
	v_add3_u32 v10, v15, v56, s5
	v_add3_u32 v11, v14, v57, s5
	v_and_b32_e32 v2, 0xffff0000, v2
	v_and_b32_e32 v5, 0xffff0000, v5
	v_and_b32_e32 v9, 0xffff0000, v9
	v_and_b32_e32 v10, 0xffff0000, v10
	v_and_b32_e32 v14, 0xffff0000, v6
	v_and_b32_e32 v56, 0xffff0000, v11
	v_and_b32_e32 v15, 0xffff0000, v3
	v_and_b32_e32 v57, 0xffff0000, v7
	v_or_b32_sdwa v41, v5, v3 dst_sel:DWORD dst_unused:UNUSED_PAD src0_sel:DWORD src1_sel:WORD_1
	v_or_b32_sdwa v40, v6, v2 dst_sel:DWORD dst_unused:UNUSED_PAD src0_sel:WORD_1 src1_sel:DWORD
	v_or_b32_sdwa v43, v10, v7 dst_sel:DWORD dst_unused:UNUSED_PAD src0_sel:DWORD src1_sel:WORD_1
	v_or_b32_sdwa v42, v11, v9 dst_sel:DWORD dst_unused:UNUSED_PAD src0_sel:WORD_1 src1_sel:DWORD
	v_mul_f32_e32 v3, 0x42000000, v14
	v_mul_f32_e32 v2, 0x42000000, v2
	v_mul_f32_e32 v7, 0x42000000, v56
	v_mul_f32_e32 v9, 0x42000000, v9
	v_med3_f32 v3, v3, s12, v54
	v_med3_f32 v2, v2, s12, v54
	v_med3_f32 v7, v7, s12, v54
	v_med3_f32 v9, v9, s12, v54
	v_cvt_pk_fp8_f32 v44, v3, v2
	v_cvt_pk_fp8_f32 v45, v7, v9
	v_mul_f32_e32 v6, 0x42000000, v15
	v_mul_f32_e32 v5, 0x42000000, v5
	v_mul_f32_e32 v11, 0x42000000, v57
	v_mul_f32_e32 v10, 0x42000000, v10
	v_med3_f32 v6, v6, s12, v54
	v_med3_f32 v5, v5, s12, v54
	v_med3_f32 v11, v11, s12, v54
	v_med3_f32 v10, v10, s12, v54
	v_cvt_pk_fp8_f32 v44, v6, v5 op_sel:[0,0,1]
	v_cvt_pk_fp8_f32 v45, v11, v10 op_sel:[0,0,1]
	global_store_dwordx4 v[34:35], v[40:43], off offset:2048
	v_mov_b32_e32 v9, v39
	v_mov_b32_e32 v5, v38
	global_store_dwordx2 v[36:37], v[44:45], off offset:1024
	global_load_dwordx4 v[40:43], v[26:27], off
	global_load_dwordx4 v[56:59], v[28:29], off
	global_load_dwordx4 v[60:63], v[26:27], off offset:16
	global_load_dwordx4 v[64:67], v[28:29], off offset:16
	v_pk_mul_f32 v[2:3], v[16:17], v[46:47] op_sel_hi:[1,0]
	v_pk_mul_f32 v[10:11], v[12:13], v[46:47] op_sel_hi:[1,0]
	v_pk_mul_f32 v[8:9], v[8:9], v[46:47] op_sel_hi:[1,0]
	v_pk_mul_f32 v[4:5], v[4:5], v[46:47] op_sel_hi:[1,0]
	v_mov_b32_e32 v6, 0
	v_mov_b32_e32 v7, 0
	s_waitcnt vmcnt(3)
	v_mov_b32_e32 v12, v41
	v_mov_b32_e32 v13, v42
	s_waitcnt vmcnt(2)
	v_mov_b32_e32 v14, v57
	v_mov_b32_e32 v15, v58
	v_mov_b32_e32 v41, v43
	v_mov_b32_e32 v57, v59
	s_waitcnt vmcnt(1)
	v_mov_b32_e32 v16, v61
	v_mov_b32_e32 v17, v62
	s_waitcnt vmcnt(0)
	v_mov_b32_e32 v38, v65
	v_mov_b32_e32 v39, v66
	v_mov_b32_e32 v61, v63
	v_mov_b32_e32 v65, v67
	v_pk_fma_f32 v[2:3], v[12:13], v[2:3], v[14:15]
	v_pk_fma_f32 v[10:11], v[40:41], v[10:11], v[56:57]
	v_pk_fma_f32 v[8:9], v[16:17], v[8:9], v[38:39]
	v_pk_fma_f32 v[4:5], v[60:61], v[4:5], v[64:65]
	v_and_b32_sdwa v12, v3, v55 dst_sel:DWORD dst_unused:UNUSED_PAD src0_sel:WORD_1 src1_sel:DWORD
	v_and_b32_sdwa v13, v2, v55 dst_sel:DWORD dst_unused:UNUSED_PAD src0_sel:WORD_1 src1_sel:DWORD
	v_and_b32_sdwa v15, v10, v55 dst_sel:DWORD dst_unused:UNUSED_PAD src0_sel:WORD_1 src1_sel:DWORD
	v_and_b32_sdwa v17, v8, v55 dst_sel:DWORD dst_unused:UNUSED_PAD src0_sel:WORD_1 src1_sel:DWORD
	v_and_b32_sdwa v39, v4, v55 dst_sel:DWORD dst_unused:UNUSED_PAD src0_sel:WORD_1 src1_sel:DWORD
	v_and_b32_sdwa v14, v11, v55 dst_sel:DWORD dst_unused:UNUSED_PAD src0_sel:WORD_1 src1_sel:DWORD
	v_add3_u32 v3, v3, v12, s5
	v_add3_u32 v2, v2, v13, s5
	v_add3_u32 v10, v10, v15, s5
	v_add3_u32 v8, v8, v17, s5
	v_add3_u32 v4, v4, v39, s5
	v_add3_u32 v11, v11, v14, s5
	v_and_b32_e32 v12, 0xffff0000, v2
	v_and_b32_e32 v8, 0xffff0000, v8
	v_and_b32_e32 v13, 0xffff0000, v10
	v_and_b32_e32 v14, 0xffff0000, v3
	v_and_b32_e32 v15, 0xffff0000, v4
	v_or_b32_sdwa v2, v10, v12 dst_sel:DWORD dst_unused:UNUSED_PAD src0_sel:WORD_1 src1_sel:DWORD
	v_mul_f32_e32 v10, 0x42000000, v13
	v_mul_f32_e32 v12, 0x42000000, v12
	v_mul_f32_e32 v13, 0x42000000, v14
	v_mul_f32_e32 v14, 0x42000000, v15
	v_mul_f32_e32 v15, 0x42000000, v8
	v_and_b32_sdwa v16, v9, v55 dst_sel:DWORD dst_unused:UNUSED_PAD src0_sel:WORD_1 src1_sel:DWORD
	v_and_b32_sdwa v38, v5, v55 dst_sel:DWORD dst_unused:UNUSED_PAD src0_sel:WORD_1 src1_sel:DWORD
	v_med3_f32 v10, v10, s12, v54
	v_med3_f32 v12, v12, s12, v54
	v_med3_f32 v14, v14, s12, v54
	v_med3_f32 v15, v15, s12, v54
	v_add3_u32 v9, v9, v16, s5
	v_add3_u32 v5, v5, v38, s5
	v_cvt_pk_fp8_f32 v6, v10, v12
	v_cvt_pk_fp8_f32 v7, v14, v15
	v_and_b32_e32 v11, 0xffff0000, v11
	v_and_b32_e32 v5, 0xffff0000, v5
	v_and_b32_e32 v16, 0xffff0000, v9
	v_or_b32_sdwa v3, v11, v3 dst_sel:DWORD dst_unused:UNUSED_PAD src0_sel:DWORD src1_sel:WORD_1
	v_mul_f32_e32 v11, 0x42000000, v11
	v_mul_f32_e32 v16, 0x42000000, v16
	v_mul_f32_e32 v17, 0x42000000, v5
	v_med3_f32 v13, v13, s12, v54
	v_med3_f32 v11, v11, s12, v54
	v_med3_f32 v10, v16, s12, v54
	v_med3_f32 v12, v17, s12, v54
	v_cvt_pk_fp8_f32 v6, v13, v11 op_sel:[0,0,1]
	v_cvt_pk_fp8_f32 v7, v10, v12 op_sel:[0,0,1]
	v_or_b32_sdwa v5, v5, v9 dst_sel:DWORD dst_unused:UNUSED_PAD src0_sel:DWORD src1_sel:WORD_1
	v_or_b32_sdwa v4, v4, v8 dst_sel:DWORD dst_unused:UNUSED_PAD src0_sel:WORD_1 src1_sel:DWORD
	global_store_dwordx4 v[34:35], v[2:5], off offset:3072
	global_store_dwordx2 v[36:37], v[6:7], off offset:1536
	s_cbranch_scc1 .LBB0_596

.Lmy_lrow0:
	s_waitcnt vmcnt(6)
	v_readlane_b32 s4, v51, 1
	v_readlane_b32 s0, v52, 0
	v_cvt_scalef32_pk_f16_fp4 v32, v0, 1.0
	v_cvt_scalef32_pk_f16_fp4 v33, v0, 1.0 op_sel:[1,0,0]
	v_cvt_scalef32_pk_f16_fp4 v34, v0, 1.0 op_sel:[0,1,0]
	v_cvt_scalef32_pk_f16_fp4 v35, v0, 1.0 op_sel:[1,1,0]
	v_cvt_scalef32_pk_f16_fp4 v36, v1, 1.0
	v_cvt_scalef32_pk_f16_fp4 v37, v1, 1.0 op_sel:[1,0,0]
	v_cvt_scalef32_pk_f16_fp4 v38, v1, 1.0 op_sel:[0,1,0]
	v_cvt_scalef32_pk_f16_fp4 v39, v1, 1.0 op_sel:[1,1,0]
	v_cvt_scalef32_pk_f16_fp4 v40, v2, 1.0
	v_cvt_scalef32_pk_f16_fp4 v41, v2, 1.0 op_sel:[1,0,0]
	v_cvt_scalef32_pk_f16_fp4 v42, v2, 1.0 op_sel:[0,1,0]
	v_cvt_scalef32_pk_f16_fp4 v43, v2, 1.0 op_sel:[1,1,0]
	v_cvt_scalef32_pk_f16_fp4 v44, v3, 1.0
	v_cvt_scalef32_pk_f16_fp4 v45, v3, 1.0 op_sel:[1,0,0]
	v_cvt_scalef32_pk_f16_fp4 v46, v3, 1.0 op_sel:[0,1,0]
	v_cvt_scalef32_pk_f16_fp4 v47, v3, 1.0 op_sel:[1,1,0]
	buffer_load_dwordx4 v[28:31], v115, s[12:15], s4 offen
	v_pk_fma_f16 v139, v32, s0, v139
	v_pk_fma_f16 v138, v33, s0, v138
	v_pk_fma_f16 v136, v34, s0, v136
	v_pk_fma_f16 v135, v35, s0, v135
	v_pk_fma_f16 v134, v36, s0, v134
	v_pk_fma_f16 v133, v37, s0, v133
	v_pk_fma_f16 v132, v38, s0, v132
	v_pk_fma_f16 v131, v39, s0, v131
	v_pk_fma_f16 v130, v40, s0, v130
	v_pk_fma_f16 v129, v41, s0, v129
	v_pk_fma_f16 v128, v42, s0, v128
	v_pk_fma_f16 v127, v43, s0, v127
	v_pk_fma_f16 v126, v44, s0, v126
	v_pk_fma_f16 v114, v45, s0, v114
	v_pk_fma_f16 v140, v46, s0, v140
	v_pk_fma_f16 v137, v47, s0, v137
	s_waitcnt vmcnt(6)
	v_readlane_b32 s4, v48, 2
	v_readlane_b32 s0, v53, 0
	v_cvt_scalef32_pk_f16_fp4 v32, v4, 1.0
	v_cvt_scalef32_pk_f16_fp4 v33, v4, 1.0 op_sel:[1,0,0]
	v_cvt_scalef32_pk_f16_fp4 v34, v4, 1.0 op_sel:[0,1,0]
	v_cvt_scalef32_pk_f16_fp4 v35, v4, 1.0 op_sel:[1,1,0]
	v_cvt_scalef32_pk_f16_fp4 v36, v5, 1.0
	v_cvt_scalef32_pk_f16_fp4 v37, v5, 1.0 op_sel:[1,0,0]
	v_cvt_scalef32_pk_f16_fp4 v38, v5, 1.0 op_sel:[0,1,0]
	v_cvt_scalef32_pk_f16_fp4 v39, v5, 1.0 op_sel:[1,1,0]
	v_cvt_scalef32_pk_f16_fp4 v40, v6, 1.0
	v_cvt_scalef32_pk_f16_fp4 v41, v6, 1.0 op_sel:[1,0,0]
	v_cvt_scalef32_pk_f16_fp4 v42, v6, 1.0 op_sel:[0,1,0]
	v_cvt_scalef32_pk_f16_fp4 v43, v6, 1.0 op_sel:[1,1,0]
	v_cvt_scalef32_pk_f16_fp4 v44, v7, 1.0
	v_cvt_scalef32_pk_f16_fp4 v45, v7, 1.0 op_sel:[1,0,0]
	v_cvt_scalef32_pk_f16_fp4 v46, v7, 1.0 op_sel:[0,1,0]
	v_cvt_scalef32_pk_f16_fp4 v47, v7, 1.0 op_sel:[1,1,0]
	buffer_load_dwordx4 v[0:3], v115, s[12:15], s4 offen
	v_pk_fma_f16 v124, v32, s0, v124
	v_pk_fma_f16 v123, v33, s0, v123
	v_pk_fma_f16 v121, v34, s0, v121
	v_pk_fma_f16 v120, v35, s0, v120
	v_pk_fma_f16 v119, v36, s0, v119
	v_pk_fma_f16 v118, v37, s0, v118
	v_pk_fma_f16 v117, v38, s0, v117
	v_pk_fma_f16 v116, v39, s0, v116
	v_pk_fma_f16 v113, v40, s0, v113
	v_pk_fma_f16 v112, v41, s0, v112
	v_pk_fma_f16 v67, v42, s0, v67
	v_pk_fma_f16 v66, v43, s0, v66
	v_pk_fma_f16 v65, v44, s0, v65
	v_pk_fma_f16 v64, v45, s0, v64
	v_pk_fma_f16 v125, v46, s0, v125
	v_pk_fma_f16 v122, v47, s0, v122
	s_waitcnt vmcnt(6)
	v_readlane_b32 s4, v49, 2
	v_readlane_b32 s0, v54, 0
	v_cvt_scalef32_pk_f16_fp4 v32, v8, 1.0
	v_cvt_scalef32_pk_f16_fp4 v33, v8, 1.0 op_sel:[1,0,0]
	v_cvt_scalef32_pk_f16_fp4 v34, v8, 1.0 op_sel:[0,1,0]
	v_cvt_scalef32_pk_f16_fp4 v35, v8, 1.0 op_sel:[1,1,0]
	v_cvt_scalef32_pk_f16_fp4 v36, v9, 1.0
	v_cvt_scalef32_pk_f16_fp4 v37, v9, 1.0 op_sel:[1,0,0]
	v_cvt_scalef32_pk_f16_fp4 v38, v9, 1.0 op_sel:[0,1,0]
	v_cvt_scalef32_pk_f16_fp4 v39, v9, 1.0 op_sel:[1,1,0]
	v_cvt_scalef32_pk_f16_fp4 v40, v10, 1.0
	v_cvt_scalef32_pk_f16_fp4 v41, v10, 1.0 op_sel:[1,0,0]
	v_cvt_scalef32_pk_f16_fp4 v42, v10, 1.0 op_sel:[0,1,0]
	v_cvt_scalef32_pk_f16_fp4 v43, v10, 1.0 op_sel:[1,1,0]
	v_cvt_scalef32_pk_f16_fp4 v44, v11, 1.0
	v_cvt_scalef32_pk_f16_fp4 v45, v11, 1.0 op_sel:[1,0,0]
	v_cvt_scalef32_pk_f16_fp4 v46, v11, 1.0 op_sel:[0,1,0]
	v_cvt_scalef32_pk_f16_fp4 v47, v11, 1.0 op_sel:[1,1,0]
	buffer_load_dwordx4 v[4:7], v115, s[12:15], s4 offen
	v_pk_fma_f16 v74, v32, s0, v74
	v_pk_fma_f16 v73, v33, s0, v73
	v_pk_fma_f16 v71, v34, s0, v71
	v_pk_fma_f16 v70, v35, s0, v70
	v_pk_fma_f16 v69, v36, s0, v69
	v_pk_fma_f16 v68, v37, s0, v68
	v_pk_fma_f16 v63, v38, s0, v63
	v_pk_fma_f16 v62, v39, s0, v62
	v_pk_fma_f16 v61, v40, s0, v61
	v_pk_fma_f16 v60, v41, s0, v60
	v_pk_fma_f16 v59, v42, s0, v59
	v_pk_fma_f16 v58, v43, s0, v58
	v_pk_fma_f16 v57, v44, s0, v57
	v_pk_fma_f16 v56, v45, s0, v56
	v_pk_fma_f16 v75, v46, s0, v75
	v_pk_fma_f16 v72, v47, s0, v72
	s_waitcnt vmcnt(6)
	v_readlane_b32 s4, v50, 2
	v_readlane_b32 s0, v55, 0
	v_cvt_scalef32_pk_f16_fp4 v32, v12, 1.0
	v_cvt_scalef32_pk_f16_fp4 v33, v12, 1.0 op_sel:[1,0,0]
	v_cvt_scalef32_pk_f16_fp4 v34, v12, 1.0 op_sel:[0,1,0]
	v_cvt_scalef32_pk_f16_fp4 v35, v12, 1.0 op_sel:[1,1,0]
	v_cvt_scalef32_pk_f16_fp4 v36, v13, 1.0
	v_cvt_scalef32_pk_f16_fp4 v37, v13, 1.0 op_sel:[1,0,0]
	v_cvt_scalef32_pk_f16_fp4 v38, v13, 1.0 op_sel:[0,1,0]
	v_cvt_scalef32_pk_f16_fp4 v39, v13, 1.0 op_sel:[1,1,0]
	v_cvt_scalef32_pk_f16_fp4 v40, v14, 1.0
	v_cvt_scalef32_pk_f16_fp4 v41, v14, 1.0 op_sel:[1,0,0]
	v_cvt_scalef32_pk_f16_fp4 v42, v14, 1.0 op_sel:[0,1,0]
	v_cvt_scalef32_pk_f16_fp4 v43, v14, 1.0 op_sel:[1,1,0]
	v_cvt_scalef32_pk_f16_fp4 v44, v15, 1.0
	v_cvt_scalef32_pk_f16_fp4 v45, v15, 1.0 op_sel:[1,0,0]
	v_cvt_scalef32_pk_f16_fp4 v46, v15, 1.0 op_sel:[0,1,0]
	v_cvt_scalef32_pk_f16_fp4 v47, v15, 1.0 op_sel:[1,1,0]
	buffer_load_dwordx4 v[8:11], v115, s[12:15], s4 offen
	v_pk_fma_f16 v162, v32, s0, v162
	v_pk_fma_f16 v161, v33, s0, v161
	v_pk_fma_f16 v160, v34, s0, v160
	v_pk_fma_f16 v159, v35, s0, v159
	v_pk_fma_f16 v158, v36, s0, v158
	v_pk_fma_f16 v157, v37, s0, v157
	v_pk_fma_f16 v156, v38, s0, v156
	v_pk_fma_f16 v147, v39, s0, v147
	v_pk_fma_f16 v146, v40, s0, v146
	v_pk_fma_f16 v145, v41, s0, v145
	v_pk_fma_f16 v144, v42, s0, v144
	v_pk_fma_f16 v143, v43, s0, v143
	v_pk_fma_f16 v142, v44, s0, v142
	v_pk_fma_f16 v141, v45, s0, v141
	v_pk_fma_f16 v149, v46, s0, v149
	v_pk_fma_f16 v148, v47, s0, v148
	s_waitcnt vmcnt(6)
	v_readlane_b32 s4, v51, 2
	v_readlane_b32 s0, v52, 1
	v_cvt_scalef32_pk_f16_fp4 v32, v16, 1.0
	v_cvt_scalef32_pk_f16_fp4 v33, v16, 1.0 op_sel:[1,0,0]
	v_cvt_scalef32_pk_f16_fp4 v34, v16, 1.0 op_sel:[0,1,0]
	v_cvt_scalef32_pk_f16_fp4 v35, v16, 1.0 op_sel:[1,1,0]
	v_cvt_scalef32_pk_f16_fp4 v36, v17, 1.0
	v_cvt_scalef32_pk_f16_fp4 v37, v17, 1.0 op_sel:[1,0,0]
	v_cvt_scalef32_pk_f16_fp4 v38, v17, 1.0 op_sel:[0,1,0]
	v_cvt_scalef32_pk_f16_fp4 v39, v17, 1.0 op_sel:[1,1,0]
	v_cvt_scalef32_pk_f16_fp4 v40, v18, 1.0
	v_cvt_scalef32_pk_f16_fp4 v41, v18, 1.0 op_sel:[1,0,0]
	v_cvt_scalef32_pk_f16_fp4 v42, v18, 1.0 op_sel:[0,1,0]
	v_cvt_scalef32_pk_f16_fp4 v43, v18, 1.0 op_sel:[1,1,0]
	v_cvt_scalef32_pk_f16_fp4 v44, v19, 1.0
	v_cvt_scalef32_pk_f16_fp4 v45, v19, 1.0 op_sel:[1,0,0]
	v_cvt_scalef32_pk_f16_fp4 v46, v19, 1.0 op_sel:[0,1,0]
	v_cvt_scalef32_pk_f16_fp4 v47, v19, 1.0 op_sel:[1,1,0]
	buffer_load_dwordx4 v[12:15], v115, s[12:15], s4 offen
	v_pk_fma_f16 v139, v32, s0, v139
	v_pk_fma_f16 v138, v33, s0, v138
	v_pk_fma_f16 v136, v34, s0, v136
	v_pk_fma_f16 v135, v35, s0, v135
	v_pk_fma_f16 v134, v36, s0, v134
	v_pk_fma_f16 v133, v37, s0, v133
	v_pk_fma_f16 v132, v38, s0, v132
	v_pk_fma_f16 v131, v39, s0, v131
	v_pk_fma_f16 v130, v40, s0, v130
	v_pk_fma_f16 v129, v41, s0, v129
	v_pk_fma_f16 v128, v42, s0, v128
	v_pk_fma_f16 v127, v43, s0, v127
	v_pk_fma_f16 v126, v44, s0, v126
	v_pk_fma_f16 v114, v45, s0, v114
	v_pk_fma_f16 v140, v46, s0, v140
	v_pk_fma_f16 v137, v47, s0, v137
	s_waitcnt vmcnt(6)
	v_readlane_b32 s4, v48, 3
	v_readlane_b32 s0, v53, 1
	v_cvt_scalef32_pk_f16_fp4 v32, v20, 1.0
	v_cvt_scalef32_pk_f16_fp4 v33, v20, 1.0 op_sel:[1,0,0]
	v_cvt_scalef32_pk_f16_fp4 v34, v20, 1.0 op_sel:[0,1,0]
	v_cvt_scalef32_pk_f16_fp4 v35, v20, 1.0 op_sel:[1,1,0]
	v_cvt_scalef32_pk_f16_fp4 v36, v21, 1.0
	v_cvt_scalef32_pk_f16_fp4 v37, v21, 1.0 op_sel:[1,0,0]
	v_cvt_scalef32_pk_f16_fp4 v38, v21, 1.0 op_sel:[0,1,0]
	v_cvt_scalef32_pk_f16_fp4 v39, v21, 1.0 op_sel:[1,1,0]
	v_cvt_scalef32_pk_f16_fp4 v40, v22, 1.0
	v_cvt_scalef32_pk_f16_fp4 v41, v22, 1.0 op_sel:[1,0,0]
	v_cvt_scalef32_pk_f16_fp4 v42, v22, 1.0 op_sel:[0,1,0]
	v_cvt_scalef32_pk_f16_fp4 v43, v22, 1.0 op_sel:[1,1,0]
	v_cvt_scalef32_pk_f16_fp4 v44, v23, 1.0
	v_cvt_scalef32_pk_f16_fp4 v45, v23, 1.0 op_sel:[1,0,0]
	v_cvt_scalef32_pk_f16_fp4 v46, v23, 1.0 op_sel:[0,1,0]
	v_cvt_scalef32_pk_f16_fp4 v47, v23, 1.0 op_sel:[1,1,0]
	buffer_load_dwordx4 v[16:19], v115, s[12:15], s4 offen
	v_pk_fma_f16 v124, v32, s0, v124
	v_pk_fma_f16 v123, v33, s0, v123
	v_pk_fma_f16 v121, v34, s0, v121
	v_pk_fma_f16 v120, v35, s0, v120
	v_pk_fma_f16 v119, v36, s0, v119
	v_pk_fma_f16 v118, v37, s0, v118
	v_pk_fma_f16 v117, v38, s0, v117
	v_pk_fma_f16 v116, v39, s0, v116
	v_pk_fma_f16 v113, v40, s0, v113
	v_pk_fma_f16 v112, v41, s0, v112
	v_pk_fma_f16 v67, v42, s0, v67
	v_pk_fma_f16 v66, v43, s0, v66
	v_pk_fma_f16 v65, v44, s0, v65
	v_pk_fma_f16 v64, v45, s0, v64
	v_pk_fma_f16 v125, v46, s0, v125
	v_pk_fma_f16 v122, v47, s0, v122
	s_waitcnt vmcnt(6)
	v_readlane_b32 s4, v49, 3
	v_readlane_b32 s0, v54, 1
	v_cvt_scalef32_pk_f16_fp4 v32, v24, 1.0
	v_cvt_scalef32_pk_f16_fp4 v33, v24, 1.0 op_sel:[1,0,0]
	v_cvt_scalef32_pk_f16_fp4 v34, v24, 1.0 op_sel:[0,1,0]
	v_cvt_scalef32_pk_f16_fp4 v35, v24, 1.0 op_sel:[1,1,0]
	v_cvt_scalef32_pk_f16_fp4 v36, v25, 1.0
	v_cvt_scalef32_pk_f16_fp4 v37, v25, 1.0 op_sel:[1,0,0]
	v_cvt_scalef32_pk_f16_fp4 v38, v25, 1.0 op_sel:[0,1,0]
	v_cvt_scalef32_pk_f16_fp4 v39, v25, 1.0 op_sel:[1,1,0]
	v_cvt_scalef32_pk_f16_fp4 v40, v26, 1.0
	v_cvt_scalef32_pk_f16_fp4 v41, v26, 1.0 op_sel:[1,0,0]
	v_cvt_scalef32_pk_f16_fp4 v42, v26, 1.0 op_sel:[0,1,0]
	v_cvt_scalef32_pk_f16_fp4 v43, v26, 1.0 op_sel:[1,1,0]
	v_cvt_scalef32_pk_f16_fp4 v44, v27, 1.0
	v_cvt_scalef32_pk_f16_fp4 v45, v27, 1.0 op_sel:[1,0,0]
	v_cvt_scalef32_pk_f16_fp4 v46, v27, 1.0 op_sel:[0,1,0]
	v_cvt_scalef32_pk_f16_fp4 v47, v27, 1.0 op_sel:[1,1,0]
	buffer_load_dwordx4 v[20:23], v115, s[12:15], s4 offen
	v_pk_fma_f16 v74, v32, s0, v74
	v_pk_fma_f16 v73, v33, s0, v73
	v_pk_fma_f16 v71, v34, s0, v71
	v_pk_fma_f16 v70, v35, s0, v70
	v_pk_fma_f16 v69, v36, s0, v69
	v_pk_fma_f16 v68, v37, s0, v68
	v_pk_fma_f16 v63, v38, s0, v63
	v_pk_fma_f16 v62, v39, s0, v62
	v_pk_fma_f16 v61, v40, s0, v61
	v_pk_fma_f16 v60, v41, s0, v60
	v_pk_fma_f16 v59, v42, s0, v59
	v_pk_fma_f16 v58, v43, s0, v58
	v_pk_fma_f16 v57, v44, s0, v57
	v_pk_fma_f16 v56, v45, s0, v56
	v_pk_fma_f16 v75, v46, s0, v75
	v_pk_fma_f16 v72, v47, s0, v72
	s_waitcnt vmcnt(6)
	v_readlane_b32 s4, v50, 3
	v_readlane_b32 s0, v55, 1
	v_cvt_scalef32_pk_f16_fp4 v32, v28, 1.0
	v_cvt_scalef32_pk_f16_fp4 v33, v28, 1.0 op_sel:[1,0,0]
	v_cvt_scalef32_pk_f16_fp4 v34, v28, 1.0 op_sel:[0,1,0]
	v_cvt_scalef32_pk_f16_fp4 v35, v28, 1.0 op_sel:[1,1,0]
	v_cvt_scalef32_pk_f16_fp4 v36, v29, 1.0
	v_cvt_scalef32_pk_f16_fp4 v37, v29, 1.0 op_sel:[1,0,0]
	v_cvt_scalef32_pk_f16_fp4 v38, v29, 1.0 op_sel:[0,1,0]
	v_cvt_scalef32_pk_f16_fp4 v39, v29, 1.0 op_sel:[1,1,0]
	v_cvt_scalef32_pk_f16_fp4 v40, v30, 1.0
	v_cvt_scalef32_pk_f16_fp4 v41, v30, 1.0 op_sel:[1,0,0]
	v_cvt_scalef32_pk_f16_fp4 v42, v30, 1.0 op_sel:[0,1,0]
	v_cvt_scalef32_pk_f16_fp4 v43, v30, 1.0 op_sel:[1,1,0]
	v_cvt_scalef32_pk_f16_fp4 v44, v31, 1.0
	v_cvt_scalef32_pk_f16_fp4 v45, v31, 1.0 op_sel:[1,0,0]
	v_cvt_scalef32_pk_f16_fp4 v46, v31, 1.0 op_sel:[0,1,0]
	v_cvt_scalef32_pk_f16_fp4 v47, v31, 1.0 op_sel:[1,1,0]
	buffer_load_dwordx4 v[24:27], v115, s[12:15], s4 offen
	v_pk_fma_f16 v162, v32, s0, v162
	v_pk_fma_f16 v161, v33, s0, v161
	v_pk_fma_f16 v160, v34, s0, v160
	v_pk_fma_f16 v159, v35, s0, v159
	v_pk_fma_f16 v158, v36, s0, v158
	v_pk_fma_f16 v157, v37, s0, v157
	v_pk_fma_f16 v156, v38, s0, v156
	v_pk_fma_f16 v147, v39, s0, v147
	v_pk_fma_f16 v146, v40, s0, v146
	v_pk_fma_f16 v145, v41, s0, v145
	v_pk_fma_f16 v144, v42, s0, v144
	v_pk_fma_f16 v143, v43, s0, v143
	v_pk_fma_f16 v142, v44, s0, v142
	v_pk_fma_f16 v141, v45, s0, v141
	v_pk_fma_f16 v149, v46, s0, v149
	v_pk_fma_f16 v148, v47, s0, v148
	s_waitcnt vmcnt(6)
	v_readlane_b32 s4, v51, 3
	v_readlane_b32 s0, v52, 2
	v_cvt_scalef32_pk_f16_fp4 v32, v0, 1.0
	v_cvt_scalef32_pk_f16_fp4 v33, v0, 1.0 op_sel:[1,0,0]
	v_cvt_scalef32_pk_f16_fp4 v34, v0, 1.0 op_sel:[0,1,0]
	v_cvt_scalef32_pk_f16_fp4 v35, v0, 1.0 op_sel:[1,1,0]
	v_cvt_scalef32_pk_f16_fp4 v36, v1, 1.0
	v_cvt_scalef32_pk_f16_fp4 v37, v1, 1.0 op_sel:[1,0,0]
	v_cvt_scalef32_pk_f16_fp4 v38, v1, 1.0 op_sel:[0,1,0]
	v_cvt_scalef32_pk_f16_fp4 v39, v1, 1.0 op_sel:[1,1,0]
	v_cvt_scalef32_pk_f16_fp4 v40, v2, 1.0
	v_cvt_scalef32_pk_f16_fp4 v41, v2, 1.0 op_sel:[1,0,0]
	v_cvt_scalef32_pk_f16_fp4 v42, v2, 1.0 op_sel:[0,1,0]
	v_cvt_scalef32_pk_f16_fp4 v43, v2, 1.0 op_sel:[1,1,0]
	v_cvt_scalef32_pk_f16_fp4 v44, v3, 1.0
	v_cvt_scalef32_pk_f16_fp4 v45, v3, 1.0 op_sel:[1,0,0]
	v_cvt_scalef32_pk_f16_fp4 v46, v3, 1.0 op_sel:[0,1,0]
	v_cvt_scalef32_pk_f16_fp4 v47, v3, 1.0 op_sel:[1,1,0]
	buffer_load_dwordx4 v[28:31], v115, s[12:15], s4 offen
	v_pk_fma_f16 v139, v32, s0, v139
	v_pk_fma_f16 v138, v33, s0, v138
	v_pk_fma_f16 v136, v34, s0, v136
	v_pk_fma_f16 v135, v35, s0, v135
	v_pk_fma_f16 v134, v36, s0, v134
	v_pk_fma_f16 v133, v37, s0, v133
	v_pk_fma_f16 v132, v38, s0, v132
	v_pk_fma_f16 v131, v39, s0, v131
	v_pk_fma_f16 v130, v40, s0, v130
	v_pk_fma_f16 v129, v41, s0, v129
	v_pk_fma_f16 v128, v42, s0, v128
	v_pk_fma_f16 v127, v43, s0, v127
	v_pk_fma_f16 v126, v44, s0, v126
	v_pk_fma_f16 v114, v45, s0, v114
	v_pk_fma_f16 v140, v46, s0, v140
	v_pk_fma_f16 v137, v47, s0, v137
	s_waitcnt vmcnt(6)
	v_readlane_b32 s4, v48, 4
	v_readlane_b32 s0, v53, 2
	v_cvt_scalef32_pk_f16_fp4 v32, v4, 1.0
	v_cvt_scalef32_pk_f16_fp4 v33, v4, 1.0 op_sel:[1,0,0]
	v_cvt_scalef32_pk_f16_fp4 v34, v4, 1.0 op_sel:[0,1,0]
	v_cvt_scalef32_pk_f16_fp4 v35, v4, 1.0 op_sel:[1,1,0]
	v_cvt_scalef32_pk_f16_fp4 v36, v5, 1.0
	v_cvt_scalef32_pk_f16_fp4 v37, v5, 1.0 op_sel:[1,0,0]
	v_cvt_scalef32_pk_f16_fp4 v38, v5, 1.0 op_sel:[0,1,0]
	v_cvt_scalef32_pk_f16_fp4 v39, v5, 1.0 op_sel:[1,1,0]
	v_cvt_scalef32_pk_f16_fp4 v40, v6, 1.0
	v_cvt_scalef32_pk_f16_fp4 v41, v6, 1.0 op_sel:[1,0,0]
	v_cvt_scalef32_pk_f16_fp4 v42, v6, 1.0 op_sel:[0,1,0]
	v_cvt_scalef32_pk_f16_fp4 v43, v6, 1.0 op_sel:[1,1,0]
	v_cvt_scalef32_pk_f16_fp4 v44, v7, 1.0
	v_cvt_scalef32_pk_f16_fp4 v45, v7, 1.0 op_sel:[1,0,0]
	v_cvt_scalef32_pk_f16_fp4 v46, v7, 1.0 op_sel:[0,1,0]
	v_cvt_scalef32_pk_f16_fp4 v47, v7, 1.0 op_sel:[1,1,0]
	buffer_load_dwordx4 v[0:3], v115, s[12:15], s4 offen
	v_pk_fma_f16 v124, v32, s0, v124
	v_pk_fma_f16 v123, v33, s0, v123
	v_pk_fma_f16 v121, v34, s0, v121
	v_pk_fma_f16 v120, v35, s0, v120
	v_pk_fma_f16 v119, v36, s0, v119
	v_pk_fma_f16 v118, v37, s0, v118
	v_pk_fma_f16 v117, v38, s0, v117
	v_pk_fma_f16 v116, v39, s0, v116
	v_pk_fma_f16 v113, v40, s0, v113
	v_pk_fma_f16 v112, v41, s0, v112
	v_pk_fma_f16 v67, v42, s0, v67
	v_pk_fma_f16 v66, v43, s0, v66
	v_pk_fma_f16 v65, v44, s0, v65
	v_pk_fma_f16 v64, v45, s0, v64
	v_pk_fma_f16 v125, v46, s0, v125
	v_pk_fma_f16 v122, v47, s0, v122
	s_waitcnt vmcnt(6)
	v_readlane_b32 s4, v49, 4
	v_readlane_b32 s0, v54, 2
	v_cvt_scalef32_pk_f16_fp4 v32, v8, 1.0
	v_cvt_scalef32_pk_f16_fp4 v33, v8, 1.0 op_sel:[1,0,0]
	v_cvt_scalef32_pk_f16_fp4 v34, v8, 1.0 op_sel:[0,1,0]
	v_cvt_scalef32_pk_f16_fp4 v35, v8, 1.0 op_sel:[1,1,0]
	v_cvt_scalef32_pk_f16_fp4 v36, v9, 1.0
	v_cvt_scalef32_pk_f16_fp4 v37, v9, 1.0 op_sel:[1,0,0]
	v_cvt_scalef32_pk_f16_fp4 v38, v9, 1.0 op_sel:[0,1,0]
	v_cvt_scalef32_pk_f16_fp4 v39, v9, 1.0 op_sel:[1,1,0]
	v_cvt_scalef32_pk_f16_fp4 v40, v10, 1.0
	v_cvt_scalef32_pk_f16_fp4 v41, v10, 1.0 op_sel:[1,0,0]
	v_cvt_scalef32_pk_f16_fp4 v42, v10, 1.0 op_sel:[0,1,0]
	v_cvt_scalef32_pk_f16_fp4 v43, v10, 1.0 op_sel:[1,1,0]
	v_cvt_scalef32_pk_f16_fp4 v44, v11, 1.0
	v_cvt_scalef32_pk_f16_fp4 v45, v11, 1.0 op_sel:[1,0,0]
	v_cvt_scalef32_pk_f16_fp4 v46, v11, 1.0 op_sel:[0,1,0]
	v_cvt_scalef32_pk_f16_fp4 v47, v11, 1.0 op_sel:[1,1,0]
	buffer_load_dwordx4 v[4:7], v115, s[12:15], s4 offen
	v_pk_fma_f16 v74, v32, s0, v74
	v_pk_fma_f16 v73, v33, s0, v73
	v_pk_fma_f16 v71, v34, s0, v71
	v_pk_fma_f16 v70, v35, s0, v70
	v_pk_fma_f16 v69, v36, s0, v69
	v_pk_fma_f16 v68, v37, s0, v68
	v_pk_fma_f16 v63, v38, s0, v63
	v_pk_fma_f16 v62, v39, s0, v62
	v_pk_fma_f16 v61, v40, s0, v61
	v_pk_fma_f16 v60, v41, s0, v60
	v_pk_fma_f16 v59, v42, s0, v59
	v_pk_fma_f16 v58, v43, s0, v58
	v_pk_fma_f16 v57, v44, s0, v57
	v_pk_fma_f16 v56, v45, s0, v56
	v_pk_fma_f16 v75, v46, s0, v75
	v_pk_fma_f16 v72, v47, s0, v72
	s_waitcnt vmcnt(6)
	v_readlane_b32 s4, v50, 4
	v_readlane_b32 s0, v55, 2
	v_cvt_scalef32_pk_f16_fp4 v32, v12, 1.0
	v_cvt_scalef32_pk_f16_fp4 v33, v12, 1.0 op_sel:[1,0,0]
	v_cvt_scalef32_pk_f16_fp4 v34, v12, 1.0 op_sel:[0,1,0]
	v_cvt_scalef32_pk_f16_fp4 v35, v12, 1.0 op_sel:[1,1,0]
	v_cvt_scalef32_pk_f16_fp4 v36, v13, 1.0
	v_cvt_scalef32_pk_f16_fp4 v37, v13, 1.0 op_sel:[1,0,0]
	v_cvt_scalef32_pk_f16_fp4 v38, v13, 1.0 op_sel:[0,1,0]
	v_cvt_scalef32_pk_f16_fp4 v39, v13, 1.0 op_sel:[1,1,0]
	v_cvt_scalef32_pk_f16_fp4 v40, v14, 1.0
	v_cvt_scalef32_pk_f16_fp4 v41, v14, 1.0 op_sel:[1,0,0]
	v_cvt_scalef32_pk_f16_fp4 v42, v14, 1.0 op_sel:[0,1,0]
	v_cvt_scalef32_pk_f16_fp4 v43, v14, 1.0 op_sel:[1,1,0]
	v_cvt_scalef32_pk_f16_fp4 v44, v15, 1.0
	v_cvt_scalef32_pk_f16_fp4 v45, v15, 1.0 op_sel:[1,0,0]
	v_cvt_scalef32_pk_f16_fp4 v46, v15, 1.0 op_sel:[0,1,0]
	v_cvt_scalef32_pk_f16_fp4 v47, v15, 1.0 op_sel:[1,1,0]
	buffer_load_dwordx4 v[8:11], v115, s[12:15], s4 offen
	v_pk_fma_f16 v162, v32, s0, v162
	v_pk_fma_f16 v161, v33, s0, v161
	v_pk_fma_f16 v160, v34, s0, v160
	v_pk_fma_f16 v159, v35, s0, v159
	v_pk_fma_f16 v158, v36, s0, v158
	v_pk_fma_f16 v157, v37, s0, v157
	v_pk_fma_f16 v156, v38, s0, v156
	v_pk_fma_f16 v147, v39, s0, v147
	v_pk_fma_f16 v146, v40, s0, v146
	v_pk_fma_f16 v145, v41, s0, v145
	v_pk_fma_f16 v144, v42, s0, v144
	v_pk_fma_f16 v143, v43, s0, v143
	v_pk_fma_f16 v142, v44, s0, v142
	v_pk_fma_f16 v141, v45, s0, v141
	v_pk_fma_f16 v149, v46, s0, v149
	v_pk_fma_f16 v148, v47, s0, v148
	s_waitcnt vmcnt(6)
	v_readlane_b32 s4, v51, 4
	v_readlane_b32 s0, v52, 3
	v_cvt_scalef32_pk_f16_fp4 v32, v16, 1.0
	v_cvt_scalef32_pk_f16_fp4 v33, v16, 1.0 op_sel:[1,0,0]
	v_cvt_scalef32_pk_f16_fp4 v34, v16, 1.0 op_sel:[0,1,0]
	v_cvt_scalef32_pk_f16_fp4 v35, v16, 1.0 op_sel:[1,1,0]
	v_cvt_scalef32_pk_f16_fp4 v36, v17, 1.0
	v_cvt_scalef32_pk_f16_fp4 v37, v17, 1.0 op_sel:[1,0,0]
	v_cvt_scalef32_pk_f16_fp4 v38, v17, 1.0 op_sel:[0,1,0]
	v_cvt_scalef32_pk_f16_fp4 v39, v17, 1.0 op_sel:[1,1,0]
	v_cvt_scalef32_pk_f16_fp4 v40, v18, 1.0
	v_cvt_scalef32_pk_f16_fp4 v41, v18, 1.0 op_sel:[1,0,0]
	v_cvt_scalef32_pk_f16_fp4 v42, v18, 1.0 op_sel:[0,1,0]
	v_cvt_scalef32_pk_f16_fp4 v43, v18, 1.0 op_sel:[1,1,0]
	v_cvt_scalef32_pk_f16_fp4 v44, v19, 1.0
	v_cvt_scalef32_pk_f16_fp4 v45, v19, 1.0 op_sel:[1,0,0]
	v_cvt_scalef32_pk_f16_fp4 v46, v19, 1.0 op_sel:[0,1,0]
	v_cvt_scalef32_pk_f16_fp4 v47, v19, 1.0 op_sel:[1,1,0]
	buffer_load_dwordx4 v[12:15], v115, s[12:15], s4 offen
	v_pk_fma_f16 v139, v32, s0, v139
	v_pk_fma_f16 v138, v33, s0, v138
	v_pk_fma_f16 v136, v34, s0, v136
	v_pk_fma_f16 v135, v35, s0, v135
	v_pk_fma_f16 v134, v36, s0, v134
	v_pk_fma_f16 v133, v37, s0, v133
	v_pk_fma_f16 v132, v38, s0, v132
	v_pk_fma_f16 v131, v39, s0, v131
	v_pk_fma_f16 v130, v40, s0, v130
	v_pk_fma_f16 v129, v41, s0, v129
	v_pk_fma_f16 v128, v42, s0, v128
	v_pk_fma_f16 v127, v43, s0, v127
	v_pk_fma_f16 v126, v44, s0, v126
	v_pk_fma_f16 v114, v45, s0, v114
	v_pk_fma_f16 v140, v46, s0, v140
	v_pk_fma_f16 v137, v47, s0, v137
	s_waitcnt vmcnt(6)
	v_readlane_b32 s4, v48, 5
	v_readlane_b32 s0, v53, 3
	v_cvt_scalef32_pk_f16_fp4 v32, v20, 1.0
	v_cvt_scalef32_pk_f16_fp4 v33, v20, 1.0 op_sel:[1,0,0]
	v_cvt_scalef32_pk_f16_fp4 v34, v20, 1.0 op_sel:[0,1,0]
	v_cvt_scalef32_pk_f16_fp4 v35, v20, 1.0 op_sel:[1,1,0]
	v_cvt_scalef32_pk_f16_fp4 v36, v21, 1.0
	v_cvt_scalef32_pk_f16_fp4 v37, v21, 1.0 op_sel:[1,0,0]
	v_cvt_scalef32_pk_f16_fp4 v38, v21, 1.0 op_sel:[0,1,0]
	v_cvt_scalef32_pk_f16_fp4 v39, v21, 1.0 op_sel:[1,1,0]
	v_cvt_scalef32_pk_f16_fp4 v40, v22, 1.0
	v_cvt_scalef32_pk_f16_fp4 v41, v22, 1.0 op_sel:[1,0,0]
	v_cvt_scalef32_pk_f16_fp4 v42, v22, 1.0 op_sel:[0,1,0]
	v_cvt_scalef32_pk_f16_fp4 v43, v22, 1.0 op_sel:[1,1,0]
	v_cvt_scalef32_pk_f16_fp4 v44, v23, 1.0
	v_cvt_scalef32_pk_f16_fp4 v45, v23, 1.0 op_sel:[1,0,0]
	v_cvt_scalef32_pk_f16_fp4 v46, v23, 1.0 op_sel:[0,1,0]
	v_cvt_scalef32_pk_f16_fp4 v47, v23, 1.0 op_sel:[1,1,0]
	buffer_load_dwordx4 v[16:19], v115, s[12:15], s4 offen
	v_pk_fma_f16 v124, v32, s0, v124
	v_pk_fma_f16 v123, v33, s0, v123
	v_pk_fma_f16 v121, v34, s0, v121
	v_pk_fma_f16 v120, v35, s0, v120
	v_pk_fma_f16 v119, v36, s0, v119
	v_pk_fma_f16 v118, v37, s0, v118
	v_pk_fma_f16 v117, v38, s0, v117
	v_pk_fma_f16 v116, v39, s0, v116
	v_pk_fma_f16 v113, v40, s0, v113
	v_pk_fma_f16 v112, v41, s0, v112
	v_pk_fma_f16 v67, v42, s0, v67
	v_pk_fma_f16 v66, v43, s0, v66
	v_pk_fma_f16 v65, v44, s0, v65
	v_pk_fma_f16 v64, v45, s0, v64
	v_pk_fma_f16 v125, v46, s0, v125
	v_pk_fma_f16 v122, v47, s0, v122
	s_waitcnt vmcnt(6)
	v_readlane_b32 s4, v49, 5
	v_readlane_b32 s0, v54, 3
	v_cvt_scalef32_pk_f16_fp4 v32, v24, 1.0
	v_cvt_scalef32_pk_f16_fp4 v33, v24, 1.0 op_sel:[1,0,0]
	v_cvt_scalef32_pk_f16_fp4 v34, v24, 1.0 op_sel:[0,1,0]
	v_cvt_scalef32_pk_f16_fp4 v35, v24, 1.0 op_sel:[1,1,0]
	v_cvt_scalef32_pk_f16_fp4 v36, v25, 1.0
	v_cvt_scalef32_pk_f16_fp4 v37, v25, 1.0 op_sel:[1,0,0]
	v_cvt_scalef32_pk_f16_fp4 v38, v25, 1.0 op_sel:[0,1,0]
	v_cvt_scalef32_pk_f16_fp4 v39, v25, 1.0 op_sel:[1,1,0]
	v_cvt_scalef32_pk_f16_fp4 v40, v26, 1.0
	v_cvt_scalef32_pk_f16_fp4 v41, v26, 1.0 op_sel:[1,0,0]
	v_cvt_scalef32_pk_f16_fp4 v42, v26, 1.0 op_sel:[0,1,0]
	v_cvt_scalef32_pk_f16_fp4 v43, v26, 1.0 op_sel:[1,1,0]
	v_cvt_scalef32_pk_f16_fp4 v44, v27, 1.0
	v_cvt_scalef32_pk_f16_fp4 v45, v27, 1.0 op_sel:[1,0,0]
	v_cvt_scalef32_pk_f16_fp4 v46, v27, 1.0 op_sel:[0,1,0]
	v_cvt_scalef32_pk_f16_fp4 v47, v27, 1.0 op_sel:[1,1,0]
	buffer_load_dwordx4 v[20:23], v115, s[12:15], s4 offen
	v_pk_fma_f16 v74, v32, s0, v74
	v_pk_fma_f16 v73, v33, s0, v73
	v_pk_fma_f16 v71, v34, s0, v71
	v_pk_fma_f16 v70, v35, s0, v70
	v_pk_fma_f16 v69, v36, s0, v69
	v_pk_fma_f16 v68, v37, s0, v68
	v_pk_fma_f16 v63, v38, s0, v63
	v_pk_fma_f16 v62, v39, s0, v62
	v_pk_fma_f16 v61, v40, s0, v61
	v_pk_fma_f16 v60, v41, s0, v60
	v_pk_fma_f16 v59, v42, s0, v59
	v_pk_fma_f16 v58, v43, s0, v58
	v_pk_fma_f16 v57, v44, s0, v57
	v_pk_fma_f16 v56, v45, s0, v56
	v_pk_fma_f16 v75, v46, s0, v75
	v_pk_fma_f16 v72, v47, s0, v72
	s_waitcnt vmcnt(6)
	v_readlane_b32 s4, v50, 5
	v_readlane_b32 s0, v55, 3
	v_cvt_scalef32_pk_f16_fp4 v32, v28, 1.0
	v_cvt_scalef32_pk_f16_fp4 v33, v28, 1.0 op_sel:[1,0,0]
	v_cvt_scalef32_pk_f16_fp4 v34, v28, 1.0 op_sel:[0,1,0]
	v_cvt_scalef32_pk_f16_fp4 v35, v28, 1.0 op_sel:[1,1,0]
	v_cvt_scalef32_pk_f16_fp4 v36, v29, 1.0
	v_cvt_scalef32_pk_f16_fp4 v37, v29, 1.0 op_sel:[1,0,0]
	v_cvt_scalef32_pk_f16_fp4 v38, v29, 1.0 op_sel:[0,1,0]
	v_cvt_scalef32_pk_f16_fp4 v39, v29, 1.0 op_sel:[1,1,0]
	v_cvt_scalef32_pk_f16_fp4 v40, v30, 1.0
	v_cvt_scalef32_pk_f16_fp4 v41, v30, 1.0 op_sel:[1,0,0]
	v_cvt_scalef32_pk_f16_fp4 v42, v30, 1.0 op_sel:[0,1,0]
	v_cvt_scalef32_pk_f16_fp4 v43, v30, 1.0 op_sel:[1,1,0]
	v_cvt_scalef32_pk_f16_fp4 v44, v31, 1.0
	v_cvt_scalef32_pk_f16_fp4 v45, v31, 1.0 op_sel:[1,0,0]
	v_cvt_scalef32_pk_f16_fp4 v46, v31, 1.0 op_sel:[0,1,0]
	v_cvt_scalef32_pk_f16_fp4 v47, v31, 1.0 op_sel:[1,1,0]
	buffer_load_dwordx4 v[24:27], v115, s[12:15], s4 offen
	v_pk_fma_f16 v162, v32, s0, v162
	v_pk_fma_f16 v161, v33, s0, v161
	v_pk_fma_f16 v160, v34, s0, v160
	v_pk_fma_f16 v159, v35, s0, v159
	v_pk_fma_f16 v158, v36, s0, v158
	v_pk_fma_f16 v157, v37, s0, v157
	v_pk_fma_f16 v156, v38, s0, v156
	v_pk_fma_f16 v147, v39, s0, v147
	v_pk_fma_f16 v146, v40, s0, v146
	v_pk_fma_f16 v145, v41, s0, v145
	v_pk_fma_f16 v144, v42, s0, v144
	v_pk_fma_f16 v143, v43, s0, v143
	v_pk_fma_f16 v142, v44, s0, v142
	v_pk_fma_f16 v141, v45, s0, v141
	v_pk_fma_f16 v149, v46, s0, v149
	v_pk_fma_f16 v148, v47, s0, v148
	s_waitcnt vmcnt(6)
	v_readlane_b32 s4, v51, 5
	v_readlane_b32 s0, v52, 4
	v_cvt_scalef32_pk_f16_fp4 v32, v0, 1.0
	v_cvt_scalef32_pk_f16_fp4 v33, v0, 1.0 op_sel:[1,0,0]
	v_cvt_scalef32_pk_f16_fp4 v34, v0, 1.0 op_sel:[0,1,0]
	v_cvt_scalef32_pk_f16_fp4 v35, v0, 1.0 op_sel:[1,1,0]
	v_cvt_scalef32_pk_f16_fp4 v36, v1, 1.0
	v_cvt_scalef32_pk_f16_fp4 v37, v1, 1.0 op_sel:[1,0,0]
	v_cvt_scalef32_pk_f16_fp4 v38, v1, 1.0 op_sel:[0,1,0]
	v_cvt_scalef32_pk_f16_fp4 v39, v1, 1.0 op_sel:[1,1,0]
	v_cvt_scalef32_pk_f16_fp4 v40, v2, 1.0
	v_cvt_scalef32_pk_f16_fp4 v41, v2, 1.0 op_sel:[1,0,0]
	v_cvt_scalef32_pk_f16_fp4 v42, v2, 1.0 op_sel:[0,1,0]
	v_cvt_scalef32_pk_f16_fp4 v43, v2, 1.0 op_sel:[1,1,0]
	v_cvt_scalef32_pk_f16_fp4 v44, v3, 1.0
	v_cvt_scalef32_pk_f16_fp4 v45, v3, 1.0 op_sel:[1,0,0]
	v_cvt_scalef32_pk_f16_fp4 v46, v3, 1.0 op_sel:[0,1,0]
	v_cvt_scalef32_pk_f16_fp4 v47, v3, 1.0 op_sel:[1,1,0]
	buffer_load_dwordx4 v[28:31], v115, s[12:15], s4 offen
	v_pk_fma_f16 v139, v32, s0, v139
	v_pk_fma_f16 v138, v33, s0, v138
	v_pk_fma_f16 v136, v34, s0, v136
	v_pk_fma_f16 v135, v35, s0, v135
	v_pk_fma_f16 v134, v36, s0, v134
	v_pk_fma_f16 v133, v37, s0, v133
	v_pk_fma_f16 v132, v38, s0, v132
	v_pk_fma_f16 v131, v39, s0, v131
	v_pk_fma_f16 v130, v40, s0, v130
	v_pk_fma_f16 v129, v41, s0, v129
	v_pk_fma_f16 v128, v42, s0, v128
	v_pk_fma_f16 v127, v43, s0, v127
	v_pk_fma_f16 v126, v44, s0, v126
	v_pk_fma_f16 v114, v45, s0, v114
	v_pk_fma_f16 v140, v46, s0, v140
	v_pk_fma_f16 v137, v47, s0, v137
	s_waitcnt vmcnt(6)
	v_readlane_b32 s4, v48, 6
	v_readlane_b32 s0, v53, 4
	v_cvt_scalef32_pk_f16_fp4 v32, v4, 1.0
	v_cvt_scalef32_pk_f16_fp4 v33, v4, 1.0 op_sel:[1,0,0]
	v_cvt_scalef32_pk_f16_fp4 v34, v4, 1.0 op_sel:[0,1,0]
	v_cvt_scalef32_pk_f16_fp4 v35, v4, 1.0 op_sel:[1,1,0]
	v_cvt_scalef32_pk_f16_fp4 v36, v5, 1.0
	v_cvt_scalef32_pk_f16_fp4 v37, v5, 1.0 op_sel:[1,0,0]
	v_cvt_scalef32_pk_f16_fp4 v38, v5, 1.0 op_sel:[0,1,0]
	v_cvt_scalef32_pk_f16_fp4 v39, v5, 1.0 op_sel:[1,1,0]
	v_cvt_scalef32_pk_f16_fp4 v40, v6, 1.0
	v_cvt_scalef32_pk_f16_fp4 v41, v6, 1.0 op_sel:[1,0,0]
	v_cvt_scalef32_pk_f16_fp4 v42, v6, 1.0 op_sel:[0,1,0]
	v_cvt_scalef32_pk_f16_fp4 v43, v6, 1.0 op_sel:[1,1,0]
	v_cvt_scalef32_pk_f16_fp4 v44, v7, 1.0
	v_cvt_scalef32_pk_f16_fp4 v45, v7, 1.0 op_sel:[1,0,0]
	v_cvt_scalef32_pk_f16_fp4 v46, v7, 1.0 op_sel:[0,1,0]
	v_cvt_scalef32_pk_f16_fp4 v47, v7, 1.0 op_sel:[1,1,0]
	buffer_load_dwordx4 v[0:3], v115, s[12:15], s4 offen
	v_pk_fma_f16 v124, v32, s0, v124
	v_pk_fma_f16 v123, v33, s0, v123
	v_pk_fma_f16 v121, v34, s0, v121
	v_pk_fma_f16 v120, v35, s0, v120
	v_pk_fma_f16 v119, v36, s0, v119
	v_pk_fma_f16 v118, v37, s0, v118
	v_pk_fma_f16 v117, v38, s0, v117
	v_pk_fma_f16 v116, v39, s0, v116
	v_pk_fma_f16 v113, v40, s0, v113
	v_pk_fma_f16 v112, v41, s0, v112
	v_pk_fma_f16 v67, v42, s0, v67
	v_pk_fma_f16 v66, v43, s0, v66
	v_pk_fma_f16 v65, v44, s0, v65
	v_pk_fma_f16 v64, v45, s0, v64
	v_pk_fma_f16 v125, v46, s0, v125
	v_pk_fma_f16 v122, v47, s0, v122
	s_waitcnt vmcnt(6)
	v_readlane_b32 s4, v49, 6
	v_readlane_b32 s0, v54, 4
	v_cvt_scalef32_pk_f16_fp4 v32, v8, 1.0
	v_cvt_scalef32_pk_f16_fp4 v33, v8, 1.0 op_sel:[1,0,0]
	v_cvt_scalef32_pk_f16_fp4 v34, v8, 1.0 op_sel:[0,1,0]
	v_cvt_scalef32_pk_f16_fp4 v35, v8, 1.0 op_sel:[1,1,0]
	v_cvt_scalef32_pk_f16_fp4 v36, v9, 1.0
	v_cvt_scalef32_pk_f16_fp4 v37, v9, 1.0 op_sel:[1,0,0]
	v_cvt_scalef32_pk_f16_fp4 v38, v9, 1.0 op_sel:[0,1,0]
	v_cvt_scalef32_pk_f16_fp4 v39, v9, 1.0 op_sel:[1,1,0]
	v_cvt_scalef32_pk_f16_fp4 v40, v10, 1.0
	v_cvt_scalef32_pk_f16_fp4 v41, v10, 1.0 op_sel:[1,0,0]
	v_cvt_scalef32_pk_f16_fp4 v42, v10, 1.0 op_sel:[0,1,0]
	v_cvt_scalef32_pk_f16_fp4 v43, v10, 1.0 op_sel:[1,1,0]
	v_cvt_scalef32_pk_f16_fp4 v44, v11, 1.0
	v_cvt_scalef32_pk_f16_fp4 v45, v11, 1.0 op_sel:[1,0,0]
	v_cvt_scalef32_pk_f16_fp4 v46, v11, 1.0 op_sel:[0,1,0]
	v_cvt_scalef32_pk_f16_fp4 v47, v11, 1.0 op_sel:[1,1,0]
	buffer_load_dwordx4 v[4:7], v115, s[12:15], s4 offen
	v_pk_fma_f16 v74, v32, s0, v74
	v_pk_fma_f16 v73, v33, s0, v73
	v_pk_fma_f16 v71, v34, s0, v71
	v_pk_fma_f16 v70, v35, s0, v70
	v_pk_fma_f16 v69, v36, s0, v69
	v_pk_fma_f16 v68, v37, s0, v68
	v_pk_fma_f16 v63, v38, s0, v63
	v_pk_fma_f16 v62, v39, s0, v62
	v_pk_fma_f16 v61, v40, s0, v61
	v_pk_fma_f16 v60, v41, s0, v60
	v_pk_fma_f16 v59, v42, s0, v59
	v_pk_fma_f16 v58, v43, s0, v58
	v_pk_fma_f16 v57, v44, s0, v57
	v_pk_fma_f16 v56, v45, s0, v56
	v_pk_fma_f16 v75, v46, s0, v75
	v_pk_fma_f16 v72, v47, s0, v72
	s_waitcnt vmcnt(6)
	v_readlane_b32 s4, v50, 6
	v_readlane_b32 s0, v55, 4
	v_cvt_scalef32_pk_f16_fp4 v32, v12, 1.0
	v_cvt_scalef32_pk_f16_fp4 v33, v12, 1.0 op_sel:[1,0,0]
	v_cvt_scalef32_pk_f16_fp4 v34, v12, 1.0 op_sel:[0,1,0]
	v_cvt_scalef32_pk_f16_fp4 v35, v12, 1.0 op_sel:[1,1,0]
	v_cvt_scalef32_pk_f16_fp4 v36, v13, 1.0
	v_cvt_scalef32_pk_f16_fp4 v37, v13, 1.0 op_sel:[1,0,0]
	v_cvt_scalef32_pk_f16_fp4 v38, v13, 1.0 op_sel:[0,1,0]
	v_cvt_scalef32_pk_f16_fp4 v39, v13, 1.0 op_sel:[1,1,0]
	v_cvt_scalef32_pk_f16_fp4 v40, v14, 1.0
	v_cvt_scalef32_pk_f16_fp4 v41, v14, 1.0 op_sel:[1,0,0]
	v_cvt_scalef32_pk_f16_fp4 v42, v14, 1.0 op_sel:[0,1,0]
	v_cvt_scalef32_pk_f16_fp4 v43, v14, 1.0 op_sel:[1,1,0]
	v_cvt_scalef32_pk_f16_fp4 v44, v15, 1.0
	v_cvt_scalef32_pk_f16_fp4 v45, v15, 1.0 op_sel:[1,0,0]
	v_cvt_scalef32_pk_f16_fp4 v46, v15, 1.0 op_sel:[0,1,0]
	v_cvt_scalef32_pk_f16_fp4 v47, v15, 1.0 op_sel:[1,1,0]
	buffer_load_dwordx4 v[8:11], v115, s[12:15], s4 offen
	v_pk_fma_f16 v162, v32, s0, v162
	v_pk_fma_f16 v161, v33, s0, v161
	v_pk_fma_f16 v160, v34, s0, v160
	v_pk_fma_f16 v159, v35, s0, v159
	v_pk_fma_f16 v158, v36, s0, v158
	v_pk_fma_f16 v157, v37, s0, v157
	v_pk_fma_f16 v156, v38, s0, v156
	v_pk_fma_f16 v147, v39, s0, v147
	v_pk_fma_f16 v146, v40, s0, v146
	v_pk_fma_f16 v145, v41, s0, v145
	v_pk_fma_f16 v144, v42, s0, v144
	v_pk_fma_f16 v143, v43, s0, v143
	v_pk_fma_f16 v142, v44, s0, v142
	v_pk_fma_f16 v141, v45, s0, v141
	v_pk_fma_f16 v149, v46, s0, v149
	v_pk_fma_f16 v148, v47, s0, v148
	s_waitcnt vmcnt(6)
	v_readlane_b32 s4, v51, 6
	v_readlane_b32 s0, v52, 5
	v_cvt_scalef32_pk_f16_fp4 v32, v16, 1.0
	v_cvt_scalef32_pk_f16_fp4 v33, v16, 1.0 op_sel:[1,0,0]
	v_cvt_scalef32_pk_f16_fp4 v34, v16, 1.0 op_sel:[0,1,0]
	v_cvt_scalef32_pk_f16_fp4 v35, v16, 1.0 op_sel:[1,1,0]
	v_cvt_scalef32_pk_f16_fp4 v36, v17, 1.0
	v_cvt_scalef32_pk_f16_fp4 v37, v17, 1.0 op_sel:[1,0,0]
	v_cvt_scalef32_pk_f16_fp4 v38, v17, 1.0 op_sel:[0,1,0]
	v_cvt_scalef32_pk_f16_fp4 v39, v17, 1.0 op_sel:[1,1,0]
	v_cvt_scalef32_pk_f16_fp4 v40, v18, 1.0
	v_cvt_scalef32_pk_f16_fp4 v41, v18, 1.0 op_sel:[1,0,0]
	v_cvt_scalef32_pk_f16_fp4 v42, v18, 1.0 op_sel:[0,1,0]
	v_cvt_scalef32_pk_f16_fp4 v43, v18, 1.0 op_sel:[1,1,0]
	v_cvt_scalef32_pk_f16_fp4 v44, v19, 1.0
	v_cvt_scalef32_pk_f16_fp4 v45, v19, 1.0 op_sel:[1,0,0]
	v_cvt_scalef32_pk_f16_fp4 v46, v19, 1.0 op_sel:[0,1,0]
	v_cvt_scalef32_pk_f16_fp4 v47, v19, 1.0 op_sel:[1,1,0]
	buffer_load_dwordx4 v[12:15], v115, s[12:15], s4 offen
	v_pk_fma_f16 v139, v32, s0, v139
	v_pk_fma_f16 v138, v33, s0, v138
	v_pk_fma_f16 v136, v34, s0, v136
	v_pk_fma_f16 v135, v35, s0, v135
	v_pk_fma_f16 v134, v36, s0, v134
	v_pk_fma_f16 v133, v37, s0, v133
	v_pk_fma_f16 v132, v38, s0, v132
	v_pk_fma_f16 v131, v39, s0, v131
	v_pk_fma_f16 v130, v40, s0, v130
	v_pk_fma_f16 v129, v41, s0, v129
	v_pk_fma_f16 v128, v42, s0, v128
	v_pk_fma_f16 v127, v43, s0, v127
	v_pk_fma_f16 v126, v44, s0, v126
	v_pk_fma_f16 v114, v45, s0, v114
	v_pk_fma_f16 v140, v46, s0, v140
	v_pk_fma_f16 v137, v47, s0, v137
	s_waitcnt vmcnt(6)
	v_readlane_b32 s4, v48, 7
	v_readlane_b32 s0, v53, 5
	v_cvt_scalef32_pk_f16_fp4 v32, v20, 1.0
	v_cvt_scalef32_pk_f16_fp4 v33, v20, 1.0 op_sel:[1,0,0]
	v_cvt_scalef32_pk_f16_fp4 v34, v20, 1.0 op_sel:[0,1,0]
	v_cvt_scalef32_pk_f16_fp4 v35, v20, 1.0 op_sel:[1,1,0]
	v_cvt_scalef32_pk_f16_fp4 v36, v21, 1.0
	v_cvt_scalef32_pk_f16_fp4 v37, v21, 1.0 op_sel:[1,0,0]
	v_cvt_scalef32_pk_f16_fp4 v38, v21, 1.0 op_sel:[0,1,0]
	v_cvt_scalef32_pk_f16_fp4 v39, v21, 1.0 op_sel:[1,1,0]
	v_cvt_scalef32_pk_f16_fp4 v40, v22, 1.0
	v_cvt_scalef32_pk_f16_fp4 v41, v22, 1.0 op_sel:[1,0,0]
	v_cvt_scalef32_pk_f16_fp4 v42, v22, 1.0 op_sel:[0,1,0]
	v_cvt_scalef32_pk_f16_fp4 v43, v22, 1.0 op_sel:[1,1,0]
	v_cvt_scalef32_pk_f16_fp4 v44, v23, 1.0
	v_cvt_scalef32_pk_f16_fp4 v45, v23, 1.0 op_sel:[1,0,0]
	v_cvt_scalef32_pk_f16_fp4 v46, v23, 1.0 op_sel:[0,1,0]
	v_cvt_scalef32_pk_f16_fp4 v47, v23, 1.0 op_sel:[1,1,0]
	buffer_load_dwordx4 v[16:19], v115, s[12:15], s4 offen
	v_pk_fma_f16 v124, v32, s0, v124
	v_pk_fma_f16 v123, v33, s0, v123
	v_pk_fma_f16 v121, v34, s0, v121
	v_pk_fma_f16 v120, v35, s0, v120
	v_pk_fma_f16 v119, v36, s0, v119
	v_pk_fma_f16 v118, v37, s0, v118
	v_pk_fma_f16 v117, v38, s0, v117
	v_pk_fma_f16 v116, v39, s0, v116
	v_pk_fma_f16 v113, v40, s0, v113
	v_pk_fma_f16 v112, v41, s0, v112
	v_pk_fma_f16 v67, v42, s0, v67
	v_pk_fma_f16 v66, v43, s0, v66
	v_pk_fma_f16 v65, v44, s0, v65
	v_pk_fma_f16 v64, v45, s0, v64
	v_pk_fma_f16 v125, v46, s0, v125
	v_pk_fma_f16 v122, v47, s0, v122
	s_waitcnt vmcnt(6)
	v_readlane_b32 s4, v49, 7
	v_readlane_b32 s0, v54, 5
	v_cvt_scalef32_pk_f16_fp4 v32, v24, 1.0
	v_cvt_scalef32_pk_f16_fp4 v33, v24, 1.0 op_sel:[1,0,0]
	v_cvt_scalef32_pk_f16_fp4 v34, v24, 1.0 op_sel:[0,1,0]
	v_cvt_scalef32_pk_f16_fp4 v35, v24, 1.0 op_sel:[1,1,0]
	v_cvt_scalef32_pk_f16_fp4 v36, v25, 1.0
	v_cvt_scalef32_pk_f16_fp4 v37, v25, 1.0 op_sel:[1,0,0]
	v_cvt_scalef32_pk_f16_fp4 v38, v25, 1.0 op_sel:[0,1,0]
	v_cvt_scalef32_pk_f16_fp4 v39, v25, 1.0 op_sel:[1,1,0]
	v_cvt_scalef32_pk_f16_fp4 v40, v26, 1.0
	v_cvt_scalef32_pk_f16_fp4 v41, v26, 1.0 op_sel:[1,0,0]
	v_cvt_scalef32_pk_f16_fp4 v42, v26, 1.0 op_sel:[0,1,0]
	v_cvt_scalef32_pk_f16_fp4 v43, v26, 1.0 op_sel:[1,1,0]
	v_cvt_scalef32_pk_f16_fp4 v44, v27, 1.0
	v_cvt_scalef32_pk_f16_fp4 v45, v27, 1.0 op_sel:[1,0,0]
	v_cvt_scalef32_pk_f16_fp4 v46, v27, 1.0 op_sel:[0,1,0]
	v_cvt_scalef32_pk_f16_fp4 v47, v27, 1.0 op_sel:[1,1,0]
	buffer_load_dwordx4 v[20:23], v115, s[12:15], s4 offen
	v_pk_fma_f16 v74, v32, s0, v74
	v_pk_fma_f16 v73, v33, s0, v73
	v_pk_fma_f16 v71, v34, s0, v71
	v_pk_fma_f16 v70, v35, s0, v70
	v_pk_fma_f16 v69, v36, s0, v69
	v_pk_fma_f16 v68, v37, s0, v68
	v_pk_fma_f16 v63, v38, s0, v63
	v_pk_fma_f16 v62, v39, s0, v62
	v_pk_fma_f16 v61, v40, s0, v61
	v_pk_fma_f16 v60, v41, s0, v60
	v_pk_fma_f16 v59, v42, s0, v59
	v_pk_fma_f16 v58, v43, s0, v58
	v_pk_fma_f16 v57, v44, s0, v57
	v_pk_fma_f16 v56, v45, s0, v56
	v_pk_fma_f16 v75, v46, s0, v75
	v_pk_fma_f16 v72, v47, s0, v72
	s_waitcnt vmcnt(6)
	v_readlane_b32 s4, v50, 7
	v_readlane_b32 s0, v55, 5
	v_cvt_scalef32_pk_f16_fp4 v32, v28, 1.0
	v_cvt_scalef32_pk_f16_fp4 v33, v28, 1.0 op_sel:[1,0,0]
	v_cvt_scalef32_pk_f16_fp4 v34, v28, 1.0 op_sel:[0,1,0]
	v_cvt_scalef32_pk_f16_fp4 v35, v28, 1.0 op_sel:[1,1,0]
	v_cvt_scalef32_pk_f16_fp4 v36, v29, 1.0
	v_cvt_scalef32_pk_f16_fp4 v37, v29, 1.0 op_sel:[1,0,0]
	v_cvt_scalef32_pk_f16_fp4 v38, v29, 1.0 op_sel:[0,1,0]
	v_cvt_scalef32_pk_f16_fp4 v39, v29, 1.0 op_sel:[1,1,0]
	v_cvt_scalef32_pk_f16_fp4 v40, v30, 1.0
	v_cvt_scalef32_pk_f16_fp4 v41, v30, 1.0 op_sel:[1,0,0]
	v_cvt_scalef32_pk_f16_fp4 v42, v30, 1.0 op_sel:[0,1,0]
	v_cvt_scalef32_pk_f16_fp4 v43, v30, 1.0 op_sel:[1,1,0]
	v_cvt_scalef32_pk_f16_fp4 v44, v31, 1.0
	v_cvt_scalef32_pk_f16_fp4 v45, v31, 1.0 op_sel:[1,0,0]
	v_cvt_scalef32_pk_f16_fp4 v46, v31, 1.0 op_sel:[0,1,0]
	v_cvt_scalef32_pk_f16_fp4 v47, v31, 1.0 op_sel:[1,1,0]
	buffer_load_dwordx4 v[24:27], v115, s[12:15], s4 offen
	v_pk_fma_f16 v162, v32, s0, v162
	v_pk_fma_f16 v161, v33, s0, v161
	v_pk_fma_f16 v160, v34, s0, v160
	v_pk_fma_f16 v159, v35, s0, v159
	v_pk_fma_f16 v158, v36, s0, v158
	v_pk_fma_f16 v157, v37, s0, v157
	v_pk_fma_f16 v156, v38, s0, v156
	v_pk_fma_f16 v147, v39, s0, v147
	v_pk_fma_f16 v146, v40, s0, v146
	v_pk_fma_f16 v145, v41, s0, v145
	v_pk_fma_f16 v144, v42, s0, v144
	v_pk_fma_f16 v143, v43, s0, v143
	v_pk_fma_f16 v142, v44, s0, v142
	v_pk_fma_f16 v141, v45, s0, v141
	v_pk_fma_f16 v149, v46, s0, v149
	v_pk_fma_f16 v148, v47, s0, v148
	s_waitcnt vmcnt(6)
	v_readlane_b32 s4, v51, 7
	v_readlane_b32 s0, v52, 6
	v_cvt_scalef32_pk_f16_fp4 v32, v0, 1.0
	v_cvt_scalef32_pk_f16_fp4 v33, v0, 1.0 op_sel:[1,0,0]
	v_cvt_scalef32_pk_f16_fp4 v34, v0, 1.0 op_sel:[0,1,0]
	v_cvt_scalef32_pk_f16_fp4 v35, v0, 1.0 op_sel:[1,1,0]
	v_cvt_scalef32_pk_f16_fp4 v36, v1, 1.0
	v_cvt_scalef32_pk_f16_fp4 v37, v1, 1.0 op_sel:[1,0,0]
	v_cvt_scalef32_pk_f16_fp4 v38, v1, 1.0 op_sel:[0,1,0]
	v_cvt_scalef32_pk_f16_fp4 v39, v1, 1.0 op_sel:[1,1,0]
	v_cvt_scalef32_pk_f16_fp4 v40, v2, 1.0
	v_cvt_scalef32_pk_f16_fp4 v41, v2, 1.0 op_sel:[1,0,0]
	v_cvt_scalef32_pk_f16_fp4 v42, v2, 1.0 op_sel:[0,1,0]
	v_cvt_scalef32_pk_f16_fp4 v43, v2, 1.0 op_sel:[1,1,0]
	v_cvt_scalef32_pk_f16_fp4 v44, v3, 1.0
	v_cvt_scalef32_pk_f16_fp4 v45, v3, 1.0 op_sel:[1,0,0]
	v_cvt_scalef32_pk_f16_fp4 v46, v3, 1.0 op_sel:[0,1,0]
	v_cvt_scalef32_pk_f16_fp4 v47, v3, 1.0 op_sel:[1,1,0]
	buffer_load_dwordx4 v[28:31], v115, s[12:15], s4 offen
	v_pk_fma_f16 v139, v32, s0, v139
	v_pk_fma_f16 v138, v33, s0, v138
	v_pk_fma_f16 v136, v34, s0, v136
	v_pk_fma_f16 v135, v35, s0, v135
	v_pk_fma_f16 v134, v36, s0, v134
	v_pk_fma_f16 v133, v37, s0, v133
	v_pk_fma_f16 v132, v38, s0, v132
	v_pk_fma_f16 v131, v39, s0, v131
	v_pk_fma_f16 v130, v40, s0, v130
	v_pk_fma_f16 v129, v41, s0, v129
	v_pk_fma_f16 v128, v42, s0, v128
	v_pk_fma_f16 v127, v43, s0, v127
	v_pk_fma_f16 v126, v44, s0, v126
	v_pk_fma_f16 v114, v45, s0, v114
	v_pk_fma_f16 v140, v46, s0, v140
	v_pk_fma_f16 v137, v47, s0, v137
	s_waitcnt vmcnt(6)
	v_readlane_b32 s4, v48, 8
	v_readlane_b32 s0, v53, 6
	v_cvt_scalef32_pk_f16_fp4 v32, v4, 1.0
	v_cvt_scalef32_pk_f16_fp4 v33, v4, 1.0 op_sel:[1,0,0]
	v_cvt_scalef32_pk_f16_fp4 v34, v4, 1.0 op_sel:[0,1,0]
	v_cvt_scalef32_pk_f16_fp4 v35, v4, 1.0 op_sel:[1,1,0]
	v_cvt_scalef32_pk_f16_fp4 v36, v5, 1.0
	v_cvt_scalef32_pk_f16_fp4 v37, v5, 1.0 op_sel:[1,0,0]
	v_cvt_scalef32_pk_f16_fp4 v38, v5, 1.0 op_sel:[0,1,0]
	v_cvt_scalef32_pk_f16_fp4 v39, v5, 1.0 op_sel:[1,1,0]
	v_cvt_scalef32_pk_f16_fp4 v40, v6, 1.0
	v_cvt_scalef32_pk_f16_fp4 v41, v6, 1.0 op_sel:[1,0,0]
	v_cvt_scalef32_pk_f16_fp4 v42, v6, 1.0 op_sel:[0,1,0]
	v_cvt_scalef32_pk_f16_fp4 v43, v6, 1.0 op_sel:[1,1,0]
	v_cvt_scalef32_pk_f16_fp4 v44, v7, 1.0
	v_cvt_scalef32_pk_f16_fp4 v45, v7, 1.0 op_sel:[1,0,0]
	v_cvt_scalef32_pk_f16_fp4 v46, v7, 1.0 op_sel:[0,1,0]
	v_cvt_scalef32_pk_f16_fp4 v47, v7, 1.0 op_sel:[1,1,0]
	buffer_load_dwordx4 v[0:3], v115, s[12:15], s4 offen
	v_pk_fma_f16 v124, v32, s0, v124
	v_pk_fma_f16 v123, v33, s0, v123
	v_pk_fma_f16 v121, v34, s0, v121
	v_pk_fma_f16 v120, v35, s0, v120
	v_pk_fma_f16 v119, v36, s0, v119
	v_pk_fma_f16 v118, v37, s0, v118
	v_pk_fma_f16 v117, v38, s0, v117
	v_pk_fma_f16 v116, v39, s0, v116
	v_pk_fma_f16 v113, v40, s0, v113
	v_pk_fma_f16 v112, v41, s0, v112
	v_pk_fma_f16 v67, v42, s0, v67
	v_pk_fma_f16 v66, v43, s0, v66
	v_pk_fma_f16 v65, v44, s0, v65
	v_pk_fma_f16 v64, v45, s0, v64
	v_pk_fma_f16 v125, v46, s0, v125
	v_pk_fma_f16 v122, v47, s0, v122
	s_waitcnt vmcnt(6)
	v_readlane_b32 s4, v49, 8
	v_readlane_b32 s0, v54, 6
	v_cvt_scalef32_pk_f16_fp4 v32, v8, 1.0
	v_cvt_scalef32_pk_f16_fp4 v33, v8, 1.0 op_sel:[1,0,0]
	v_cvt_scalef32_pk_f16_fp4 v34, v8, 1.0 op_sel:[0,1,0]
	v_cvt_scalef32_pk_f16_fp4 v35, v8, 1.0 op_sel:[1,1,0]
	v_cvt_scalef32_pk_f16_fp4 v36, v9, 1.0
	v_cvt_scalef32_pk_f16_fp4 v37, v9, 1.0 op_sel:[1,0,0]
	v_cvt_scalef32_pk_f16_fp4 v38, v9, 1.0 op_sel:[0,1,0]
	v_cvt_scalef32_pk_f16_fp4 v39, v9, 1.0 op_sel:[1,1,0]
	v_cvt_scalef32_pk_f16_fp4 v40, v10, 1.0
	v_cvt_scalef32_pk_f16_fp4 v41, v10, 1.0 op_sel:[1,0,0]
	v_cvt_scalef32_pk_f16_fp4 v42, v10, 1.0 op_sel:[0,1,0]
	v_cvt_scalef32_pk_f16_fp4 v43, v10, 1.0 op_sel:[1,1,0]
	v_cvt_scalef32_pk_f16_fp4 v44, v11, 1.0
	v_cvt_scalef32_pk_f16_fp4 v45, v11, 1.0 op_sel:[1,0,0]
	v_cvt_scalef32_pk_f16_fp4 v46, v11, 1.0 op_sel:[0,1,0]
	v_cvt_scalef32_pk_f16_fp4 v47, v11, 1.0 op_sel:[1,1,0]
	buffer_load_dwordx4 v[4:7], v115, s[12:15], s4 offen
	v_pk_fma_f16 v74, v32, s0, v74
	v_pk_fma_f16 v73, v33, s0, v73
	v_pk_fma_f16 v71, v34, s0, v71
	v_pk_fma_f16 v70, v35, s0, v70
	v_pk_fma_f16 v69, v36, s0, v69
	v_pk_fma_f16 v68, v37, s0, v68
	v_pk_fma_f16 v63, v38, s0, v63
	v_pk_fma_f16 v62, v39, s0, v62
	v_pk_fma_f16 v61, v40, s0, v61
	v_pk_fma_f16 v60, v41, s0, v60
	v_pk_fma_f16 v59, v42, s0, v59
	v_pk_fma_f16 v58, v43, s0, v58
	v_pk_fma_f16 v57, v44, s0, v57
	v_pk_fma_f16 v56, v45, s0, v56
	v_pk_fma_f16 v75, v46, s0, v75
	v_pk_fma_f16 v72, v47, s0, v72
	s_waitcnt vmcnt(6)
	v_readlane_b32 s4, v50, 8
	v_readlane_b32 s0, v55, 6
	v_cvt_scalef32_pk_f16_fp4 v32, v12, 1.0
	v_cvt_scalef32_pk_f16_fp4 v33, v12, 1.0 op_sel:[1,0,0]
	v_cvt_scalef32_pk_f16_fp4 v34, v12, 1.0 op_sel:[0,1,0]
	v_cvt_scalef32_pk_f16_fp4 v35, v12, 1.0 op_sel:[1,1,0]
	v_cvt_scalef32_pk_f16_fp4 v36, v13, 1.0
	v_cvt_scalef32_pk_f16_fp4 v37, v13, 1.0 op_sel:[1,0,0]
	v_cvt_scalef32_pk_f16_fp4 v38, v13, 1.0 op_sel:[0,1,0]
	v_cvt_scalef32_pk_f16_fp4 v39, v13, 1.0 op_sel:[1,1,0]
	v_cvt_scalef32_pk_f16_fp4 v40, v14, 1.0
	v_cvt_scalef32_pk_f16_fp4 v41, v14, 1.0 op_sel:[1,0,0]
	v_cvt_scalef32_pk_f16_fp4 v42, v14, 1.0 op_sel:[0,1,0]
	v_cvt_scalef32_pk_f16_fp4 v43, v14, 1.0 op_sel:[1,1,0]
	v_cvt_scalef32_pk_f16_fp4 v44, v15, 1.0
	v_cvt_scalef32_pk_f16_fp4 v45, v15, 1.0 op_sel:[1,0,0]
	v_cvt_scalef32_pk_f16_fp4 v46, v15, 1.0 op_sel:[0,1,0]
	v_cvt_scalef32_pk_f16_fp4 v47, v15, 1.0 op_sel:[1,1,0]
	buffer_load_dwordx4 v[8:11], v115, s[12:15], s4 offen
	v_pk_fma_f16 v162, v32, s0, v162
	v_pk_fma_f16 v161, v33, s0, v161
	v_pk_fma_f16 v160, v34, s0, v160
	v_pk_fma_f16 v159, v35, s0, v159
	v_pk_fma_f16 v158, v36, s0, v158
	v_pk_fma_f16 v157, v37, s0, v157
	v_pk_fma_f16 v156, v38, s0, v156
	v_pk_fma_f16 v147, v39, s0, v147
	v_pk_fma_f16 v146, v40, s0, v146
	v_pk_fma_f16 v145, v41, s0, v145
	v_pk_fma_f16 v144, v42, s0, v144
	v_pk_fma_f16 v143, v43, s0, v143
	v_pk_fma_f16 v142, v44, s0, v142
	v_pk_fma_f16 v141, v45, s0, v141
	v_pk_fma_f16 v149, v46, s0, v149
	v_pk_fma_f16 v148, v47, s0, v148
	s_waitcnt vmcnt(6)
	v_readlane_b32 s4, v51, 8
	v_readlane_b32 s0, v52, 7
	v_cvt_scalef32_pk_f16_fp4 v32, v16, 1.0
	v_cvt_scalef32_pk_f16_fp4 v33, v16, 1.0 op_sel:[1,0,0]
	v_cvt_scalef32_pk_f16_fp4 v34, v16, 1.0 op_sel:[0,1,0]
	v_cvt_scalef32_pk_f16_fp4 v35, v16, 1.0 op_sel:[1,1,0]
	v_cvt_scalef32_pk_f16_fp4 v36, v17, 1.0
	v_cvt_scalef32_pk_f16_fp4 v37, v17, 1.0 op_sel:[1,0,0]
	v_cvt_scalef32_pk_f16_fp4 v38, v17, 1.0 op_sel:[0,1,0]
	v_cvt_scalef32_pk_f16_fp4 v39, v17, 1.0 op_sel:[1,1,0]
	v_cvt_scalef32_pk_f16_fp4 v40, v18, 1.0
	v_cvt_scalef32_pk_f16_fp4 v41, v18, 1.0 op_sel:[1,0,0]
	v_cvt_scalef32_pk_f16_fp4 v42, v18, 1.0 op_sel:[0,1,0]
	v_cvt_scalef32_pk_f16_fp4 v43, v18, 1.0 op_sel:[1,1,0]
	v_cvt_scalef32_pk_f16_fp4 v44, v19, 1.0
	v_cvt_scalef32_pk_f16_fp4 v45, v19, 1.0 op_sel:[1,0,0]
	v_cvt_scalef32_pk_f16_fp4 v46, v19, 1.0 op_sel:[0,1,0]
	v_cvt_scalef32_pk_f16_fp4 v47, v19, 1.0 op_sel:[1,1,0]
	buffer_load_dwordx4 v[12:15], v115, s[12:15], s4 offen
	v_pk_fma_f16 v139, v32, s0, v139
	v_pk_fma_f16 v138, v33, s0, v138
	v_pk_fma_f16 v136, v34, s0, v136
	v_pk_fma_f16 v135, v35, s0, v135
	v_pk_fma_f16 v134, v36, s0, v134
	v_pk_fma_f16 v133, v37, s0, v133
	v_pk_fma_f16 v132, v38, s0, v132
	v_pk_fma_f16 v131, v39, s0, v131
	v_pk_fma_f16 v130, v40, s0, v130
	v_pk_fma_f16 v129, v41, s0, v129
	v_pk_fma_f16 v128, v42, s0, v128
	v_pk_fma_f16 v127, v43, s0, v127
	v_pk_fma_f16 v126, v44, s0, v126
	v_pk_fma_f16 v114, v45, s0, v114
	v_pk_fma_f16 v140, v46, s0, v140
	v_pk_fma_f16 v137, v47, s0, v137
	s_waitcnt vmcnt(6)
	v_readlane_b32 s4, v48, 9
	v_readlane_b32 s0, v53, 7
	v_cvt_scalef32_pk_f16_fp4 v32, v20, 1.0
	v_cvt_scalef32_pk_f16_fp4 v33, v20, 1.0 op_sel:[1,0,0]
	v_cvt_scalef32_pk_f16_fp4 v34, v20, 1.0 op_sel:[0,1,0]
	v_cvt_scalef32_pk_f16_fp4 v35, v20, 1.0 op_sel:[1,1,0]
	v_cvt_scalef32_pk_f16_fp4 v36, v21, 1.0
	v_cvt_scalef32_pk_f16_fp4 v37, v21, 1.0 op_sel:[1,0,0]
	v_cvt_scalef32_pk_f16_fp4 v38, v21, 1.0 op_sel:[0,1,0]
	v_cvt_scalef32_pk_f16_fp4 v39, v21, 1.0 op_sel:[1,1,0]
	v_cvt_scalef32_pk_f16_fp4 v40, v22, 1.0
	v_cvt_scalef32_pk_f16_fp4 v41, v22, 1.0 op_sel:[1,0,0]
	v_cvt_scalef32_pk_f16_fp4 v42, v22, 1.0 op_sel:[0,1,0]
	v_cvt_scalef32_pk_f16_fp4 v43, v22, 1.0 op_sel:[1,1,0]
	v_cvt_scalef32_pk_f16_fp4 v44, v23, 1.0
	v_cvt_scalef32_pk_f16_fp4 v45, v23, 1.0 op_sel:[1,0,0]
	v_cvt_scalef32_pk_f16_fp4 v46, v23, 1.0 op_sel:[0,1,0]
	v_cvt_scalef32_pk_f16_fp4 v47, v23, 1.0 op_sel:[1,1,0]
	buffer_load_dwordx4 v[16:19], v115, s[12:15], s4 offen
	v_pk_fma_f16 v124, v32, s0, v124
	v_pk_fma_f16 v123, v33, s0, v123
	v_pk_fma_f16 v121, v34, s0, v121
	v_pk_fma_f16 v120, v35, s0, v120
	v_pk_fma_f16 v119, v36, s0, v119
	v_pk_fma_f16 v118, v37, s0, v118
	v_pk_fma_f16 v117, v38, s0, v117
	v_pk_fma_f16 v116, v39, s0, v116
	v_pk_fma_f16 v113, v40, s0, v113
	v_pk_fma_f16 v112, v41, s0, v112
	v_pk_fma_f16 v67, v42, s0, v67
	v_pk_fma_f16 v66, v43, s0, v66
	v_pk_fma_f16 v65, v44, s0, v65
	v_pk_fma_f16 v64, v45, s0, v64
	v_pk_fma_f16 v125, v46, s0, v125
	v_pk_fma_f16 v122, v47, s0, v122
	s_waitcnt vmcnt(6)
	v_readlane_b32 s4, v49, 9
	v_readlane_b32 s0, v54, 7
	v_cvt_scalef32_pk_f16_fp4 v32, v24, 1.0
	v_cvt_scalef32_pk_f16_fp4 v33, v24, 1.0 op_sel:[1,0,0]
	v_cvt_scalef32_pk_f16_fp4 v34, v24, 1.0 op_sel:[0,1,0]
	v_cvt_scalef32_pk_f16_fp4 v35, v24, 1.0 op_sel:[1,1,0]
	v_cvt_scalef32_pk_f16_fp4 v36, v25, 1.0
	v_cvt_scalef32_pk_f16_fp4 v37, v25, 1.0 op_sel:[1,0,0]
	v_cvt_scalef32_pk_f16_fp4 v38, v25, 1.0 op_sel:[0,1,0]
	v_cvt_scalef32_pk_f16_fp4 v39, v25, 1.0 op_sel:[1,1,0]
	v_cvt_scalef32_pk_f16_fp4 v40, v26, 1.0
	v_cvt_scalef32_pk_f16_fp4 v41, v26, 1.0 op_sel:[1,0,0]
	v_cvt_scalef32_pk_f16_fp4 v42, v26, 1.0 op_sel:[0,1,0]
	v_cvt_scalef32_pk_f16_fp4 v43, v26, 1.0 op_sel:[1,1,0]
	v_cvt_scalef32_pk_f16_fp4 v44, v27, 1.0
	v_cvt_scalef32_pk_f16_fp4 v45, v27, 1.0 op_sel:[1,0,0]
	v_cvt_scalef32_pk_f16_fp4 v46, v27, 1.0 op_sel:[0,1,0]
	v_cvt_scalef32_pk_f16_fp4 v47, v27, 1.0 op_sel:[1,1,0]
	buffer_load_dwordx4 v[20:23], v115, s[12:15], s4 offen
	v_pk_fma_f16 v74, v32, s0, v74
	v_pk_fma_f16 v73, v33, s0, v73
	v_pk_fma_f16 v71, v34, s0, v71
	v_pk_fma_f16 v70, v35, s0, v70
	v_pk_fma_f16 v69, v36, s0, v69
	v_pk_fma_f16 v68, v37, s0, v68
	v_pk_fma_f16 v63, v38, s0, v63
	v_pk_fma_f16 v62, v39, s0, v62
	v_pk_fma_f16 v61, v40, s0, v61
	v_pk_fma_f16 v60, v41, s0, v60
	v_pk_fma_f16 v59, v42, s0, v59
	v_pk_fma_f16 v58, v43, s0, v58
	v_pk_fma_f16 v57, v44, s0, v57
	v_pk_fma_f16 v56, v45, s0, v56
	v_pk_fma_f16 v75, v46, s0, v75
	v_pk_fma_f16 v72, v47, s0, v72
	s_waitcnt vmcnt(6)
	v_readlane_b32 s4, v50, 9
	v_readlane_b32 s0, v55, 7
	v_cvt_scalef32_pk_f16_fp4 v32, v28, 1.0
	v_cvt_scalef32_pk_f16_fp4 v33, v28, 1.0 op_sel:[1,0,0]
	v_cvt_scalef32_pk_f16_fp4 v34, v28, 1.0 op_sel:[0,1,0]
	v_cvt_scalef32_pk_f16_fp4 v35, v28, 1.0 op_sel:[1,1,0]
	v_cvt_scalef32_pk_f16_fp4 v36, v29, 1.0
	v_cvt_scalef32_pk_f16_fp4 v37, v29, 1.0 op_sel:[1,0,0]
	v_cvt_scalef32_pk_f16_fp4 v38, v29, 1.0 op_sel:[0,1,0]
	v_cvt_scalef32_pk_f16_fp4 v39, v29, 1.0 op_sel:[1,1,0]
	v_cvt_scalef32_pk_f16_fp4 v40, v30, 1.0
	v_cvt_scalef32_pk_f16_fp4 v41, v30, 1.0 op_sel:[1,0,0]
	v_cvt_scalef32_pk_f16_fp4 v42, v30, 1.0 op_sel:[0,1,0]
	v_cvt_scalef32_pk_f16_fp4 v43, v30, 1.0 op_sel:[1,1,0]
	v_cvt_scalef32_pk_f16_fp4 v44, v31, 1.0
	v_cvt_scalef32_pk_f16_fp4 v45, v31, 1.0 op_sel:[1,0,0]
	v_cvt_scalef32_pk_f16_fp4 v46, v31, 1.0 op_sel:[0,1,0]
	v_cvt_scalef32_pk_f16_fp4 v47, v31, 1.0 op_sel:[1,1,0]
	buffer_load_dwordx4 v[24:27], v115, s[12:15], s4 offen
	v_pk_fma_f16 v162, v32, s0, v162
	v_pk_fma_f16 v161, v33, s0, v161
	v_pk_fma_f16 v160, v34, s0, v160
	v_pk_fma_f16 v159, v35, s0, v159
	v_pk_fma_f16 v158, v36, s0, v158
	v_pk_fma_f16 v157, v37, s0, v157
	v_pk_fma_f16 v156, v38, s0, v156
	v_pk_fma_f16 v147, v39, s0, v147
	v_pk_fma_f16 v146, v40, s0, v146
	v_pk_fma_f16 v145, v41, s0, v145
	v_pk_fma_f16 v144, v42, s0, v144
	v_pk_fma_f16 v143, v43, s0, v143
	v_pk_fma_f16 v142, v44, s0, v142
	v_pk_fma_f16 v141, v45, s0, v141
	v_pk_fma_f16 v149, v46, s0, v149
	v_pk_fma_f16 v148, v47, s0, v148
	s_waitcnt vmcnt(6)
	v_readlane_b32 s4, v51, 9
	v_readlane_b32 s0, v52, 8
	v_cvt_scalef32_pk_f16_fp4 v32, v0, 1.0
	v_cvt_scalef32_pk_f16_fp4 v33, v0, 1.0 op_sel:[1,0,0]
	v_cvt_scalef32_pk_f16_fp4 v34, v0, 1.0 op_sel:[0,1,0]
	v_cvt_scalef32_pk_f16_fp4 v35, v0, 1.0 op_sel:[1,1,0]
	v_cvt_scalef32_pk_f16_fp4 v36, v1, 1.0
	v_cvt_scalef32_pk_f16_fp4 v37, v1, 1.0 op_sel:[1,0,0]
	v_cvt_scalef32_pk_f16_fp4 v38, v1, 1.0 op_sel:[0,1,0]
	v_cvt_scalef32_pk_f16_fp4 v39, v1, 1.0 op_sel:[1,1,0]
	v_cvt_scalef32_pk_f16_fp4 v40, v2, 1.0
	v_cvt_scalef32_pk_f16_fp4 v41, v2, 1.0 op_sel:[1,0,0]
	v_cvt_scalef32_pk_f16_fp4 v42, v2, 1.0 op_sel:[0,1,0]
	v_cvt_scalef32_pk_f16_fp4 v43, v2, 1.0 op_sel:[1,1,0]
	v_cvt_scalef32_pk_f16_fp4 v44, v3, 1.0
	v_cvt_scalef32_pk_f16_fp4 v45, v3, 1.0 op_sel:[1,0,0]
	v_cvt_scalef32_pk_f16_fp4 v46, v3, 1.0 op_sel:[0,1,0]
	v_cvt_scalef32_pk_f16_fp4 v47, v3, 1.0 op_sel:[1,1,0]
	buffer_load_dwordx4 v[28:31], v115, s[12:15], s4 offen
	v_pk_fma_f16 v139, v32, s0, v139
	v_pk_fma_f16 v138, v33, s0, v138
	v_pk_fma_f16 v136, v34, s0, v136
	v_pk_fma_f16 v135, v35, s0, v135
	v_pk_fma_f16 v134, v36, s0, v134
	v_pk_fma_f16 v133, v37, s0, v133
	v_pk_fma_f16 v132, v38, s0, v132
	v_pk_fma_f16 v131, v39, s0, v131
	v_pk_fma_f16 v130, v40, s0, v130
	v_pk_fma_f16 v129, v41, s0, v129
	v_pk_fma_f16 v128, v42, s0, v128
	v_pk_fma_f16 v127, v43, s0, v127
	v_pk_fma_f16 v126, v44, s0, v126
	v_pk_fma_f16 v114, v45, s0, v114
	v_pk_fma_f16 v140, v46, s0, v140
	v_pk_fma_f16 v137, v47, s0, v137
	s_waitcnt vmcnt(6)
	v_readlane_b32 s4, v48, 10
	v_readlane_b32 s0, v53, 8
	v_cvt_scalef32_pk_f16_fp4 v32, v4, 1.0
	v_cvt_scalef32_pk_f16_fp4 v33, v4, 1.0 op_sel:[1,0,0]
	v_cvt_scalef32_pk_f16_fp4 v34, v4, 1.0 op_sel:[0,1,0]
	v_cvt_scalef32_pk_f16_fp4 v35, v4, 1.0 op_sel:[1,1,0]
	v_cvt_scalef32_pk_f16_fp4 v36, v5, 1.0
	v_cvt_scalef32_pk_f16_fp4 v37, v5, 1.0 op_sel:[1,0,0]
	v_cvt_scalef32_pk_f16_fp4 v38, v5, 1.0 op_sel:[0,1,0]
	v_cvt_scalef32_pk_f16_fp4 v39, v5, 1.0 op_sel:[1,1,0]
	v_cvt_scalef32_pk_f16_fp4 v40, v6, 1.0
	v_cvt_scalef32_pk_f16_fp4 v41, v6, 1.0 op_sel:[1,0,0]
	v_cvt_scalef32_pk_f16_fp4 v42, v6, 1.0 op_sel:[0,1,0]
	v_cvt_scalef32_pk_f16_fp4 v43, v6, 1.0 op_sel:[1,1,0]
	v_cvt_scalef32_pk_f16_fp4 v44, v7, 1.0
	v_cvt_scalef32_pk_f16_fp4 v45, v7, 1.0 op_sel:[1,0,0]
	v_cvt_scalef32_pk_f16_fp4 v46, v7, 1.0 op_sel:[0,1,0]
	v_cvt_scalef32_pk_f16_fp4 v47, v7, 1.0 op_sel:[1,1,0]
	buffer_load_dwordx4 v[0:3], v115, s[12:15], s4 offen
	v_pk_fma_f16 v124, v32, s0, v124
	v_pk_fma_f16 v123, v33, s0, v123
	v_pk_fma_f16 v121, v34, s0, v121
	v_pk_fma_f16 v120, v35, s0, v120
	v_pk_fma_f16 v119, v36, s0, v119
	v_pk_fma_f16 v118, v37, s0, v118
	v_pk_fma_f16 v117, v38, s0, v117
	v_pk_fma_f16 v116, v39, s0, v116
	v_pk_fma_f16 v113, v40, s0, v113
	v_pk_fma_f16 v112, v41, s0, v112
	v_pk_fma_f16 v67, v42, s0, v67
	v_pk_fma_f16 v66, v43, s0, v66
	v_pk_fma_f16 v65, v44, s0, v65
	v_pk_fma_f16 v64, v45, s0, v64
	v_pk_fma_f16 v125, v46, s0, v125
	v_pk_fma_f16 v122, v47, s0, v122
	s_waitcnt vmcnt(6)
	v_readlane_b32 s4, v49, 10
	v_readlane_b32 s0, v54, 8
	v_cvt_scalef32_pk_f16_fp4 v32, v8, 1.0
	v_cvt_scalef32_pk_f16_fp4 v33, v8, 1.0 op_sel:[1,0,0]
	v_cvt_scalef32_pk_f16_fp4 v34, v8, 1.0 op_sel:[0,1,0]
	v_cvt_scalef32_pk_f16_fp4 v35, v8, 1.0 op_sel:[1,1,0]
	v_cvt_scalef32_pk_f16_fp4 v36, v9, 1.0
	v_cvt_scalef32_pk_f16_fp4 v37, v9, 1.0 op_sel:[1,0,0]
	v_cvt_scalef32_pk_f16_fp4 v38, v9, 1.0 op_sel:[0,1,0]
	v_cvt_scalef32_pk_f16_fp4 v39, v9, 1.0 op_sel:[1,1,0]
	v_cvt_scalef32_pk_f16_fp4 v40, v10, 1.0
	v_cvt_scalef32_pk_f16_fp4 v41, v10, 1.0 op_sel:[1,0,0]
	v_cvt_scalef32_pk_f16_fp4 v42, v10, 1.0 op_sel:[0,1,0]
	v_cvt_scalef32_pk_f16_fp4 v43, v10, 1.0 op_sel:[1,1,0]
	v_cvt_scalef32_pk_f16_fp4 v44, v11, 1.0
	v_cvt_scalef32_pk_f16_fp4 v45, v11, 1.0 op_sel:[1,0,0]
	v_cvt_scalef32_pk_f16_fp4 v46, v11, 1.0 op_sel:[0,1,0]
	v_cvt_scalef32_pk_f16_fp4 v47, v11, 1.0 op_sel:[1,1,0]
	buffer_load_dwordx4 v[4:7], v115, s[12:15], s4 offen
	v_pk_fma_f16 v74, v32, s0, v74
	v_pk_fma_f16 v73, v33, s0, v73
	v_pk_fma_f16 v71, v34, s0, v71
	v_pk_fma_f16 v70, v35, s0, v70
	v_pk_fma_f16 v69, v36, s0, v69
	v_pk_fma_f16 v68, v37, s0, v68
	v_pk_fma_f16 v63, v38, s0, v63
	v_pk_fma_f16 v62, v39, s0, v62
	v_pk_fma_f16 v61, v40, s0, v61
	v_pk_fma_f16 v60, v41, s0, v60
	v_pk_fma_f16 v59, v42, s0, v59
	v_pk_fma_f16 v58, v43, s0, v58
	v_pk_fma_f16 v57, v44, s0, v57
	v_pk_fma_f16 v56, v45, s0, v56
	v_pk_fma_f16 v75, v46, s0, v75
	v_pk_fma_f16 v72, v47, s0, v72
	s_waitcnt vmcnt(6)
	v_readlane_b32 s4, v50, 10
	v_readlane_b32 s0, v55, 8
	v_cvt_scalef32_pk_f16_fp4 v32, v12, 1.0
	v_cvt_scalef32_pk_f16_fp4 v33, v12, 1.0 op_sel:[1,0,0]
	v_cvt_scalef32_pk_f16_fp4 v34, v12, 1.0 op_sel:[0,1,0]
	v_cvt_scalef32_pk_f16_fp4 v35, v12, 1.0 op_sel:[1,1,0]
	v_cvt_scalef32_pk_f16_fp4 v36, v13, 1.0
	v_cvt_scalef32_pk_f16_fp4 v37, v13, 1.0 op_sel:[1,0,0]
	v_cvt_scalef32_pk_f16_fp4 v38, v13, 1.0 op_sel:[0,1,0]
	v_cvt_scalef32_pk_f16_fp4 v39, v13, 1.0 op_sel:[1,1,0]
	v_cvt_scalef32_pk_f16_fp4 v40, v14, 1.0
	v_cvt_scalef32_pk_f16_fp4 v41, v14, 1.0 op_sel:[1,0,0]
	v_cvt_scalef32_pk_f16_fp4 v42, v14, 1.0 op_sel:[0,1,0]
	v_cvt_scalef32_pk_f16_fp4 v43, v14, 1.0 op_sel:[1,1,0]
	v_cvt_scalef32_pk_f16_fp4 v44, v15, 1.0
	v_cvt_scalef32_pk_f16_fp4 v45, v15, 1.0 op_sel:[1,0,0]
	v_cvt_scalef32_pk_f16_fp4 v46, v15, 1.0 op_sel:[0,1,0]
	v_cvt_scalef32_pk_f16_fp4 v47, v15, 1.0 op_sel:[1,1,0]
	buffer_load_dwordx4 v[8:11], v115, s[12:15], s4 offen
	v_pk_fma_f16 v162, v32, s0, v162
	v_pk_fma_f16 v161, v33, s0, v161
	v_pk_fma_f16 v160, v34, s0, v160
	v_pk_fma_f16 v159, v35, s0, v159
	v_pk_fma_f16 v158, v36, s0, v158
	v_pk_fma_f16 v157, v37, s0, v157
	v_pk_fma_f16 v156, v38, s0, v156
	v_pk_fma_f16 v147, v39, s0, v147
	v_pk_fma_f16 v146, v40, s0, v146
	v_pk_fma_f16 v145, v41, s0, v145
	v_pk_fma_f16 v144, v42, s0, v144
	v_pk_fma_f16 v143, v43, s0, v143
	v_pk_fma_f16 v142, v44, s0, v142
	v_pk_fma_f16 v141, v45, s0, v141
	v_pk_fma_f16 v149, v46, s0, v149
	v_pk_fma_f16 v148, v47, s0, v148
	s_waitcnt vmcnt(6)
	v_readlane_b32 s4, v51, 10
	v_readlane_b32 s0, v52, 9
	v_cvt_scalef32_pk_f16_fp4 v32, v16, 1.0
	v_cvt_scalef32_pk_f16_fp4 v33, v16, 1.0 op_sel:[1,0,0]
	v_cvt_scalef32_pk_f16_fp4 v34, v16, 1.0 op_sel:[0,1,0]
	v_cvt_scalef32_pk_f16_fp4 v35, v16, 1.0 op_sel:[1,1,0]
	v_cvt_scalef32_pk_f16_fp4 v36, v17, 1.0
	v_cvt_scalef32_pk_f16_fp4 v37, v17, 1.0 op_sel:[1,0,0]
	v_cvt_scalef32_pk_f16_fp4 v38, v17, 1.0 op_sel:[0,1,0]
	v_cvt_scalef32_pk_f16_fp4 v39, v17, 1.0 op_sel:[1,1,0]
	v_cvt_scalef32_pk_f16_fp4 v40, v18, 1.0
	v_cvt_scalef32_pk_f16_fp4 v41, v18, 1.0 op_sel:[1,0,0]
	v_cvt_scalef32_pk_f16_fp4 v42, v18, 1.0 op_sel:[0,1,0]
	v_cvt_scalef32_pk_f16_fp4 v43, v18, 1.0 op_sel:[1,1,0]
	v_cvt_scalef32_pk_f16_fp4 v44, v19, 1.0
	v_cvt_scalef32_pk_f16_fp4 v45, v19, 1.0 op_sel:[1,0,0]
	v_cvt_scalef32_pk_f16_fp4 v46, v19, 1.0 op_sel:[0,1,0]
	v_cvt_scalef32_pk_f16_fp4 v47, v19, 1.0 op_sel:[1,1,0]
	buffer_load_dwordx4 v[12:15], v115, s[12:15], s4 offen
	v_pk_fma_f16 v139, v32, s0, v139
	v_pk_fma_f16 v138, v33, s0, v138
	v_pk_fma_f16 v136, v34, s0, v136
	v_pk_fma_f16 v135, v35, s0, v135
	v_pk_fma_f16 v134, v36, s0, v134
	v_pk_fma_f16 v133, v37, s0, v133
	v_pk_fma_f16 v132, v38, s0, v132
	v_pk_fma_f16 v131, v39, s0, v131
	v_pk_fma_f16 v130, v40, s0, v130
	v_pk_fma_f16 v129, v41, s0, v129
	v_pk_fma_f16 v128, v42, s0, v128
	v_pk_fma_f16 v127, v43, s0, v127
	v_pk_fma_f16 v126, v44, s0, v126
	v_pk_fma_f16 v114, v45, s0, v114
	v_pk_fma_f16 v140, v46, s0, v140
	v_pk_fma_f16 v137, v47, s0, v137
	s_waitcnt vmcnt(6)
	v_readlane_b32 s4, v48, 11
	v_readlane_b32 s0, v53, 9
	v_cvt_scalef32_pk_f16_fp4 v32, v20, 1.0
	v_cvt_scalef32_pk_f16_fp4 v33, v20, 1.0 op_sel:[1,0,0]
	v_cvt_scalef32_pk_f16_fp4 v34, v20, 1.0 op_sel:[0,1,0]
	v_cvt_scalef32_pk_f16_fp4 v35, v20, 1.0 op_sel:[1,1,0]
	v_cvt_scalef32_pk_f16_fp4 v36, v21, 1.0
	v_cvt_scalef32_pk_f16_fp4 v37, v21, 1.0 op_sel:[1,0,0]
	v_cvt_scalef32_pk_f16_fp4 v38, v21, 1.0 op_sel:[0,1,0]
	v_cvt_scalef32_pk_f16_fp4 v39, v21, 1.0 op_sel:[1,1,0]
	v_cvt_scalef32_pk_f16_fp4 v40, v22, 1.0
	v_cvt_scalef32_pk_f16_fp4 v41, v22, 1.0 op_sel:[1,0,0]
	v_cvt_scalef32_pk_f16_fp4 v42, v22, 1.0 op_sel:[0,1,0]
	v_cvt_scalef32_pk_f16_fp4 v43, v22, 1.0 op_sel:[1,1,0]
	v_cvt_scalef32_pk_f16_fp4 v44, v23, 1.0
	v_cvt_scalef32_pk_f16_fp4 v45, v23, 1.0 op_sel:[1,0,0]
	v_cvt_scalef32_pk_f16_fp4 v46, v23, 1.0 op_sel:[0,1,0]
	v_cvt_scalef32_pk_f16_fp4 v47, v23, 1.0 op_sel:[1,1,0]
	buffer_load_dwordx4 v[16:19], v115, s[12:15], s4 offen
	v_pk_fma_f16 v124, v32, s0, v124
	v_pk_fma_f16 v123, v33, s0, v123
	v_pk_fma_f16 v121, v34, s0, v121
	v_pk_fma_f16 v120, v35, s0, v120
	v_pk_fma_f16 v119, v36, s0, v119
	v_pk_fma_f16 v118, v37, s0, v118
	v_pk_fma_f16 v117, v38, s0, v117
	v_pk_fma_f16 v116, v39, s0, v116
	v_pk_fma_f16 v113, v40, s0, v113
	v_pk_fma_f16 v112, v41, s0, v112
	v_pk_fma_f16 v67, v42, s0, v67
	v_pk_fma_f16 v66, v43, s0, v66
	v_pk_fma_f16 v65, v44, s0, v65
	v_pk_fma_f16 v64, v45, s0, v64
	v_pk_fma_f16 v125, v46, s0, v125
	v_pk_fma_f16 v122, v47, s0, v122
	s_waitcnt vmcnt(6)
	v_readlane_b32 s4, v49, 11
	v_readlane_b32 s0, v54, 9
	v_cvt_scalef32_pk_f16_fp4 v32, v24, 1.0
	v_cvt_scalef32_pk_f16_fp4 v33, v24, 1.0 op_sel:[1,0,0]
	v_cvt_scalef32_pk_f16_fp4 v34, v24, 1.0 op_sel:[0,1,0]
	v_cvt_scalef32_pk_f16_fp4 v35, v24, 1.0 op_sel:[1,1,0]
	v_cvt_scalef32_pk_f16_fp4 v36, v25, 1.0
	v_cvt_scalef32_pk_f16_fp4 v37, v25, 1.0 op_sel:[1,0,0]
	v_cvt_scalef32_pk_f16_fp4 v38, v25, 1.0 op_sel:[0,1,0]
	v_cvt_scalef32_pk_f16_fp4 v39, v25, 1.0 op_sel:[1,1,0]
	v_cvt_scalef32_pk_f16_fp4 v40, v26, 1.0
	v_cvt_scalef32_pk_f16_fp4 v41, v26, 1.0 op_sel:[1,0,0]
	v_cvt_scalef32_pk_f16_fp4 v42, v26, 1.0 op_sel:[0,1,0]
	v_cvt_scalef32_pk_f16_fp4 v43, v26, 1.0 op_sel:[1,1,0]
	v_cvt_scalef32_pk_f16_fp4 v44, v27, 1.0
	v_cvt_scalef32_pk_f16_fp4 v45, v27, 1.0 op_sel:[1,0,0]
	v_cvt_scalef32_pk_f16_fp4 v46, v27, 1.0 op_sel:[0,1,0]
	v_cvt_scalef32_pk_f16_fp4 v47, v27, 1.0 op_sel:[1,1,0]
	buffer_load_dwordx4 v[20:23], v115, s[12:15], s4 offen
	v_pk_fma_f16 v74, v32, s0, v74
	v_pk_fma_f16 v73, v33, s0, v73
	v_pk_fma_f16 v71, v34, s0, v71
	v_pk_fma_f16 v70, v35, s0, v70
	v_pk_fma_f16 v69, v36, s0, v69
	v_pk_fma_f16 v68, v37, s0, v68
	v_pk_fma_f16 v63, v38, s0, v63
	v_pk_fma_f16 v62, v39, s0, v62
	v_pk_fma_f16 v61, v40, s0, v61
	v_pk_fma_f16 v60, v41, s0, v60
	v_pk_fma_f16 v59, v42, s0, v59
	v_pk_fma_f16 v58, v43, s0, v58
	v_pk_fma_f16 v57, v44, s0, v57
	v_pk_fma_f16 v56, v45, s0, v56
	v_pk_fma_f16 v75, v46, s0, v75
	v_pk_fma_f16 v72, v47, s0, v72
	s_waitcnt vmcnt(6)
	v_readlane_b32 s4, v50, 11
	v_readlane_b32 s0, v55, 9
	v_cvt_scalef32_pk_f16_fp4 v32, v28, 1.0
	v_cvt_scalef32_pk_f16_fp4 v33, v28, 1.0 op_sel:[1,0,0]
	v_cvt_scalef32_pk_f16_fp4 v34, v28, 1.0 op_sel:[0,1,0]
	v_cvt_scalef32_pk_f16_fp4 v35, v28, 1.0 op_sel:[1,1,0]
	v_cvt_scalef32_pk_f16_fp4 v36, v29, 1.0
	v_cvt_scalef32_pk_f16_fp4 v37, v29, 1.0 op_sel:[1,0,0]
	v_cvt_scalef32_pk_f16_fp4 v38, v29, 1.0 op_sel:[0,1,0]
	v_cvt_scalef32_pk_f16_fp4 v39, v29, 1.0 op_sel:[1,1,0]
	v_cvt_scalef32_pk_f16_fp4 v40, v30, 1.0
	v_cvt_scalef32_pk_f16_fp4 v41, v30, 1.0 op_sel:[1,0,0]
	v_cvt_scalef32_pk_f16_fp4 v42, v30, 1.0 op_sel:[0,1,0]
	v_cvt_scalef32_pk_f16_fp4 v43, v30, 1.0 op_sel:[1,1,0]
	v_cvt_scalef32_pk_f16_fp4 v44, v31, 1.0
	v_cvt_scalef32_pk_f16_fp4 v45, v31, 1.0 op_sel:[1,0,0]
	v_cvt_scalef32_pk_f16_fp4 v46, v31, 1.0 op_sel:[0,1,0]
	v_cvt_scalef32_pk_f16_fp4 v47, v31, 1.0 op_sel:[1,1,0]
	buffer_load_dwordx4 v[24:27], v115, s[12:15], s4 offen
	v_pk_fma_f16 v162, v32, s0, v162
	v_pk_fma_f16 v161, v33, s0, v161
	v_pk_fma_f16 v160, v34, s0, v160
	v_pk_fma_f16 v159, v35, s0, v159
	v_pk_fma_f16 v158, v36, s0, v158
	v_pk_fma_f16 v157, v37, s0, v157
	v_pk_fma_f16 v156, v38, s0, v156
	v_pk_fma_f16 v147, v39, s0, v147
	v_pk_fma_f16 v146, v40, s0, v146
	v_pk_fma_f16 v145, v41, s0, v145
	v_pk_fma_f16 v144, v42, s0, v144
	v_pk_fma_f16 v143, v43, s0, v143
	v_pk_fma_f16 v142, v44, s0, v142
	v_pk_fma_f16 v141, v45, s0, v141
	v_pk_fma_f16 v149, v46, s0, v149
	v_pk_fma_f16 v148, v47, s0, v148
	s_waitcnt vmcnt(6)
	v_readlane_b32 s4, v51, 11
	v_readlane_b32 s0, v52, 10
	v_cvt_scalef32_pk_f16_fp4 v32, v0, 1.0
	v_cvt_scalef32_pk_f16_fp4 v33, v0, 1.0 op_sel:[1,0,0]
	v_cvt_scalef32_pk_f16_fp4 v34, v0, 1.0 op_sel:[0,1,0]
	v_cvt_scalef32_pk_f16_fp4 v35, v0, 1.0 op_sel:[1,1,0]
	v_cvt_scalef32_pk_f16_fp4 v36, v1, 1.0
	v_cvt_scalef32_pk_f16_fp4 v37, v1, 1.0 op_sel:[1,0,0]
	v_cvt_scalef32_pk_f16_fp4 v38, v1, 1.0 op_sel:[0,1,0]
	v_cvt_scalef32_pk_f16_fp4 v39, v1, 1.0 op_sel:[1,1,0]
	v_cvt_scalef32_pk_f16_fp4 v40, v2, 1.0
	v_cvt_scalef32_pk_f16_fp4 v41, v2, 1.0 op_sel:[1,0,0]
	v_cvt_scalef32_pk_f16_fp4 v42, v2, 1.0 op_sel:[0,1,0]
	v_cvt_scalef32_pk_f16_fp4 v43, v2, 1.0 op_sel:[1,1,0]
	v_cvt_scalef32_pk_f16_fp4 v44, v3, 1.0
	v_cvt_scalef32_pk_f16_fp4 v45, v3, 1.0 op_sel:[1,0,0]
	v_cvt_scalef32_pk_f16_fp4 v46, v3, 1.0 op_sel:[0,1,0]
	v_cvt_scalef32_pk_f16_fp4 v47, v3, 1.0 op_sel:[1,1,0]
	buffer_load_dwordx4 v[28:31], v115, s[12:15], s4 offen
	v_pk_fma_f16 v139, v32, s0, v139
	v_pk_fma_f16 v138, v33, s0, v138
	v_pk_fma_f16 v136, v34, s0, v136
	v_pk_fma_f16 v135, v35, s0, v135
	v_pk_fma_f16 v134, v36, s0, v134
	v_pk_fma_f16 v133, v37, s0, v133
	v_pk_fma_f16 v132, v38, s0, v132
	v_pk_fma_f16 v131, v39, s0, v131
	v_pk_fma_f16 v130, v40, s0, v130
	v_pk_fma_f16 v129, v41, s0, v129
	v_pk_fma_f16 v128, v42, s0, v128
	v_pk_fma_f16 v127, v43, s0, v127
	v_pk_fma_f16 v126, v44, s0, v126
	v_pk_fma_f16 v114, v45, s0, v114
	v_pk_fma_f16 v140, v46, s0, v140
	v_pk_fma_f16 v137, v47, s0, v137
	s_waitcnt vmcnt(6)
	v_readlane_b32 s4, v48, 12
	v_readlane_b32 s0, v53, 10
	v_cvt_scalef32_pk_f16_fp4 v32, v4, 1.0
	v_cvt_scalef32_pk_f16_fp4 v33, v4, 1.0 op_sel:[1,0,0]
	v_cvt_scalef32_pk_f16_fp4 v34, v4, 1.0 op_sel:[0,1,0]
	v_cvt_scalef32_pk_f16_fp4 v35, v4, 1.0 op_sel:[1,1,0]
	v_cvt_scalef32_pk_f16_fp4 v36, v5, 1.0
	v_cvt_scalef32_pk_f16_fp4 v37, v5, 1.0 op_sel:[1,0,0]
	v_cvt_scalef32_pk_f16_fp4 v38, v5, 1.0 op_sel:[0,1,0]
	v_cvt_scalef32_pk_f16_fp4 v39, v5, 1.0 op_sel:[1,1,0]
	v_cvt_scalef32_pk_f16_fp4 v40, v6, 1.0
	v_cvt_scalef32_pk_f16_fp4 v41, v6, 1.0 op_sel:[1,0,0]
	v_cvt_scalef32_pk_f16_fp4 v42, v6, 1.0 op_sel:[0,1,0]
	v_cvt_scalef32_pk_f16_fp4 v43, v6, 1.0 op_sel:[1,1,0]
	v_cvt_scalef32_pk_f16_fp4 v44, v7, 1.0
	v_cvt_scalef32_pk_f16_fp4 v45, v7, 1.0 op_sel:[1,0,0]
	v_cvt_scalef32_pk_f16_fp4 v46, v7, 1.0 op_sel:[0,1,0]
	v_cvt_scalef32_pk_f16_fp4 v47, v7, 1.0 op_sel:[1,1,0]
	buffer_load_dwordx4 v[0:3], v115, s[12:15], s4 offen
	v_pk_fma_f16 v124, v32, s0, v124
	v_pk_fma_f16 v123, v33, s0, v123
	v_pk_fma_f16 v121, v34, s0, v121
	v_pk_fma_f16 v120, v35, s0, v120
	v_pk_fma_f16 v119, v36, s0, v119
	v_pk_fma_f16 v118, v37, s0, v118
	v_pk_fma_f16 v117, v38, s0, v117
	v_pk_fma_f16 v116, v39, s0, v116
	v_pk_fma_f16 v113, v40, s0, v113
	v_pk_fma_f16 v112, v41, s0, v112
	v_pk_fma_f16 v67, v42, s0, v67
	v_pk_fma_f16 v66, v43, s0, v66
	v_pk_fma_f16 v65, v44, s0, v65
	v_pk_fma_f16 v64, v45, s0, v64
	v_pk_fma_f16 v125, v46, s0, v125
	v_pk_fma_f16 v122, v47, s0, v122
	s_waitcnt vmcnt(6)
	v_readlane_b32 s4, v49, 12
	v_readlane_b32 s0, v54, 10
	v_cvt_scalef32_pk_f16_fp4 v32, v8, 1.0
	v_cvt_scalef32_pk_f16_fp4 v33, v8, 1.0 op_sel:[1,0,0]
	v_cvt_scalef32_pk_f16_fp4 v34, v8, 1.0 op_sel:[0,1,0]
	v_cvt_scalef32_pk_f16_fp4 v35, v8, 1.0 op_sel:[1,1,0]
	v_cvt_scalef32_pk_f16_fp4 v36, v9, 1.0
	v_cvt_scalef32_pk_f16_fp4 v37, v9, 1.0 op_sel:[1,0,0]
	v_cvt_scalef32_pk_f16_fp4 v38, v9, 1.0 op_sel:[0,1,0]
	v_cvt_scalef32_pk_f16_fp4 v39, v9, 1.0 op_sel:[1,1,0]
	v_cvt_scalef32_pk_f16_fp4 v40, v10, 1.0
	v_cvt_scalef32_pk_f16_fp4 v41, v10, 1.0 op_sel:[1,0,0]
	v_cvt_scalef32_pk_f16_fp4 v42, v10, 1.0 op_sel:[0,1,0]
	v_cvt_scalef32_pk_f16_fp4 v43, v10, 1.0 op_sel:[1,1,0]
	v_cvt_scalef32_pk_f16_fp4 v44, v11, 1.0
	v_cvt_scalef32_pk_f16_fp4 v45, v11, 1.0 op_sel:[1,0,0]
	v_cvt_scalef32_pk_f16_fp4 v46, v11, 1.0 op_sel:[0,1,0]
	v_cvt_scalef32_pk_f16_fp4 v47, v11, 1.0 op_sel:[1,1,0]
	buffer_load_dwordx4 v[4:7], v115, s[12:15], s4 offen
	v_pk_fma_f16 v74, v32, s0, v74
	v_pk_fma_f16 v73, v33, s0, v73
	v_pk_fma_f16 v71, v34, s0, v71
	v_pk_fma_f16 v70, v35, s0, v70
	v_pk_fma_f16 v69, v36, s0, v69
	v_pk_fma_f16 v68, v37, s0, v68
	v_pk_fma_f16 v63, v38, s0, v63
	v_pk_fma_f16 v62, v39, s0, v62
	v_pk_fma_f16 v61, v40, s0, v61
	v_pk_fma_f16 v60, v41, s0, v60
	v_pk_fma_f16 v59, v42, s0, v59
	v_pk_fma_f16 v58, v43, s0, v58
	v_pk_fma_f16 v57, v44, s0, v57
	v_pk_fma_f16 v56, v45, s0, v56
	v_pk_fma_f16 v75, v46, s0, v75
	v_pk_fma_f16 v72, v47, s0, v72
	s_waitcnt vmcnt(6)
	v_readlane_b32 s4, v50, 12
	v_readlane_b32 s0, v55, 10
	v_cvt_scalef32_pk_f16_fp4 v32, v12, 1.0
	v_cvt_scalef32_pk_f16_fp4 v33, v12, 1.0 op_sel:[1,0,0]
	v_cvt_scalef32_pk_f16_fp4 v34, v12, 1.0 op_sel:[0,1,0]
	v_cvt_scalef32_pk_f16_fp4 v35, v12, 1.0 op_sel:[1,1,0]
	v_cvt_scalef32_pk_f16_fp4 v36, v13, 1.0
	v_cvt_scalef32_pk_f16_fp4 v37, v13, 1.0 op_sel:[1,0,0]
	v_cvt_scalef32_pk_f16_fp4 v38, v13, 1.0 op_sel:[0,1,0]
	v_cvt_scalef32_pk_f16_fp4 v39, v13, 1.0 op_sel:[1,1,0]
	v_cvt_scalef32_pk_f16_fp4 v40, v14, 1.0
	v_cvt_scalef32_pk_f16_fp4 v41, v14, 1.0 op_sel:[1,0,0]
	v_cvt_scalef32_pk_f16_fp4 v42, v14, 1.0 op_sel:[0,1,0]
	v_cvt_scalef32_pk_f16_fp4 v43, v14, 1.0 op_sel:[1,1,0]
	v_cvt_scalef32_pk_f16_fp4 v44, v15, 1.0
	v_cvt_scalef32_pk_f16_fp4 v45, v15, 1.0 op_sel:[1,0,0]
	v_cvt_scalef32_pk_f16_fp4 v46, v15, 1.0 op_sel:[0,1,0]
	v_cvt_scalef32_pk_f16_fp4 v47, v15, 1.0 op_sel:[1,1,0]
	buffer_load_dwordx4 v[8:11], v115, s[12:15], s4 offen
	v_pk_fma_f16 v162, v32, s0, v162
	v_pk_fma_f16 v161, v33, s0, v161
	v_pk_fma_f16 v160, v34, s0, v160
	v_pk_fma_f16 v159, v35, s0, v159
	v_pk_fma_f16 v158, v36, s0, v158
	v_pk_fma_f16 v157, v37, s0, v157
	v_pk_fma_f16 v156, v38, s0, v156
	v_pk_fma_f16 v147, v39, s0, v147
	v_pk_fma_f16 v146, v40, s0, v146
	v_pk_fma_f16 v145, v41, s0, v145
	v_pk_fma_f16 v144, v42, s0, v144
	v_pk_fma_f16 v143, v43, s0, v143
	v_pk_fma_f16 v142, v44, s0, v142
	v_pk_fma_f16 v141, v45, s0, v141
	v_pk_fma_f16 v149, v46, s0, v149
	v_pk_fma_f16 v148, v47, s0, v148
	s_waitcnt vmcnt(6)
	v_readlane_b32 s4, v51, 12
	v_readlane_b32 s0, v52, 11
	v_cvt_scalef32_pk_f16_fp4 v32, v16, 1.0
	v_cvt_scalef32_pk_f16_fp4 v33, v16, 1.0 op_sel:[1,0,0]
	v_cvt_scalef32_pk_f16_fp4 v34, v16, 1.0 op_sel:[0,1,0]
	v_cvt_scalef32_pk_f16_fp4 v35, v16, 1.0 op_sel:[1,1,0]
	v_cvt_scalef32_pk_f16_fp4 v36, v17, 1.0
	v_cvt_scalef32_pk_f16_fp4 v37, v17, 1.0 op_sel:[1,0,0]
	v_cvt_scalef32_pk_f16_fp4 v38, v17, 1.0 op_sel:[0,1,0]
	v_cvt_scalef32_pk_f16_fp4 v39, v17, 1.0 op_sel:[1,1,0]
	v_cvt_scalef32_pk_f16_fp4 v40, v18, 1.0
	v_cvt_scalef32_pk_f16_fp4 v41, v18, 1.0 op_sel:[1,0,0]
	v_cvt_scalef32_pk_f16_fp4 v42, v18, 1.0 op_sel:[0,1,0]
	v_cvt_scalef32_pk_f16_fp4 v43, v18, 1.0 op_sel:[1,1,0]
	v_cvt_scalef32_pk_f16_fp4 v44, v19, 1.0
	v_cvt_scalef32_pk_f16_fp4 v45, v19, 1.0 op_sel:[1,0,0]
	v_cvt_scalef32_pk_f16_fp4 v46, v19, 1.0 op_sel:[0,1,0]
	v_cvt_scalef32_pk_f16_fp4 v47, v19, 1.0 op_sel:[1,1,0]
	buffer_load_dwordx4 v[12:15], v115, s[12:15], s4 offen
	v_pk_fma_f16 v139, v32, s0, v139
	v_pk_fma_f16 v138, v33, s0, v138
	v_pk_fma_f16 v136, v34, s0, v136
	v_pk_fma_f16 v135, v35, s0, v135
	v_pk_fma_f16 v134, v36, s0, v134
	v_pk_fma_f16 v133, v37, s0, v133
	v_pk_fma_f16 v132, v38, s0, v132
	v_pk_fma_f16 v131, v39, s0, v131
	v_pk_fma_f16 v130, v40, s0, v130
	v_pk_fma_f16 v129, v41, s0, v129
	v_pk_fma_f16 v128, v42, s0, v128
	v_pk_fma_f16 v127, v43, s0, v127
	v_pk_fma_f16 v126, v44, s0, v126
	v_pk_fma_f16 v114, v45, s0, v114
	v_pk_fma_f16 v140, v46, s0, v140
	v_pk_fma_f16 v137, v47, s0, v137
	s_waitcnt vmcnt(6)
	v_readlane_b32 s4, v48, 13
	v_readlane_b32 s0, v53, 11
	v_cvt_scalef32_pk_f16_fp4 v32, v20, 1.0
	v_cvt_scalef32_pk_f16_fp4 v33, v20, 1.0 op_sel:[1,0,0]
	v_cvt_scalef32_pk_f16_fp4 v34, v20, 1.0 op_sel:[0,1,0]
	v_cvt_scalef32_pk_f16_fp4 v35, v20, 1.0 op_sel:[1,1,0]
	v_cvt_scalef32_pk_f16_fp4 v36, v21, 1.0
	v_cvt_scalef32_pk_f16_fp4 v37, v21, 1.0 op_sel:[1,0,0]
	v_cvt_scalef32_pk_f16_fp4 v38, v21, 1.0 op_sel:[0,1,0]
	v_cvt_scalef32_pk_f16_fp4 v39, v21, 1.0 op_sel:[1,1,0]
	v_cvt_scalef32_pk_f16_fp4 v40, v22, 1.0
	v_cvt_scalef32_pk_f16_fp4 v41, v22, 1.0 op_sel:[1,0,0]
	v_cvt_scalef32_pk_f16_fp4 v42, v22, 1.0 op_sel:[0,1,0]
	v_cvt_scalef32_pk_f16_fp4 v43, v22, 1.0 op_sel:[1,1,0]
	v_cvt_scalef32_pk_f16_fp4 v44, v23, 1.0
	v_cvt_scalef32_pk_f16_fp4 v45, v23, 1.0 op_sel:[1,0,0]
	v_cvt_scalef32_pk_f16_fp4 v46, v23, 1.0 op_sel:[0,1,0]
	v_cvt_scalef32_pk_f16_fp4 v47, v23, 1.0 op_sel:[1,1,0]
	buffer_load_dwordx4 v[16:19], v115, s[12:15], s4 offen
	v_pk_fma_f16 v124, v32, s0, v124
	v_pk_fma_f16 v123, v33, s0, v123
	v_pk_fma_f16 v121, v34, s0, v121
	v_pk_fma_f16 v120, v35, s0, v120
	v_pk_fma_f16 v119, v36, s0, v119
	v_pk_fma_f16 v118, v37, s0, v118
	v_pk_fma_f16 v117, v38, s0, v117
	v_pk_fma_f16 v116, v39, s0, v116
	v_pk_fma_f16 v113, v40, s0, v113
	v_pk_fma_f16 v112, v41, s0, v112
	v_pk_fma_f16 v67, v42, s0, v67
	v_pk_fma_f16 v66, v43, s0, v66
	v_pk_fma_f16 v65, v44, s0, v65
	v_pk_fma_f16 v64, v45, s0, v64
	v_pk_fma_f16 v125, v46, s0, v125
	v_pk_fma_f16 v122, v47, s0, v122
	s_waitcnt vmcnt(6)
	v_readlane_b32 s4, v49, 13
	v_readlane_b32 s0, v54, 11
	v_cvt_scalef32_pk_f16_fp4 v32, v24, 1.0
	v_cvt_scalef32_pk_f16_fp4 v33, v24, 1.0 op_sel:[1,0,0]
	v_cvt_scalef32_pk_f16_fp4 v34, v24, 1.0 op_sel:[0,1,0]
	v_cvt_scalef32_pk_f16_fp4 v35, v24, 1.0 op_sel:[1,1,0]
	v_cvt_scalef32_pk_f16_fp4 v36, v25, 1.0
	v_cvt_scalef32_pk_f16_fp4 v37, v25, 1.0 op_sel:[1,0,0]
	v_cvt_scalef32_pk_f16_fp4 v38, v25, 1.0 op_sel:[0,1,0]
	v_cvt_scalef32_pk_f16_fp4 v39, v25, 1.0 op_sel:[1,1,0]
	v_cvt_scalef32_pk_f16_fp4 v40, v26, 1.0
	v_cvt_scalef32_pk_f16_fp4 v41, v26, 1.0 op_sel:[1,0,0]
	v_cvt_scalef32_pk_f16_fp4 v42, v26, 1.0 op_sel:[0,1,0]
	v_cvt_scalef32_pk_f16_fp4 v43, v26, 1.0 op_sel:[1,1,0]
	v_cvt_scalef32_pk_f16_fp4 v44, v27, 1.0
	v_cvt_scalef32_pk_f16_fp4 v45, v27, 1.0 op_sel:[1,0,0]
	v_cvt_scalef32_pk_f16_fp4 v46, v27, 1.0 op_sel:[0,1,0]
	v_cvt_scalef32_pk_f16_fp4 v47, v27, 1.0 op_sel:[1,1,0]
	buffer_load_dwordx4 v[20:23], v115, s[12:15], s4 offen
	v_pk_fma_f16 v74, v32, s0, v74
	v_pk_fma_f16 v73, v33, s0, v73
	v_pk_fma_f16 v71, v34, s0, v71
	v_pk_fma_f16 v70, v35, s0, v70
	v_pk_fma_f16 v69, v36, s0, v69
	v_pk_fma_f16 v68, v37, s0, v68
	v_pk_fma_f16 v63, v38, s0, v63
	v_pk_fma_f16 v62, v39, s0, v62
	v_pk_fma_f16 v61, v40, s0, v61
	v_pk_fma_f16 v60, v41, s0, v60
	v_pk_fma_f16 v59, v42, s0, v59
	v_pk_fma_f16 v58, v43, s0, v58
	v_pk_fma_f16 v57, v44, s0, v57
	v_pk_fma_f16 v56, v45, s0, v56
	v_pk_fma_f16 v75, v46, s0, v75
	v_pk_fma_f16 v72, v47, s0, v72
	s_waitcnt vmcnt(6)
	v_readlane_b32 s4, v50, 13
	v_readlane_b32 s0, v55, 11
	v_cvt_scalef32_pk_f16_fp4 v32, v28, 1.0
	v_cvt_scalef32_pk_f16_fp4 v33, v28, 1.0 op_sel:[1,0,0]
	v_cvt_scalef32_pk_f16_fp4 v34, v28, 1.0 op_sel:[0,1,0]
	v_cvt_scalef32_pk_f16_fp4 v35, v28, 1.0 op_sel:[1,1,0]
	v_cvt_scalef32_pk_f16_fp4 v36, v29, 1.0
	v_cvt_scalef32_pk_f16_fp4 v37, v29, 1.0 op_sel:[1,0,0]
	v_cvt_scalef32_pk_f16_fp4 v38, v29, 1.0 op_sel:[0,1,0]
	v_cvt_scalef32_pk_f16_fp4 v39, v29, 1.0 op_sel:[1,1,0]
	v_cvt_scalef32_pk_f16_fp4 v40, v30, 1.0
	v_cvt_scalef32_pk_f16_fp4 v41, v30, 1.0 op_sel:[1,0,0]
	v_cvt_scalef32_pk_f16_fp4 v42, v30, 1.0 op_sel:[0,1,0]
	v_cvt_scalef32_pk_f16_fp4 v43, v30, 1.0 op_sel:[1,1,0]
	v_cvt_scalef32_pk_f16_fp4 v44, v31, 1.0
	v_cvt_scalef32_pk_f16_fp4 v45, v31, 1.0 op_sel:[1,0,0]
	v_cvt_scalef32_pk_f16_fp4 v46, v31, 1.0 op_sel:[0,1,0]
	v_cvt_scalef32_pk_f16_fp4 v47, v31, 1.0 op_sel:[1,1,0]
	buffer_load_dwordx4 v[24:27], v115, s[12:15], s4 offen
	v_pk_fma_f16 v162, v32, s0, v162
	v_pk_fma_f16 v161, v33, s0, v161
	v_pk_fma_f16 v160, v34, s0, v160
	v_pk_fma_f16 v159, v35, s0, v159
	v_pk_fma_f16 v158, v36, s0, v158
	v_pk_fma_f16 v157, v37, s0, v157
	v_pk_fma_f16 v156, v38, s0, v156
	v_pk_fma_f16 v147, v39, s0, v147
	v_pk_fma_f16 v146, v40, s0, v146
	v_pk_fma_f16 v145, v41, s0, v145
	v_pk_fma_f16 v144, v42, s0, v144
	v_pk_fma_f16 v143, v43, s0, v143
	v_pk_fma_f16 v142, v44, s0, v142
	v_pk_fma_f16 v141, v45, s0, v141
	v_pk_fma_f16 v149, v46, s0, v149
	v_pk_fma_f16 v148, v47, s0, v148
	s_waitcnt vmcnt(6)
	v_readlane_b32 s4, v51, 13
	v_readlane_b32 s0, v52, 12
	v_cvt_scalef32_pk_f16_fp4 v32, v0, 1.0
	v_cvt_scalef32_pk_f16_fp4 v33, v0, 1.0 op_sel:[1,0,0]
	v_cvt_scalef32_pk_f16_fp4 v34, v0, 1.0 op_sel:[0,1,0]
	v_cvt_scalef32_pk_f16_fp4 v35, v0, 1.0 op_sel:[1,1,0]
	v_cvt_scalef32_pk_f16_fp4 v36, v1, 1.0
	v_cvt_scalef32_pk_f16_fp4 v37, v1, 1.0 op_sel:[1,0,0]
	v_cvt_scalef32_pk_f16_fp4 v38, v1, 1.0 op_sel:[0,1,0]
	v_cvt_scalef32_pk_f16_fp4 v39, v1, 1.0 op_sel:[1,1,0]
	v_cvt_scalef32_pk_f16_fp4 v40, v2, 1.0
	v_cvt_scalef32_pk_f16_fp4 v41, v2, 1.0 op_sel:[1,0,0]
	v_cvt_scalef32_pk_f16_fp4 v42, v2, 1.0 op_sel:[0,1,0]
	v_cvt_scalef32_pk_f16_fp4 v43, v2, 1.0 op_sel:[1,1,0]
	v_cvt_scalef32_pk_f16_fp4 v44, v3, 1.0
	v_cvt_scalef32_pk_f16_fp4 v45, v3, 1.0 op_sel:[1,0,0]
	v_cvt_scalef32_pk_f16_fp4 v46, v3, 1.0 op_sel:[0,1,0]
	v_cvt_scalef32_pk_f16_fp4 v47, v3, 1.0 op_sel:[1,1,0]
	buffer_load_dwordx4 v[28:31], v115, s[12:15], s4 offen
	v_pk_fma_f16 v139, v32, s0, v139
	v_pk_fma_f16 v138, v33, s0, v138
	v_pk_fma_f16 v136, v34, s0, v136
	v_pk_fma_f16 v135, v35, s0, v135
	v_pk_fma_f16 v134, v36, s0, v134
	v_pk_fma_f16 v133, v37, s0, v133
	v_pk_fma_f16 v132, v38, s0, v132
	v_pk_fma_f16 v131, v39, s0, v131
	v_pk_fma_f16 v130, v40, s0, v130
	v_pk_fma_f16 v129, v41, s0, v129
	v_pk_fma_f16 v128, v42, s0, v128
	v_pk_fma_f16 v127, v43, s0, v127
	v_pk_fma_f16 v126, v44, s0, v126
	v_pk_fma_f16 v114, v45, s0, v114
	v_pk_fma_f16 v140, v46, s0, v140
	v_pk_fma_f16 v137, v47, s0, v137
	s_waitcnt vmcnt(6)
	v_readlane_b32 s4, v48, 14
	v_readlane_b32 s0, v53, 12
	v_cvt_scalef32_pk_f16_fp4 v32, v4, 1.0
	v_cvt_scalef32_pk_f16_fp4 v33, v4, 1.0 op_sel:[1,0,0]
	v_cvt_scalef32_pk_f16_fp4 v34, v4, 1.0 op_sel:[0,1,0]
	v_cvt_scalef32_pk_f16_fp4 v35, v4, 1.0 op_sel:[1,1,0]
	v_cvt_scalef32_pk_f16_fp4 v36, v5, 1.0
	v_cvt_scalef32_pk_f16_fp4 v37, v5, 1.0 op_sel:[1,0,0]
	v_cvt_scalef32_pk_f16_fp4 v38, v5, 1.0 op_sel:[0,1,0]
	v_cvt_scalef32_pk_f16_fp4 v39, v5, 1.0 op_sel:[1,1,0]
	v_cvt_scalef32_pk_f16_fp4 v40, v6, 1.0
	v_cvt_scalef32_pk_f16_fp4 v41, v6, 1.0 op_sel:[1,0,0]
	v_cvt_scalef32_pk_f16_fp4 v42, v6, 1.0 op_sel:[0,1,0]
	v_cvt_scalef32_pk_f16_fp4 v43, v6, 1.0 op_sel:[1,1,0]
	v_cvt_scalef32_pk_f16_fp4 v44, v7, 1.0
	v_cvt_scalef32_pk_f16_fp4 v45, v7, 1.0 op_sel:[1,0,0]
	v_cvt_scalef32_pk_f16_fp4 v46, v7, 1.0 op_sel:[0,1,0]
	v_cvt_scalef32_pk_f16_fp4 v47, v7, 1.0 op_sel:[1,1,0]
	buffer_load_dwordx4 v[0:3], v115, s[12:15], s4 offen
	v_pk_fma_f16 v124, v32, s0, v124
	v_pk_fma_f16 v123, v33, s0, v123
	v_pk_fma_f16 v121, v34, s0, v121
	v_pk_fma_f16 v120, v35, s0, v120
	v_pk_fma_f16 v119, v36, s0, v119
	v_pk_fma_f16 v118, v37, s0, v118
	v_pk_fma_f16 v117, v38, s0, v117
	v_pk_fma_f16 v116, v39, s0, v116
	v_pk_fma_f16 v113, v40, s0, v113
	v_pk_fma_f16 v112, v41, s0, v112
	v_pk_fma_f16 v67, v42, s0, v67
	v_pk_fma_f16 v66, v43, s0, v66
	v_pk_fma_f16 v65, v44, s0, v65
	v_pk_fma_f16 v64, v45, s0, v64
	v_pk_fma_f16 v125, v46, s0, v125
	v_pk_fma_f16 v122, v47, s0, v122
	s_waitcnt vmcnt(6)
	v_readlane_b32 s4, v49, 14
	v_readlane_b32 s0, v54, 12
	v_cvt_scalef32_pk_f16_fp4 v32, v8, 1.0
	v_cvt_scalef32_pk_f16_fp4 v33, v8, 1.0 op_sel:[1,0,0]
	v_cvt_scalef32_pk_f16_fp4 v34, v8, 1.0 op_sel:[0,1,0]
	v_cvt_scalef32_pk_f16_fp4 v35, v8, 1.0 op_sel:[1,1,0]
	v_cvt_scalef32_pk_f16_fp4 v36, v9, 1.0
	v_cvt_scalef32_pk_f16_fp4 v37, v9, 1.0 op_sel:[1,0,0]
	v_cvt_scalef32_pk_f16_fp4 v38, v9, 1.0 op_sel:[0,1,0]
	v_cvt_scalef32_pk_f16_fp4 v39, v9, 1.0 op_sel:[1,1,0]
	v_cvt_scalef32_pk_f16_fp4 v40, v10, 1.0
	v_cvt_scalef32_pk_f16_fp4 v41, v10, 1.0 op_sel:[1,0,0]
	v_cvt_scalef32_pk_f16_fp4 v42, v10, 1.0 op_sel:[0,1,0]
	v_cvt_scalef32_pk_f16_fp4 v43, v10, 1.0 op_sel:[1,1,0]
	v_cvt_scalef32_pk_f16_fp4 v44, v11, 1.0
	v_cvt_scalef32_pk_f16_fp4 v45, v11, 1.0 op_sel:[1,0,0]
	v_cvt_scalef32_pk_f16_fp4 v46, v11, 1.0 op_sel:[0,1,0]
	v_cvt_scalef32_pk_f16_fp4 v47, v11, 1.0 op_sel:[1,1,0]
	buffer_load_dwordx4 v[4:7], v115, s[12:15], s4 offen
	v_pk_fma_f16 v74, v32, s0, v74
	v_pk_fma_f16 v73, v33, s0, v73
	v_pk_fma_f16 v71, v34, s0, v71
	v_pk_fma_f16 v70, v35, s0, v70
	v_pk_fma_f16 v69, v36, s0, v69
	v_pk_fma_f16 v68, v37, s0, v68
	v_pk_fma_f16 v63, v38, s0, v63
	v_pk_fma_f16 v62, v39, s0, v62
	v_pk_fma_f16 v61, v40, s0, v61
	v_pk_fma_f16 v60, v41, s0, v60
	v_pk_fma_f16 v59, v42, s0, v59
	v_pk_fma_f16 v58, v43, s0, v58
	v_pk_fma_f16 v57, v44, s0, v57
	v_pk_fma_f16 v56, v45, s0, v56
	v_pk_fma_f16 v75, v46, s0, v75
	v_pk_fma_f16 v72, v47, s0, v72
	s_waitcnt vmcnt(6)
	v_readlane_b32 s4, v50, 14
	v_readlane_b32 s0, v55, 12
	v_cvt_scalef32_pk_f16_fp4 v32, v12, 1.0
	v_cvt_scalef32_pk_f16_fp4 v33, v12, 1.0 op_sel:[1,0,0]
	v_cvt_scalef32_pk_f16_fp4 v34, v12, 1.0 op_sel:[0,1,0]
	v_cvt_scalef32_pk_f16_fp4 v35, v12, 1.0 op_sel:[1,1,0]
	v_cvt_scalef32_pk_f16_fp4 v36, v13, 1.0
	v_cvt_scalef32_pk_f16_fp4 v37, v13, 1.0 op_sel:[1,0,0]
	v_cvt_scalef32_pk_f16_fp4 v38, v13, 1.0 op_sel:[0,1,0]
	v_cvt_scalef32_pk_f16_fp4 v39, v13, 1.0 op_sel:[1,1,0]
	v_cvt_scalef32_pk_f16_fp4 v40, v14, 1.0
	v_cvt_scalef32_pk_f16_fp4 v41, v14, 1.0 op_sel:[1,0,0]
	v_cvt_scalef32_pk_f16_fp4 v42, v14, 1.0 op_sel:[0,1,0]
	v_cvt_scalef32_pk_f16_fp4 v43, v14, 1.0 op_sel:[1,1,0]
	v_cvt_scalef32_pk_f16_fp4 v44, v15, 1.0
	v_cvt_scalef32_pk_f16_fp4 v45, v15, 1.0 op_sel:[1,0,0]
	v_cvt_scalef32_pk_f16_fp4 v46, v15, 1.0 op_sel:[0,1,0]
	v_cvt_scalef32_pk_f16_fp4 v47, v15, 1.0 op_sel:[1,1,0]
	buffer_load_dwordx4 v[8:11], v115, s[12:15], s4 offen
	v_pk_fma_f16 v162, v32, s0, v162
	v_pk_fma_f16 v161, v33, s0, v161
	v_pk_fma_f16 v160, v34, s0, v160
	v_pk_fma_f16 v159, v35, s0, v159
	v_pk_fma_f16 v158, v36, s0, v158
	v_pk_fma_f16 v157, v37, s0, v157
	v_pk_fma_f16 v156, v38, s0, v156
	v_pk_fma_f16 v147, v39, s0, v147
	v_pk_fma_f16 v146, v40, s0, v146
	v_pk_fma_f16 v145, v41, s0, v145
	v_pk_fma_f16 v144, v42, s0, v144
	v_pk_fma_f16 v143, v43, s0, v143
	v_pk_fma_f16 v142, v44, s0, v142
	v_pk_fma_f16 v141, v45, s0, v141
	v_pk_fma_f16 v149, v46, s0, v149
	v_pk_fma_f16 v148, v47, s0, v148
	s_waitcnt vmcnt(6)
	v_readlane_b32 s4, v51, 14
	v_readlane_b32 s0, v52, 13
	v_cvt_scalef32_pk_f16_fp4 v32, v16, 1.0
	v_cvt_scalef32_pk_f16_fp4 v33, v16, 1.0 op_sel:[1,0,0]
	v_cvt_scalef32_pk_f16_fp4 v34, v16, 1.0 op_sel:[0,1,0]
	v_cvt_scalef32_pk_f16_fp4 v35, v16, 1.0 op_sel:[1,1,0]
	v_cvt_scalef32_pk_f16_fp4 v36, v17, 1.0
	v_cvt_scalef32_pk_f16_fp4 v37, v17, 1.0 op_sel:[1,0,0]
	v_cvt_scalef32_pk_f16_fp4 v38, v17, 1.0 op_sel:[0,1,0]
	v_cvt_scalef32_pk_f16_fp4 v39, v17, 1.0 op_sel:[1,1,0]
	v_cvt_scalef32_pk_f16_fp4 v40, v18, 1.0
	v_cvt_scalef32_pk_f16_fp4 v41, v18, 1.0 op_sel:[1,0,0]
	v_cvt_scalef32_pk_f16_fp4 v42, v18, 1.0 op_sel:[0,1,0]
	v_cvt_scalef32_pk_f16_fp4 v43, v18, 1.0 op_sel:[1,1,0]
	v_cvt_scalef32_pk_f16_fp4 v44, v19, 1.0
	v_cvt_scalef32_pk_f16_fp4 v45, v19, 1.0 op_sel:[1,0,0]
	v_cvt_scalef32_pk_f16_fp4 v46, v19, 1.0 op_sel:[0,1,0]
	v_cvt_scalef32_pk_f16_fp4 v47, v19, 1.0 op_sel:[1,1,0]
	buffer_load_dwordx4 v[12:15], v115, s[12:15], s4 offen
	v_pk_fma_f16 v139, v32, s0, v139
	v_pk_fma_f16 v138, v33, s0, v138
	v_pk_fma_f16 v136, v34, s0, v136
	v_pk_fma_f16 v135, v35, s0, v135
	v_pk_fma_f16 v134, v36, s0, v134
	v_pk_fma_f16 v133, v37, s0, v133
	v_pk_fma_f16 v132, v38, s0, v132
	v_pk_fma_f16 v131, v39, s0, v131
	v_pk_fma_f16 v130, v40, s0, v130
	v_pk_fma_f16 v129, v41, s0, v129
	v_pk_fma_f16 v128, v42, s0, v128
	v_pk_fma_f16 v127, v43, s0, v127
	v_pk_fma_f16 v126, v44, s0, v126
	v_pk_fma_f16 v114, v45, s0, v114
	v_pk_fma_f16 v140, v46, s0, v140
	v_pk_fma_f16 v137, v47, s0, v137
	s_waitcnt vmcnt(6)
	v_readlane_b32 s4, v48, 15
	v_readlane_b32 s0, v53, 13
	v_cvt_scalef32_pk_f16_fp4 v32, v20, 1.0
	v_cvt_scalef32_pk_f16_fp4 v33, v20, 1.0 op_sel:[1,0,0]
	v_cvt_scalef32_pk_f16_fp4 v34, v20, 1.0 op_sel:[0,1,0]
	v_cvt_scalef32_pk_f16_fp4 v35, v20, 1.0 op_sel:[1,1,0]
	v_cvt_scalef32_pk_f16_fp4 v36, v21, 1.0
	v_cvt_scalef32_pk_f16_fp4 v37, v21, 1.0 op_sel:[1,0,0]
	v_cvt_scalef32_pk_f16_fp4 v38, v21, 1.0 op_sel:[0,1,0]
	v_cvt_scalef32_pk_f16_fp4 v39, v21, 1.0 op_sel:[1,1,0]
	v_cvt_scalef32_pk_f16_fp4 v40, v22, 1.0
	v_cvt_scalef32_pk_f16_fp4 v41, v22, 1.0 op_sel:[1,0,0]
	v_cvt_scalef32_pk_f16_fp4 v42, v22, 1.0 op_sel:[0,1,0]
	v_cvt_scalef32_pk_f16_fp4 v43, v22, 1.0 op_sel:[1,1,0]
	v_cvt_scalef32_pk_f16_fp4 v44, v23, 1.0
	v_cvt_scalef32_pk_f16_fp4 v45, v23, 1.0 op_sel:[1,0,0]
	v_cvt_scalef32_pk_f16_fp4 v46, v23, 1.0 op_sel:[0,1,0]
	v_cvt_scalef32_pk_f16_fp4 v47, v23, 1.0 op_sel:[1,1,0]
	buffer_load_dwordx4 v[16:19], v115, s[12:15], s4 offen
	v_pk_fma_f16 v124, v32, s0, v124
	v_pk_fma_f16 v123, v33, s0, v123
	v_pk_fma_f16 v121, v34, s0, v121
	v_pk_fma_f16 v120, v35, s0, v120
	v_pk_fma_f16 v119, v36, s0, v119
	v_pk_fma_f16 v118, v37, s0, v118
	v_pk_fma_f16 v117, v38, s0, v117
	v_pk_fma_f16 v116, v39, s0, v116
	v_pk_fma_f16 v113, v40, s0, v113
	v_pk_fma_f16 v112, v41, s0, v112
	v_pk_fma_f16 v67, v42, s0, v67
	v_pk_fma_f16 v66, v43, s0, v66
	v_pk_fma_f16 v65, v44, s0, v65
	v_pk_fma_f16 v64, v45, s0, v64
	v_pk_fma_f16 v125, v46, s0, v125
	v_pk_fma_f16 v122, v47, s0, v122
	s_waitcnt vmcnt(6)
	v_readlane_b32 s4, v49, 15
	v_readlane_b32 s0, v54, 13
	v_cvt_scalef32_pk_f16_fp4 v32, v24, 1.0
	v_cvt_scalef32_pk_f16_fp4 v33, v24, 1.0 op_sel:[1,0,0]
	v_cvt_scalef32_pk_f16_fp4 v34, v24, 1.0 op_sel:[0,1,0]
	v_cvt_scalef32_pk_f16_fp4 v35, v24, 1.0 op_sel:[1,1,0]
	v_cvt_scalef32_pk_f16_fp4 v36, v25, 1.0
	v_cvt_scalef32_pk_f16_fp4 v37, v25, 1.0 op_sel:[1,0,0]
	v_cvt_scalef32_pk_f16_fp4 v38, v25, 1.0 op_sel:[0,1,0]
	v_cvt_scalef32_pk_f16_fp4 v39, v25, 1.0 op_sel:[1,1,0]
	v_cvt_scalef32_pk_f16_fp4 v40, v26, 1.0
	v_cvt_scalef32_pk_f16_fp4 v41, v26, 1.0 op_sel:[1,0,0]
	v_cvt_scalef32_pk_f16_fp4 v42, v26, 1.0 op_sel:[0,1,0]
	v_cvt_scalef32_pk_f16_fp4 v43, v26, 1.0 op_sel:[1,1,0]
	v_cvt_scalef32_pk_f16_fp4 v44, v27, 1.0
	v_cvt_scalef32_pk_f16_fp4 v45, v27, 1.0 op_sel:[1,0,0]
	v_cvt_scalef32_pk_f16_fp4 v46, v27, 1.0 op_sel:[0,1,0]
	v_cvt_scalef32_pk_f16_fp4 v47, v27, 1.0 op_sel:[1,1,0]
	buffer_load_dwordx4 v[20:23], v115, s[12:15], s4 offen
	v_pk_fma_f16 v74, v32, s0, v74
	v_pk_fma_f16 v73, v33, s0, v73
	v_pk_fma_f16 v71, v34, s0, v71
	v_pk_fma_f16 v70, v35, s0, v70
	v_pk_fma_f16 v69, v36, s0, v69
	v_pk_fma_f16 v68, v37, s0, v68
	v_pk_fma_f16 v63, v38, s0, v63
	v_pk_fma_f16 v62, v39, s0, v62
	v_pk_fma_f16 v61, v40, s0, v61
	v_pk_fma_f16 v60, v41, s0, v60
	v_pk_fma_f16 v59, v42, s0, v59
	v_pk_fma_f16 v58, v43, s0, v58
	v_pk_fma_f16 v57, v44, s0, v57
	v_pk_fma_f16 v56, v45, s0, v56
	v_pk_fma_f16 v75, v46, s0, v75
	v_pk_fma_f16 v72, v47, s0, v72
	s_waitcnt vmcnt(6)
	v_readlane_b32 s4, v50, 15
	v_readlane_b32 s0, v55, 13
	v_cvt_scalef32_pk_f16_fp4 v32, v28, 1.0
	v_cvt_scalef32_pk_f16_fp4 v33, v28, 1.0 op_sel:[1,0,0]
	v_cvt_scalef32_pk_f16_fp4 v34, v28, 1.0 op_sel:[0,1,0]
	v_cvt_scalef32_pk_f16_fp4 v35, v28, 1.0 op_sel:[1,1,0]
	v_cvt_scalef32_pk_f16_fp4 v36, v29, 1.0
	v_cvt_scalef32_pk_f16_fp4 v37, v29, 1.0 op_sel:[1,0,0]
	v_cvt_scalef32_pk_f16_fp4 v38, v29, 1.0 op_sel:[0,1,0]
	v_cvt_scalef32_pk_f16_fp4 v39, v29, 1.0 op_sel:[1,1,0]
	v_cvt_scalef32_pk_f16_fp4 v40, v30, 1.0
	v_cvt_scalef32_pk_f16_fp4 v41, v30, 1.0 op_sel:[1,0,0]
	v_cvt_scalef32_pk_f16_fp4 v42, v30, 1.0 op_sel:[0,1,0]
	v_cvt_scalef32_pk_f16_fp4 v43, v30, 1.0 op_sel:[1,1,0]
	v_cvt_scalef32_pk_f16_fp4 v44, v31, 1.0
	v_cvt_scalef32_pk_f16_fp4 v45, v31, 1.0 op_sel:[1,0,0]
	v_cvt_scalef32_pk_f16_fp4 v46, v31, 1.0 op_sel:[0,1,0]
	v_cvt_scalef32_pk_f16_fp4 v47, v31, 1.0 op_sel:[1,1,0]
	buffer_load_dwordx4 v[24:27], v115, s[12:15], s4 offen
	v_pk_fma_f16 v162, v32, s0, v162
	v_pk_fma_f16 v161, v33, s0, v161
	v_pk_fma_f16 v160, v34, s0, v160
	v_pk_fma_f16 v159, v35, s0, v159
	v_pk_fma_f16 v158, v36, s0, v158
	v_pk_fma_f16 v157, v37, s0, v157
	v_pk_fma_f16 v156, v38, s0, v156
	v_pk_fma_f16 v147, v39, s0, v147
	v_pk_fma_f16 v146, v40, s0, v146
	v_pk_fma_f16 v145, v41, s0, v145
	v_pk_fma_f16 v144, v42, s0, v144
	v_pk_fma_f16 v143, v43, s0, v143
	v_pk_fma_f16 v142, v44, s0, v142
	v_pk_fma_f16 v141, v45, s0, v141
	v_pk_fma_f16 v149, v46, s0, v149
	v_pk_fma_f16 v148, v47, s0, v148
	s_waitcnt vmcnt(6)
	v_readlane_b32 s4, v51, 15
	v_readlane_b32 s0, v52, 14
	v_cvt_scalef32_pk_f16_fp4 v32, v0, 1.0
	v_cvt_scalef32_pk_f16_fp4 v33, v0, 1.0 op_sel:[1,0,0]
	v_cvt_scalef32_pk_f16_fp4 v34, v0, 1.0 op_sel:[0,1,0]
	v_cvt_scalef32_pk_f16_fp4 v35, v0, 1.0 op_sel:[1,1,0]
	v_cvt_scalef32_pk_f16_fp4 v36, v1, 1.0
	v_cvt_scalef32_pk_f16_fp4 v37, v1, 1.0 op_sel:[1,0,0]
	v_cvt_scalef32_pk_f16_fp4 v38, v1, 1.0 op_sel:[0,1,0]
	v_cvt_scalef32_pk_f16_fp4 v39, v1, 1.0 op_sel:[1,1,0]
	v_cvt_scalef32_pk_f16_fp4 v40, v2, 1.0
	v_cvt_scalef32_pk_f16_fp4 v41, v2, 1.0 op_sel:[1,0,0]
	v_cvt_scalef32_pk_f16_fp4 v42, v2, 1.0 op_sel:[0,1,0]
	v_cvt_scalef32_pk_f16_fp4 v43, v2, 1.0 op_sel:[1,1,0]
	v_cvt_scalef32_pk_f16_fp4 v44, v3, 1.0
	v_cvt_scalef32_pk_f16_fp4 v45, v3, 1.0 op_sel:[1,0,0]
	v_cvt_scalef32_pk_f16_fp4 v46, v3, 1.0 op_sel:[0,1,0]
	v_cvt_scalef32_pk_f16_fp4 v47, v3, 1.0 op_sel:[1,1,0]
	buffer_load_dwordx4 v[28:31], v115, s[12:15], s4 offen
	v_pk_fma_f16 v139, v32, s0, v139
	v_pk_fma_f16 v138, v33, s0, v138
	v_pk_fma_f16 v136, v34, s0, v136
	v_pk_fma_f16 v135, v35, s0, v135
	v_pk_fma_f16 v134, v36, s0, v134
	v_pk_fma_f16 v133, v37, s0, v133
	v_pk_fma_f16 v132, v38, s0, v132
	v_pk_fma_f16 v131, v39, s0, v131
	v_pk_fma_f16 v130, v40, s0, v130
	v_pk_fma_f16 v129, v41, s0, v129
	v_pk_fma_f16 v128, v42, s0, v128
	v_pk_fma_f16 v127, v43, s0, v127
	v_pk_fma_f16 v126, v44, s0, v126
	v_pk_fma_f16 v114, v45, s0, v114
	v_pk_fma_f16 v140, v46, s0, v140
	v_pk_fma_f16 v137, v47, s0, v137
	s_waitcnt vmcnt(6)
	v_readlane_b32 s4, v48, 16
	v_readlane_b32 s0, v53, 14
	v_cvt_scalef32_pk_f16_fp4 v32, v4, 1.0
	v_cvt_scalef32_pk_f16_fp4 v33, v4, 1.0 op_sel:[1,0,0]
	v_cvt_scalef32_pk_f16_fp4 v34, v4, 1.0 op_sel:[0,1,0]
	v_cvt_scalef32_pk_f16_fp4 v35, v4, 1.0 op_sel:[1,1,0]
	v_cvt_scalef32_pk_f16_fp4 v36, v5, 1.0
	v_cvt_scalef32_pk_f16_fp4 v37, v5, 1.0 op_sel:[1,0,0]
	v_cvt_scalef32_pk_f16_fp4 v38, v5, 1.0 op_sel:[0,1,0]
	v_cvt_scalef32_pk_f16_fp4 v39, v5, 1.0 op_sel:[1,1,0]
	v_cvt_scalef32_pk_f16_fp4 v40, v6, 1.0
	v_cvt_scalef32_pk_f16_fp4 v41, v6, 1.0 op_sel:[1,0,0]
	v_cvt_scalef32_pk_f16_fp4 v42, v6, 1.0 op_sel:[0,1,0]
	v_cvt_scalef32_pk_f16_fp4 v43, v6, 1.0 op_sel:[1,1,0]
	v_cvt_scalef32_pk_f16_fp4 v44, v7, 1.0
	v_cvt_scalef32_pk_f16_fp4 v45, v7, 1.0 op_sel:[1,0,0]
	v_cvt_scalef32_pk_f16_fp4 v46, v7, 1.0 op_sel:[0,1,0]
	v_cvt_scalef32_pk_f16_fp4 v47, v7, 1.0 op_sel:[1,1,0]
	buffer_load_dwordx4 v[0:3], v115, s[12:15], s4 offen
	v_pk_fma_f16 v124, v32, s0, v124
	v_pk_fma_f16 v123, v33, s0, v123
	v_pk_fma_f16 v121, v34, s0, v121
	v_pk_fma_f16 v120, v35, s0, v120
	v_pk_fma_f16 v119, v36, s0, v119
	v_pk_fma_f16 v118, v37, s0, v118
	v_pk_fma_f16 v117, v38, s0, v117
	v_pk_fma_f16 v116, v39, s0, v116
	v_pk_fma_f16 v113, v40, s0, v113
	v_pk_fma_f16 v112, v41, s0, v112
	v_pk_fma_f16 v67, v42, s0, v67
	v_pk_fma_f16 v66, v43, s0, v66
	v_pk_fma_f16 v65, v44, s0, v65
	v_pk_fma_f16 v64, v45, s0, v64
	v_pk_fma_f16 v125, v46, s0, v125
	v_pk_fma_f16 v122, v47, s0, v122
	s_waitcnt vmcnt(6)
	v_readlane_b32 s4, v49, 16
	v_readlane_b32 s0, v54, 14
	v_cvt_scalef32_pk_f16_fp4 v32, v8, 1.0
	v_cvt_scalef32_pk_f16_fp4 v33, v8, 1.0 op_sel:[1,0,0]
	v_cvt_scalef32_pk_f16_fp4 v34, v8, 1.0 op_sel:[0,1,0]
	v_cvt_scalef32_pk_f16_fp4 v35, v8, 1.0 op_sel:[1,1,0]
	v_cvt_scalef32_pk_f16_fp4 v36, v9, 1.0
	v_cvt_scalef32_pk_f16_fp4 v37, v9, 1.0 op_sel:[1,0,0]
	v_cvt_scalef32_pk_f16_fp4 v38, v9, 1.0 op_sel:[0,1,0]
	v_cvt_scalef32_pk_f16_fp4 v39, v9, 1.0 op_sel:[1,1,0]
	v_cvt_scalef32_pk_f16_fp4 v40, v10, 1.0
	v_cvt_scalef32_pk_f16_fp4 v41, v10, 1.0 op_sel:[1,0,0]
	v_cvt_scalef32_pk_f16_fp4 v42, v10, 1.0 op_sel:[0,1,0]
	v_cvt_scalef32_pk_f16_fp4 v43, v10, 1.0 op_sel:[1,1,0]
	v_cvt_scalef32_pk_f16_fp4 v44, v11, 1.0
	v_cvt_scalef32_pk_f16_fp4 v45, v11, 1.0 op_sel:[1,0,0]
	v_cvt_scalef32_pk_f16_fp4 v46, v11, 1.0 op_sel:[0,1,0]
	v_cvt_scalef32_pk_f16_fp4 v47, v11, 1.0 op_sel:[1,1,0]
	buffer_load_dwordx4 v[4:7], v115, s[12:15], s4 offen
	v_pk_fma_f16 v74, v32, s0, v74
	v_pk_fma_f16 v73, v33, s0, v73
	v_pk_fma_f16 v71, v34, s0, v71
	v_pk_fma_f16 v70, v35, s0, v70
	v_pk_fma_f16 v69, v36, s0, v69
	v_pk_fma_f16 v68, v37, s0, v68
	v_pk_fma_f16 v63, v38, s0, v63
	v_pk_fma_f16 v62, v39, s0, v62
	v_pk_fma_f16 v61, v40, s0, v61
	v_pk_fma_f16 v60, v41, s0, v60
	v_pk_fma_f16 v59, v42, s0, v59
	v_pk_fma_f16 v58, v43, s0, v58
	v_pk_fma_f16 v57, v44, s0, v57
	v_pk_fma_f16 v56, v45, s0, v56
	v_pk_fma_f16 v75, v46, s0, v75
	v_pk_fma_f16 v72, v47, s0, v72
	s_waitcnt vmcnt(6)
	v_readlane_b32 s4, v50, 16
	v_readlane_b32 s0, v55, 14
	v_cvt_scalef32_pk_f16_fp4 v32, v12, 1.0
	v_cvt_scalef32_pk_f16_fp4 v33, v12, 1.0 op_sel:[1,0,0]
	v_cvt_scalef32_pk_f16_fp4 v34, v12, 1.0 op_sel:[0,1,0]
	v_cvt_scalef32_pk_f16_fp4 v35, v12, 1.0 op_sel:[1,1,0]
	v_cvt_scalef32_pk_f16_fp4 v36, v13, 1.0
	v_cvt_scalef32_pk_f16_fp4 v37, v13, 1.0 op_sel:[1,0,0]
	v_cvt_scalef32_pk_f16_fp4 v38, v13, 1.0 op_sel:[0,1,0]
	v_cvt_scalef32_pk_f16_fp4 v39, v13, 1.0 op_sel:[1,1,0]
	v_cvt_scalef32_pk_f16_fp4 v40, v14, 1.0
	v_cvt_scalef32_pk_f16_fp4 v41, v14, 1.0 op_sel:[1,0,0]
	v_cvt_scalef32_pk_f16_fp4 v42, v14, 1.0 op_sel:[0,1,0]
	v_cvt_scalef32_pk_f16_fp4 v43, v14, 1.0 op_sel:[1,1,0]
	v_cvt_scalef32_pk_f16_fp4 v44, v15, 1.0
	v_cvt_scalef32_pk_f16_fp4 v45, v15, 1.0 op_sel:[1,0,0]
	v_cvt_scalef32_pk_f16_fp4 v46, v15, 1.0 op_sel:[0,1,0]
	v_cvt_scalef32_pk_f16_fp4 v47, v15, 1.0 op_sel:[1,1,0]
	buffer_load_dwordx4 v[8:11], v115, s[12:15], s4 offen
	v_pk_fma_f16 v162, v32, s0, v162
	v_pk_fma_f16 v161, v33, s0, v161
	v_pk_fma_f16 v160, v34, s0, v160
	v_pk_fma_f16 v159, v35, s0, v159
	v_pk_fma_f16 v158, v36, s0, v158
	v_pk_fma_f16 v157, v37, s0, v157
	v_pk_fma_f16 v156, v38, s0, v156
	v_pk_fma_f16 v147, v39, s0, v147
	v_pk_fma_f16 v146, v40, s0, v146
	v_pk_fma_f16 v145, v41, s0, v145
	v_pk_fma_f16 v144, v42, s0, v144
	v_pk_fma_f16 v143, v43, s0, v143
	v_pk_fma_f16 v142, v44, s0, v142
	v_pk_fma_f16 v141, v45, s0, v141
	v_pk_fma_f16 v149, v46, s0, v149
	v_pk_fma_f16 v148, v47, s0, v148
	s_waitcnt vmcnt(6)
	v_readlane_b32 s4, v51, 16
	v_readlane_b32 s0, v52, 15
	v_cvt_scalef32_pk_f16_fp4 v32, v16, 1.0
	v_cvt_scalef32_pk_f16_fp4 v33, v16, 1.0 op_sel:[1,0,0]
	v_cvt_scalef32_pk_f16_fp4 v34, v16, 1.0 op_sel:[0,1,0]
	v_cvt_scalef32_pk_f16_fp4 v35, v16, 1.0 op_sel:[1,1,0]
	v_cvt_scalef32_pk_f16_fp4 v36, v17, 1.0
	v_cvt_scalef32_pk_f16_fp4 v37, v17, 1.0 op_sel:[1,0,0]
	v_cvt_scalef32_pk_f16_fp4 v38, v17, 1.0 op_sel:[0,1,0]
	v_cvt_scalef32_pk_f16_fp4 v39, v17, 1.0 op_sel:[1,1,0]
	v_cvt_scalef32_pk_f16_fp4 v40, v18, 1.0
	v_cvt_scalef32_pk_f16_fp4 v41, v18, 1.0 op_sel:[1,0,0]
	v_cvt_scalef32_pk_f16_fp4 v42, v18, 1.0 op_sel:[0,1,0]
	v_cvt_scalef32_pk_f16_fp4 v43, v18, 1.0 op_sel:[1,1,0]
	v_cvt_scalef32_pk_f16_fp4 v44, v19, 1.0
	v_cvt_scalef32_pk_f16_fp4 v45, v19, 1.0 op_sel:[1,0,0]
	v_cvt_scalef32_pk_f16_fp4 v46, v19, 1.0 op_sel:[0,1,0]
	v_cvt_scalef32_pk_f16_fp4 v47, v19, 1.0 op_sel:[1,1,0]
	buffer_load_dwordx4 v[12:15], v115, s[12:15], s4 offen
	v_pk_fma_f16 v139, v32, s0, v139
	v_pk_fma_f16 v138, v33, s0, v138
	v_pk_fma_f16 v136, v34, s0, v136
	v_pk_fma_f16 v135, v35, s0, v135
	v_pk_fma_f16 v134, v36, s0, v134
	v_pk_fma_f16 v133, v37, s0, v133
	v_pk_fma_f16 v132, v38, s0, v132
	v_pk_fma_f16 v131, v39, s0, v131
	v_pk_fma_f16 v130, v40, s0, v130
	v_pk_fma_f16 v129, v41, s0, v129
	v_pk_fma_f16 v128, v42, s0, v128
	v_pk_fma_f16 v127, v43, s0, v127
	v_pk_fma_f16 v126, v44, s0, v126
	v_pk_fma_f16 v114, v45, s0, v114
	v_pk_fma_f16 v140, v46, s0, v140
	v_pk_fma_f16 v137, v47, s0, v137
	s_waitcnt vmcnt(6)
	v_readlane_b32 s4, v48, 17
	v_readlane_b32 s0, v53, 15
	v_cvt_scalef32_pk_f16_fp4 v32, v20, 1.0
	v_cvt_scalef32_pk_f16_fp4 v33, v20, 1.0 op_sel:[1,0,0]
	v_cvt_scalef32_pk_f16_fp4 v34, v20, 1.0 op_sel:[0,1,0]
	v_cvt_scalef32_pk_f16_fp4 v35, v20, 1.0 op_sel:[1,1,0]
	v_cvt_scalef32_pk_f16_fp4 v36, v21, 1.0
	v_cvt_scalef32_pk_f16_fp4 v37, v21, 1.0 op_sel:[1,0,0]
	v_cvt_scalef32_pk_f16_fp4 v38, v21, 1.0 op_sel:[0,1,0]
	v_cvt_scalef32_pk_f16_fp4 v39, v21, 1.0 op_sel:[1,1,0]
	v_cvt_scalef32_pk_f16_fp4 v40, v22, 1.0
	v_cvt_scalef32_pk_f16_fp4 v41, v22, 1.0 op_sel:[1,0,0]
	v_cvt_scalef32_pk_f16_fp4 v42, v22, 1.0 op_sel:[0,1,0]
	v_cvt_scalef32_pk_f16_fp4 v43, v22, 1.0 op_sel:[1,1,0]
	v_cvt_scalef32_pk_f16_fp4 v44, v23, 1.0
	v_cvt_scalef32_pk_f16_fp4 v45, v23, 1.0 op_sel:[1,0,0]
	v_cvt_scalef32_pk_f16_fp4 v46, v23, 1.0 op_sel:[0,1,0]
	v_cvt_scalef32_pk_f16_fp4 v47, v23, 1.0 op_sel:[1,1,0]
	buffer_load_dwordx4 v[16:19], v115, s[12:15], s4 offen
	v_pk_fma_f16 v124, v32, s0, v124
	v_pk_fma_f16 v123, v33, s0, v123
	v_pk_fma_f16 v121, v34, s0, v121
	v_pk_fma_f16 v120, v35, s0, v120
	v_pk_fma_f16 v119, v36, s0, v119
	v_pk_fma_f16 v118, v37, s0, v118
	v_pk_fma_f16 v117, v38, s0, v117
	v_pk_fma_f16 v116, v39, s0, v116
	v_pk_fma_f16 v113, v40, s0, v113
	v_pk_fma_f16 v112, v41, s0, v112
	v_pk_fma_f16 v67, v42, s0, v67
	v_pk_fma_f16 v66, v43, s0, v66
	v_pk_fma_f16 v65, v44, s0, v65
	v_pk_fma_f16 v64, v45, s0, v64
	v_pk_fma_f16 v125, v46, s0, v125
	v_pk_fma_f16 v122, v47, s0, v122
	s_waitcnt vmcnt(6)
	v_readlane_b32 s4, v49, 17
	v_readlane_b32 s0, v54, 15
	v_cvt_scalef32_pk_f16_fp4 v32, v24, 1.0
	v_cvt_scalef32_pk_f16_fp4 v33, v24, 1.0 op_sel:[1,0,0]
	v_cvt_scalef32_pk_f16_fp4 v34, v24, 1.0 op_sel:[0,1,0]
	v_cvt_scalef32_pk_f16_fp4 v35, v24, 1.0 op_sel:[1,1,0]
	v_cvt_scalef32_pk_f16_fp4 v36, v25, 1.0
	v_cvt_scalef32_pk_f16_fp4 v37, v25, 1.0 op_sel:[1,0,0]
	v_cvt_scalef32_pk_f16_fp4 v38, v25, 1.0 op_sel:[0,1,0]
	v_cvt_scalef32_pk_f16_fp4 v39, v25, 1.0 op_sel:[1,1,0]
	v_cvt_scalef32_pk_f16_fp4 v40, v26, 1.0
	v_cvt_scalef32_pk_f16_fp4 v41, v26, 1.0 op_sel:[1,0,0]
	v_cvt_scalef32_pk_f16_fp4 v42, v26, 1.0 op_sel:[0,1,0]
	v_cvt_scalef32_pk_f16_fp4 v43, v26, 1.0 op_sel:[1,1,0]
	v_cvt_scalef32_pk_f16_fp4 v44, v27, 1.0
	v_cvt_scalef32_pk_f16_fp4 v45, v27, 1.0 op_sel:[1,0,0]
	v_cvt_scalef32_pk_f16_fp4 v46, v27, 1.0 op_sel:[0,1,0]
	v_cvt_scalef32_pk_f16_fp4 v47, v27, 1.0 op_sel:[1,1,0]
	buffer_load_dwordx4 v[20:23], v115, s[12:15], s4 offen
	v_pk_fma_f16 v74, v32, s0, v74
	v_pk_fma_f16 v73, v33, s0, v73
	v_pk_fma_f16 v71, v34, s0, v71
	v_pk_fma_f16 v70, v35, s0, v70
	v_pk_fma_f16 v69, v36, s0, v69
	v_pk_fma_f16 v68, v37, s0, v68
	v_pk_fma_f16 v63, v38, s0, v63
	v_pk_fma_f16 v62, v39, s0, v62
	v_pk_fma_f16 v61, v40, s0, v61
	v_pk_fma_f16 v60, v41, s0, v60
	v_pk_fma_f16 v59, v42, s0, v59
	v_pk_fma_f16 v58, v43, s0, v58
	v_pk_fma_f16 v57, v44, s0, v57
	v_pk_fma_f16 v56, v45, s0, v56
	v_pk_fma_f16 v75, v46, s0, v75
	v_pk_fma_f16 v72, v47, s0, v72
	s_waitcnt vmcnt(6)
	v_readlane_b32 s4, v50, 17
	v_readlane_b32 s0, v55, 15
	v_cvt_scalef32_pk_f16_fp4 v32, v28, 1.0
	v_cvt_scalef32_pk_f16_fp4 v33, v28, 1.0 op_sel:[1,0,0]
	v_cvt_scalef32_pk_f16_fp4 v34, v28, 1.0 op_sel:[0,1,0]
	v_cvt_scalef32_pk_f16_fp4 v35, v28, 1.0 op_sel:[1,1,0]
	v_cvt_scalef32_pk_f16_fp4 v36, v29, 1.0
	v_cvt_scalef32_pk_f16_fp4 v37, v29, 1.0 op_sel:[1,0,0]
	v_cvt_scalef32_pk_f16_fp4 v38, v29, 1.0 op_sel:[0,1,0]
	v_cvt_scalef32_pk_f16_fp4 v39, v29, 1.0 op_sel:[1,1,0]
	v_cvt_scalef32_pk_f16_fp4 v40, v30, 1.0
	v_cvt_scalef32_pk_f16_fp4 v41, v30, 1.0 op_sel:[1,0,0]
	v_cvt_scalef32_pk_f16_fp4 v42, v30, 1.0 op_sel:[0,1,0]
	v_cvt_scalef32_pk_f16_fp4 v43, v30, 1.0 op_sel:[1,1,0]
	v_cvt_scalef32_pk_f16_fp4 v44, v31, 1.0
	v_cvt_scalef32_pk_f16_fp4 v45, v31, 1.0 op_sel:[1,0,0]
	v_cvt_scalef32_pk_f16_fp4 v46, v31, 1.0 op_sel:[0,1,0]
	v_cvt_scalef32_pk_f16_fp4 v47, v31, 1.0 op_sel:[1,1,0]
	buffer_load_dwordx4 v[24:27], v115, s[12:15], s4 offen
	v_pk_fma_f16 v162, v32, s0, v162
	v_pk_fma_f16 v161, v33, s0, v161
	v_pk_fma_f16 v160, v34, s0, v160
	v_pk_fma_f16 v159, v35, s0, v159
	v_pk_fma_f16 v158, v36, s0, v158
	v_pk_fma_f16 v157, v37, s0, v157
	v_pk_fma_f16 v156, v38, s0, v156
	v_pk_fma_f16 v147, v39, s0, v147
	v_pk_fma_f16 v146, v40, s0, v146
	v_pk_fma_f16 v145, v41, s0, v145
	v_pk_fma_f16 v144, v42, s0, v144
	v_pk_fma_f16 v143, v43, s0, v143
	v_pk_fma_f16 v142, v44, s0, v142
	v_pk_fma_f16 v141, v45, s0, v141
	v_pk_fma_f16 v149, v46, s0, v149
	v_pk_fma_f16 v148, v47, s0, v148
	v_add_u32_e32 v111, 64, v111
	s_add_i32 s11, s11, 1
	s_cmp_eq_u32 s11, 8
	s_cbranch_scc0 .Lmy_lblk
	s_waitcnt vmcnt(0) lgkmcnt(0)
	s_movk_i32 s12, 0x1000
	v_lshlrev_b32_e32 v236, 6, v78
	v_add_u32_e32 v237, 0x1000, v236
	global_load_dwordx4 v[172:175], v236, s[16:17] offset:0
	global_load_dwordx4 v[204:207], v236, s[18:19] offset:0
	global_load_dwordx4 v[176:179], v236, s[16:17] offset:16
	global_load_dwordx4 v[208:211], v236, s[18:19] offset:16
	global_load_dwordx4 v[180:183], v236, s[16:17] offset:32
	global_load_dwordx4 v[212:215], v236, s[18:19] offset:32
	global_load_dwordx4 v[184:187], v236, s[16:17] offset:48
	global_load_dwordx4 v[216:219], v236, s[18:19] offset:48
	global_load_dwordx4 v[188:191], v237, s[16:17] offset:0
	global_load_dwordx4 v[220:223], v237, s[18:19] offset:0
	global_load_dwordx4 v[192:195], v237, s[16:17] offset:16
	global_load_dwordx4 v[224:227], v237, s[18:19] offset:16
	global_load_dwordx4 v[196:199], v237, s[16:17] offset:32
	global_load_dwordx4 v[228:231], v237, s[18:19] offset:32
	global_load_dwordx4 v[200:203], v237, s[16:17] offset:48
	global_load_dwordx4 v[232:235], v237, s[18:19] offset:48
	s_lshl_b32 s0, s10, 2
	v_mov_b32_e32 v0, v78
	s_or_b32 s10, s0, s22
	s_ashr_i32 s11, s10, 31
	v_lshlrev_b32_e32 v42, 4, v0
	v_ashrrev_i32_e32 v43, 31, v42
	s_lshl_b64 s[0:1], s[10:11], 11
	v_lshl_add_u64 v[0:1], s[0:1], 0, v[42:43]
	v_lshlrev_b64 v[0:1], 1, v[0:1]
	v_lshl_add_u64 v[28:29], s[70:71], 0, v[0:1]
	global_load_dwordx4 v[4:7], v[28:29], off offset:2064
	v_lshl_add_u64 v[24:25], s[2:3], 0, v[0:1]
	global_load_dwordx4 v[0:3], v[24:25], off offset:2064
	global_load_dwordx4 v[8:11], v[28:29], off
	global_load_dwordx4 v[12:15], v[24:25], off
	global_load_dwordx4 v[16:19], v[28:29], off offset:16
	global_load_dwordx4 v[20:23], v[24:25], off offset:16
	s_nop 0
	global_load_dwordx4 v[24:27], v[24:25], off offset:2048
	s_nop 0
	global_load_dwordx4 v[28:31], v[28:29], off offset:2048
	v_cvt_f32_f16_sdwa v35, v139 dst_sel:DWORD dst_unused:UNUSED_PAD src0_sel:WORD_1
	v_cvt_f32_f16_e32 v34, v139
	v_cvt_f32_f16_sdwa v41, v136 dst_sel:DWORD dst_unused:UNUSED_PAD src0_sel:WORD_1
	v_cvt_f32_f16_e32 v40, v136
	v_cvt_f32_f16_sdwa v37, v138 dst_sel:DWORD dst_unused:UNUSED_PAD src0_sel:WORD_1
	v_cvt_f32_f16_e32 v36, v138
	s_waitcnt vmcnt(9)
	v_cvt_f32_f16_sdwa v45, v135 dst_sel:DWORD dst_unused:UNUSED_PAD src0_sel:WORD_1
	v_cvt_f32_f16_e32 v44, v135
	v_cvt_f32_f16_sdwa v47, v134 dst_sel:DWORD dst_unused:UNUSED_PAD src0_sel:WORD_1
	v_cvt_f32_f16_e32 v46, v134
	v_cvt_f32_f16_sdwa v49, v133 dst_sel:DWORD dst_unused:UNUSED_PAD src0_sel:WORD_1
	v_cvt_f32_f16_e32 v48, v133
	v_cvt_f32_f16_sdwa v51, v132 dst_sel:DWORD dst_unused:UNUSED_PAD src0_sel:WORD_1
	v_cvt_f32_f16_e32 v50, v132
	v_cvt_f32_f16_sdwa v39, v137 dst_sel:DWORD dst_unused:UNUSED_PAD src0_sel:WORD_1
	v_cvt_f32_f16_e32 v38, v137
	v_cvt_f32_f16_sdwa v33, v140 dst_sel:DWORD dst_unused:UNUSED_PAD src0_sel:WORD_1
	v_cvt_f32_f16_e32 v32, v140
	s_lshl_b64 s[14:15], s[10:11], 13
	s_waitcnt vmcnt(6)
	v_and_b32_e32 v55, 0xffff0000, v2
	v_lshlrev_b32_e32 v54, 16, v2
	v_and_b32_e32 v53, 0xffff0000, v6
	v_lshlrev_b32_e32 v52, 16, v6
	s_waitcnt vmcnt(5)
	v_lshlrev_b32_e32 v104, 16, v8
	v_and_b32_e32 v105, 0xffff0000, v8
	s_waitcnt vmcnt(4)
	v_lshlrev_b32_e32 v106, 16, v12
	v_and_b32_e32 v107, 0xffff0000, v12
	v_and_b32_e32 v109, 0xffff0000, v7
	v_lshlrev_b32_e32 v108, 16, v7
	v_and_b32_e32 v7, 0xffff0000, v3
	v_lshlrev_b32_e32 v6, 16, v3
	v_lshlrev_b32_e32 v2, 16, v10
	v_and_b32_e32 v3, 0xffff0000, v10
	v_lshlrev_b32_e32 v110, 16, v14
	v_and_b32_e32 v111, 0xffff0000, v14
	v_lshlrev_b32_e32 v10, 16, v11
	v_and_b32_e32 v11, 0xffff0000, v11
	v_lshlrev_b32_e32 v14, 16, v15
	v_and_b32_e32 v15, 0xffff0000, v15
	s_waitcnt vmcnt(3)
	v_lshlrev_b32_e32 v132, 16, v16
	v_and_b32_e32 v133, 0xffff0000, v16
	s_waitcnt vmcnt(2)
	v_lshlrev_b32_e32 v134, 16, v20
	v_and_b32_e32 v135, 0xffff0000, v20
	v_lshlrev_b32_e32 v16, 16, v17
	v_and_b32_e32 v17, 0xffff0000, v17
	v_lshlrev_b32_e32 v20, 16, v21
	v_and_b32_e32 v21, 0xffff0000, v21
	v_pk_fma_f32 v[52:53], v[52:53], s[6:7], v[54:55] op_sel_hi:[1,0,1]
	v_pk_fma_f32 v[54:55], v[104:105], s[6:7], v[106:107] op_sel_hi:[1,0,1]
	v_lshlrev_b32_e32 v8, 16, v9
	v_and_b32_e32 v9, 0xffff0000, v9
	v_lshlrev_b32_e32 v12, 16, v13
	v_and_b32_e32 v13, 0xffff0000, v13
	v_pk_fma_f32 v[2:3], v[2:3], s[6:7], v[110:111] op_sel_hi:[1,0,1]
	v_pk_fma_f32 v[10:11], v[10:11], s[6:7], v[14:15] op_sel_hi:[1,0,1]
	v_pk_fma_f32 v[14:15], v[16:17], s[6:7], v[20:21] op_sel_hi:[1,0,1]
	v_pk_add_f32 v[20:21], v[54:55], v[34:35]
	v_pk_fma_f32 v[8:9], v[8:9], s[6:7], v[12:13] op_sel_hi:[1,0,1]
	v_pk_add_f32 v[40:41], v[2:3], v[40:41]
	v_add_f32_e32 v2, 0, v20
	v_pk_add_f32 v[8:9], v[8:9], v[36:37]
	v_add_f32_e32 v2, v21, v2
	v_add_f32_e32 v2, v8, v2
	v_add_f32_e32 v2, v9, v2
	v_add_f32_e32 v2, v40, v2
	v_pk_add_f32 v[10:11], v[10:11], v[44:45]
	v_add_f32_e32 v2, v41, v2
	v_pk_fma_f32 v[12:13], v[132:133], s[6:7], v[134:135] op_sel_hi:[1,0,1]
	v_add_f32_e32 v2, v10, v2
	v_pk_add_f32 v[12:13], v[12:13], v[46:47]
	v_add_f32_e32 v2, v11, v2
	v_add_f32_e32 v2, v12, v2
	v_pk_add_f32 v[14:15], v[14:15], v[48:49]
	v_add_f32_e32 v2, v13, v2
	v_lshlrev_b32_e32 v136, 16, v18
	v_and_b32_e32 v137, 0xffff0000, v18
	v_lshlrev_b32_e32 v138, 16, v22
	v_pk_fma_f32 v[6:7], v[108:109], s[6:7], v[6:7] op_sel_hi:[1,0,1]
	v_add_f32_e32 v2, v14, v2
	v_and_b32_e32 v139, 0xffff0000, v22
	v_pk_add_f32 v[38:39], v[6:7], v[38:39]
	v_add_f32_e32 v6, v15, v2
	v_pk_fma_f32 v[2:3], v[136:137], s[6:7], v[138:139] op_sel_hi:[1,0,1]
	v_and_b32_e32 v7, 0xffff0000, v19
	v_pk_add_f32 v[44:45], v[2:3], v[50:51]
	v_cvt_f32_f16_sdwa v3, v131 dst_sel:DWORD dst_unused:UNUSED_PAD src0_sel:WORD_1
	v_add_f32_e32 v2, v44, v6
	v_add_f32_e32 v22, v45, v2
	v_cvt_f32_f16_e32 v2, v131
	v_lshlrev_b32_e32 v6, 16, v19
	v_lshlrev_b32_e32 v18, 16, v23
	v_and_b32_e32 v19, 0xffff0000, v23
	v_pk_fma_f32 v[6:7], v[6:7], s[6:7], v[18:19] op_sel_hi:[1,0,1]
	v_pk_add_f32 v[16:17], v[52:53], v[32:33]
	v_pk_add_f32 v[18:19], v[6:7], v[2:3]
	v_cvt_f32_f16_sdwa v3, v130 dst_sel:DWORD dst_unused:UNUSED_PAD src0_sel:WORD_1
	v_add_f32_e32 v2, v18, v22
	v_add_f32_e32 v32, v19, v2
	v_cvt_f32_f16_e32 v2, v130
	s_waitcnt vmcnt(0)
	v_lshlrev_b32_e32 v6, 16, v28
	v_and_b32_e32 v7, 0xffff0000, v28
	v_lshlrev_b32_e32 v22, 16, v24
	v_and_b32_e32 v23, 0xffff0000, v24
	v_pk_fma_f32 v[6:7], v[6:7], s[6:7], v[22:23] op_sel_hi:[1,0,1]
	v_lshlrev_b32_e32 v24, 16, v25
	v_pk_add_f32 v[22:23], v[6:7], v[2:3]
	v_cvt_f32_f16_sdwa v3, v129 dst_sel:DWORD dst_unused:UNUSED_PAD src0_sel:WORD_1
	v_add_f32_e32 v2, v22, v32
	v_add_f32_e32 v28, v23, v2
	v_cvt_f32_f16_e32 v2, v129
	v_lshlrev_b32_e32 v6, 16, v29
	v_and_b32_e32 v7, 0xffff0000, v29
	v_and_b32_e32 v25, 0xffff0000, v25
	v_pk_fma_f32 v[6:7], v[6:7], s[6:7], v[24:25] op_sel_hi:[1,0,1]
	v_and_b32_e32 v29, 0xffff0000, v26
	v_pk_add_f32 v[24:25], v[6:7], v[2:3]
	v_cvt_f32_f16_sdwa v3, v128 dst_sel:DWORD dst_unused:UNUSED_PAD src0_sel:WORD_1
	v_add_f32_e32 v2, v24, v28
	v_add_f32_e32 v32, v25, v2
	v_cvt_f32_f16_e32 v2, v128
	v_lshlrev_b32_e32 v6, 16, v30
	v_and_b32_e32 v7, 0xffff0000, v30
	v_lshlrev_b32_e32 v28, 16, v26
	v_pk_fma_f32 v[6:7], v[6:7], s[6:7], v[28:29] op_sel_hi:[1,0,1]
	v_lshlrev_b32_e32 v26, 16, v27
	v_pk_add_f32 v[28:29], v[6:7], v[2:3]
	v_cvt_f32_f16_sdwa v3, v127 dst_sel:DWORD dst_unused:UNUSED_PAD src0_sel:WORD_1
	v_add_f32_e32 v2, v28, v32
	v_add_f32_e32 v30, v29, v2
	v_cvt_f32_f16_e32 v2, v127
	v_lshlrev_b32_e32 v6, 16, v31
	v_and_b32_e32 v7, 0xffff0000, v31
	v_and_b32_e32 v27, 0xffff0000, v27
	v_pk_fma_f32 v[6:7], v[6:7], s[6:7], v[26:27] op_sel_hi:[1,0,1]
	v_and_b32_e32 v31, 0xffff0000, v0
	v_pk_add_f32 v[26:27], v[6:7], v[2:3]
	v_cvt_f32_f16_sdwa v3, v126 dst_sel:DWORD dst_unused:UNUSED_PAD src0_sel:WORD_1
	v_add_f32_e32 v2, v26, v30
	v_add_f32_e32 v32, v27, v2
	v_cvt_f32_f16_e32 v2, v126
	v_lshlrev_b32_e32 v6, 16, v4
	v_and_b32_e32 v7, 0xffff0000, v4
	v_lshlrev_b32_e32 v30, 16, v0
	v_pk_fma_f32 v[6:7], v[6:7], s[6:7], v[30:31] op_sel_hi:[1,0,1]
	v_lshlrev_b32_e32 v4, 16, v5
	v_pk_add_f32 v[30:31], v[6:7], v[2:3]
	v_cvt_f32_f16_sdwa v3, v114 dst_sel:DWORD dst_unused:UNUSED_PAD src0_sel:WORD_1
	v_cvt_f32_f16_e32 v2, v114
	v_add_f32_e32 v0, v30, v32
	v_add_f32_e32 v6, v31, v0
	v_and_b32_e32 v5, 0xffff0000, v5
	v_lshlrev_b32_e32 v0, 16, v1
	v_and_b32_e32 v1, 0xffff0000, v1
	v_pk_fma_f32 v[0:1], v[4:5], s[6:7], v[0:1] op_sel_hi:[1,0,1]
	v_lshlrev_b64 v[36:37], 2, v[42:43]
	v_pk_add_f32 v[46:47], v[0:1], v[2:3]
	v_lshl_add_u64 v[32:33], s[16:17], 0, v[36:37]
	v_add_f32_e32 v0, v46, v6
	v_add_f32_e32 v0, v47, v0
	v_add_f32_e32 v0, v16, v0
	v_add_f32_e32 v0, v17, v0
	v_add_f32_e32 v0, v38, v0
	v_add_f32_e32 v0, v39, v0
	s_nop 1
	v_mov_b32_dpp v1, v0 quad_perm:[1,0,3,2] row_mask:0xf bank_mask:0xf
	v_lshl_add_u64 v[34:35], s[18:19], 0, v[36:37]
	s_waitcnt lgkmcnt(0)
	v_add_f32_e32 v0, v0, v1
	s_nop 1
	v_mov_b32_dpp v1, v0 quad_perm:[2,3,0,1] row_mask:0xf bank_mask:0xf
	s_waitcnt lgkmcnt(0)
	v_add_f32_e32 v0, v0, v1
	s_nop 1
	v_mov_b32_dpp v1, v0 row_half_mirror row_mask:0xf bank_mask:0xf
	s_waitcnt lgkmcnt(0)
	v_add_f32_e32 v0, v0, v1
	s_nop 1
	v_mov_b32_dpp v1, v0 row_mirror row_mask:0xf bank_mask:0xf
	s_waitcnt lgkmcnt(0)
	v_add_f32_e32 v0, v0, v1
	v_mov_b32_e32 v1, v0
	v_mov_b32_e32 v244, v0
	s_nop 1
	v_permlane16_swap_b32 v1, v244
	s_nop 1
	s_waitcnt lgkmcnt(0)
	v_add_f32_e32 v48, v1, v244
	v_mov_b32_e32 v49, v48
	v_mov_b32_e32 v244, v48
	s_nop 1
	v_permlane32_swap_b32 v49, v244
	s_nop 1
	s_waitcnt lgkmcnt(0)
	v_add_f32_e32 v48, v49, v244
	v_mul_f32_e32 v48, 0x3a000000, v48
	v_pk_add_f32 v[20:21], v[20:21], v[48:49] op_sel_hi:[1,0] neg_lo:[0,1] neg_hi:[0,1]
	v_pk_add_f32 v[8:9], v[8:9], v[48:49] op_sel_hi:[1,0] neg_lo:[0,1] neg_hi:[0,1]
	v_pk_mul_f32 v[50:51], v[20:21], v[20:21]
	v_pk_mul_f32 v[52:53], v[8:9], v[8:9]
	v_add_f32_e32 v50, v50, v51
	v_pk_add_f32 v[40:41], v[40:41], v[48:49] op_sel_hi:[1,0] neg_lo:[0,1] neg_hi:[0,1]
	v_add_f32_e32 v50, v52, v50
	v_pk_mul_f32 v[54:55], v[40:41], v[40:41]
	v_add_f32_e32 v50, v53, v50
	v_pk_add_f32 v[10:11], v[10:11], v[48:49] op_sel_hi:[1,0] neg_lo:[0,1] neg_hi:[0,1]
	v_add_f32_e32 v50, v54, v50
	v_pk_mul_f32 v[104:105], v[10:11], v[10:11]
	v_add_f32_e32 v50, v55, v50
	v_pk_add_f32 v[12:13], v[12:13], v[48:49] op_sel_hi:[1,0] neg_lo:[0,1] neg_hi:[0,1]
	v_add_f32_e32 v50, v104, v50
	v_pk_mul_f32 v[106:107], v[12:13], v[12:13]
	v_add_f32_e32 v50, v105, v50
	v_pk_add_f32 v[14:15], v[14:15], v[48:49] op_sel_hi:[1,0] neg_lo:[0,1] neg_hi:[0,1]
	v_add_f32_e32 v50, v106, v50
	v_pk_mul_f32 v[108:109], v[14:15], v[14:15]
	v_add_f32_e32 v50, v107, v50
	v_pk_add_f32 v[44:45], v[44:45], v[48:49] op_sel_hi:[1,0] neg_lo:[0,1] neg_hi:[0,1]
	v_add_f32_e32 v50, v108, v50
	v_pk_mul_f32 v[110:111], v[44:45], v[44:45]
	v_add_f32_e32 v50, v109, v50
	v_pk_add_f32 v[18:19], v[18:19], v[48:49] op_sel_hi:[1,0] neg_lo:[0,1] neg_hi:[0,1]
	v_add_f32_e32 v50, v110, v50
	v_pk_mul_f32 v[114:115], v[18:19], v[18:19]
	v_add_f32_e32 v50, v111, v50
	v_pk_add_f32 v[22:23], v[22:23], v[48:49] op_sel_hi:[1,0] neg_lo:[0,1] neg_hi:[0,1]
	v_add_f32_e32 v50, v114, v50
	v_pk_mul_f32 v[126:127], v[22:23], v[22:23]
	v_add_f32_e32 v50, v115, v50
	v_pk_add_f32 v[24:25], v[24:25], v[48:49] op_sel_hi:[1,0] neg_lo:[0,1] neg_hi:[0,1]
	v_add_f32_e32 v50, v126, v50
	v_pk_mul_f32 v[128:129], v[24:25], v[24:25]
	v_add_f32_e32 v50, v127, v50
	v_pk_add_f32 v[28:29], v[28:29], v[48:49] op_sel_hi:[1,0] neg_lo:[0,1] neg_hi:[0,1]
	v_add_f32_e32 v50, v128, v50
	v_pk_mul_f32 v[130:131], v[28:29], v[28:29]
	v_add_f32_e32 v50, v129, v50
	v_pk_add_f32 v[26:27], v[26:27], v[48:49] op_sel_hi:[1,0] neg_lo:[0,1] neg_hi:[0,1]
	v_add_f32_e32 v50, v130, v50
	v_pk_mul_f32 v[132:133], v[26:27], v[26:27]
	v_add_f32_e32 v50, v131, v50
	v_pk_add_f32 v[30:31], v[30:31], v[48:49] op_sel_hi:[1,0] neg_lo:[0,1] neg_hi:[0,1]
	v_add_f32_e32 v50, v132, v50
	v_pk_mul_f32 v[134:135], v[30:31], v[30:31]
	v_add_f32_e32 v50, v133, v50
	v_pk_add_f32 v[46:47], v[46:47], v[48:49] op_sel_hi:[1,0] neg_lo:[0,1] neg_hi:[0,1]
	v_add_f32_e32 v50, v134, v50
	v_pk_mul_f32 v[136:137], v[46:47], v[46:47]
	v_add_f32_e32 v50, v135, v50
	v_pk_add_f32 v[16:17], v[16:17], v[48:49] op_sel_hi:[1,0] neg_lo:[0,1] neg_hi:[0,1]
	v_add_f32_e32 v50, v136, v50
	v_pk_add_f32 v[138:139], v[38:39], v[48:49] op_sel_hi:[1,0] neg_lo:[0,1] neg_hi:[0,1]
	v_pk_mul_f32 v[48:49], v[16:17], v[16:17]
	v_add_f32_e32 v50, v137, v50
	v_add_f32_e32 v48, v48, v50
	v_pk_mul_f32 v[38:39], v[138:139], v[138:139]
	v_add_f32_e32 v48, v49, v48
	v_add_f32_e32 v38, v38, v48
	v_add_f32_e32 v38, v39, v38
	s_nop 1
	v_mov_b32_dpp v39, v38 quad_perm:[1,0,3,2] row_mask:0xf bank_mask:0xf
	v_cvt_f32_f16_sdwa v105, v119 dst_sel:DWORD dst_unused:UNUSED_PAD src0_sel:WORD_1
	v_cvt_f32_f16_e32 v104, v119
	v_cvt_f32_f16_sdwa v107, v118 dst_sel:DWORD dst_unused:UNUSED_PAD src0_sel:WORD_1
	v_cvt_f32_f16_e32 v106, v118
	s_waitcnt lgkmcnt(0)
	v_add_f32_e32 v38, v38, v39
	s_nop 1
	v_mov_b32_dpp v39, v38 quad_perm:[2,3,0,1] row_mask:0xf bank_mask:0xf
	v_cvt_f32_f16_sdwa v119, v65 dst_sel:DWORD dst_unused:UNUSED_PAD src0_sel:WORD_1
	v_cvt_f32_f16_e32 v118, v65
	v_cvt_f32_f16_sdwa v65, v64 dst_sel:DWORD dst_unused:UNUSED_PAD src0_sel:WORD_1
	v_cvt_f32_f16_e32 v64, v64
	s_waitcnt lgkmcnt(0)
	v_add_f32_e32 v38, v38, v39
	s_nop 1
	v_mov_b32_dpp v39, v38 row_half_mirror row_mask:0xf bank_mask:0xf
	v_cvt_f32_f16_sdwa v55, v120 dst_sel:DWORD dst_unused:UNUSED_PAD src0_sel:WORD_1
	v_cvt_f32_f16_e32 v54, v120
	v_cvt_f32_f16_sdwa v109, v117 dst_sel:DWORD dst_unused:UNUSED_PAD src0_sel:WORD_1
	v_cvt_f32_f16_e32 v108, v117
	s_waitcnt lgkmcnt(0)
	v_add_f32_e32 v38, v38, v39
	s_nop 1
	v_mov_b32_dpp v39, v38 row_mirror row_mask:0xf bank_mask:0xf
	v_cvt_f32_f16_sdwa v111, v116 dst_sel:DWORD dst_unused:UNUSED_PAD src0_sel:WORD_1
	v_cvt_f32_f16_e32 v110, v116
	v_cvt_f32_f16_sdwa v115, v113 dst_sel:DWORD dst_unused:UNUSED_PAD src0_sel:WORD_1
	v_cvt_f32_f16_e32 v114, v113
	s_waitcnt lgkmcnt(0)
	v_add_f32_e32 v38, v38, v39
	v_mov_b32_e32 v39, v38
	v_mov_b32_e32 v244, v38
	s_nop 1
	v_permlane16_swap_b32 v39, v244
	s_nop 1
	v_cvt_f32_f16_sdwa v113, v112 dst_sel:DWORD dst_unused:UNUSED_PAD src0_sel:WORD_1
	v_cvt_f32_f16_e32 v112, v112
	v_cvt_f32_f16_sdwa v117, v67 dst_sel:DWORD dst_unused:UNUSED_PAD src0_sel:WORD_1
	v_cvt_f32_f16_e32 v116, v67
	s_waitcnt lgkmcnt(0)
	v_add_f32_e32 v38, v39, v244
	v_mov_b32_e32 v39, v38
	v_mov_b32_e32 v244, v38
	s_nop 1
	v_permlane32_swap_b32 v39, v244
	s_nop 1
	v_cvt_f32_f16_sdwa v67, v66 dst_sel:DWORD dst_unused:UNUSED_PAD src0_sel:WORD_1
	v_cvt_f32_f16_e32 v66, v66
	s_waitcnt lgkmcnt(0)
	v_add_f32_e32 v38, v39, v244
	v_fmamk_f32 v38, v38, 0x3a000000, v101
	v_mul_f32_e32 v39, 0x4f800000, v38
	v_cmp_gt_f32_e32 vcc, s7, v38
	s_nop 1
	v_cndmask_b32_e32 v38, v38, v39, vcc
	v_sqrt_f32_e32 v39, v38
	s_nop 0
	v_add_u32_e32 v48, -1, v39
	v_fma_f32 v49, -v48, v39, v38
	v_cmp_ge_f32_e64 s[0:1], 0, v49
	v_add_u32_e32 v49, 1, v39
	s_nop 0
	v_cndmask_b32_e64 v48, v39, v48, s[0:1]
	v_fma_f32 v39, -v49, v39, v38
	v_cmp_lt_f32_e64 s[0:1], 0, v39
	s_nop 1
	v_cndmask_b32_e64 v39, v48, v49, s[0:1]
	v_mul_f32_e32 v48, 0x37800000, v39
	v_cndmask_b32_e32 v39, v39, v48, vcc
	v_cmp_class_f32_e32 vcc, v38, v102
	s_nop 1
	v_cndmask_b32_e32 v38, v39, v38, vcc
	v_div_scale_f32 v39, s[0:1], v38, v38, 1.0
	v_rcp_f32_e32 v50, v39
	s_add_u32 s0, s20, s14
	s_addc_u32 s1, s21, s15
	v_lshl_add_u64 v[48:49], s[0:1], 0, v[36:37]
	v_fma_f32 v51, -v39, v50, 1.0
	v_fmac_f32_e32 v50, v51, v50
	v_div_scale_f32 v51, vcc, 1.0, v38, 1.0
	v_mul_f32_e32 v52, v51, v50
	v_fma_f32 v53, -v39, v52, v51
	v_fmac_f32_e32 v52, v53, v50
	v_fma_f32 v39, -v39, v52, v51
	v_div_fmas_f32 v39, v39, v50, v52
	v_div_fixup_f32 v50, v39, v38, 1.0
	v_pk_mul_f32 v[20:21], v[20:21], v[50:51] op_sel_hi:[1,0]
	v_pk_mul_f32 v[8:9], v[8:9], v[50:51] op_sel_hi:[1,0]
	v_pk_fma_f32 v[0:1], v[172:173], v[20:21], v[204:205]
	v_pk_fma_f32 v[2:3], v[174:175], v[8:9], v[206:207]
	global_store_dwordx4 v[48:49], v[0:3], off
	s_nop 1
	s_nop 0
	v_pk_mul_f32 v[8:9], v[10:11], v[50:51] op_sel_hi:[1,0]
	v_pk_mul_f32 v[10:11], v[40:41], v[50:51] op_sel_hi:[1,0]
	v_add_co_u32_e32 v38, vcc, s12, v32
	s_or_b32 s0, s10, 1
	s_nop 0
	v_addc_co_u32_e32 v39, vcc, 0, v33, vcc
	v_add_co_u32_e32 v40, vcc, s12, v34
	s_ashr_i32 s1, s0, 31
	s_nop 0
	v_addc_co_u32_e32 v41, vcc, 0, v35, vcc
	s_lshl_b64 s[14:15], s[0:1], 11
	v_cvt_f32_f16_sdwa v53, v121 dst_sel:DWORD dst_unused:UNUSED_PAD src0_sel:WORD_1
	v_cvt_f32_f16_e32 v52, v121
	s_lshl_b64 s[0:1], s[0:1], 13
	v_pk_fma_f32 v[0:1], v[176:177], v[10:11], v[208:209]
	v_pk_fma_f32 v[2:3], v[178:179], v[8:9], v[210:211]
	global_store_dwordx4 v[48:49], v[0:3], off offset:16
	s_nop 1
	s_nop 0
	v_pk_mul_f32 v[8:9], v[14:15], v[50:51] op_sel_hi:[1,0]
	v_pk_mul_f32 v[10:11], v[12:13], v[50:51] op_sel_hi:[1,0]
	v_pk_mul_f32 v[12:13], v[22:23], v[50:51] op_sel_hi:[1,0]
	v_pk_mul_f32 v[14:15], v[16:17], v[50:51] op_sel_hi:[1,0]
	v_pk_fma_f32 v[0:1], v[180:181], v[10:11], v[212:213]
	v_pk_fma_f32 v[2:3], v[182:183], v[8:9], v[214:215]
	global_store_dwordx4 v[48:49], v[0:3], off offset:32
	s_nop 1
	s_nop 0
	v_pk_mul_f32 v[8:9], v[18:19], v[50:51] op_sel_hi:[1,0]
	v_pk_mul_f32 v[10:11], v[44:45], v[50:51] op_sel_hi:[1,0]
	v_pk_fma_f32 v[2:3], v[186:187], v[8:9], v[218:219]
	v_pk_fma_f32 v[0:1], v[184:185], v[10:11], v[216:217]
	global_store_dwordx4 v[48:49], v[0:3], off offset:48
	s_nop 1
	s_nop 0
	v_add_co_u32_e32 v8, vcc, s12, v48
	v_pk_mul_f32 v[10:11], v[24:25], v[50:51] op_sel_hi:[1,0]
	s_nop 0
	v_addc_co_u32_e32 v9, vcc, 0, v49, vcc
	v_cvt_f32_f16_sdwa v49, v123 dst_sel:DWORD dst_unused:UNUSED_PAD src0_sel:WORD_1
	v_cvt_f32_f16_e32 v48, v123
	v_pk_fma_f32 v[0:1], v[188:189], v[12:13], v[220:221]
	v_pk_fma_f32 v[2:3], v[190:191], v[10:11], v[222:223]
	global_store_dwordx4 v[8:9], v[0:3], off
	s_nop 1
	s_nop 0
	v_pk_mul_f32 v[10:11], v[26:27], v[50:51] op_sel_hi:[1,0]
	v_pk_mul_f32 v[12:13], v[28:29], v[50:51] op_sel_hi:[1,0]
	v_pk_fma_f32 v[2:3], v[194:195], v[10:11], v[226:227]
	v_pk_fma_f32 v[0:1], v[192:193], v[12:13], v[224:225]
	global_store_dwordx4 v[8:9], v[0:3], off offset:16
	s_nop 1
	s_nop 0
	v_pk_mul_f32 v[10:11], v[46:47], v[50:51] op_sel_hi:[1,0]
	v_pk_mul_f32 v[12:13], v[30:31], v[50:51] op_sel_hi:[1,0]
	v_pk_fma_f32 v[2:3], v[198:199], v[10:11], v[230:231]
	v_pk_fma_f32 v[0:1], v[196:197], v[12:13], v[228:229]
	global_store_dwordx4 v[8:9], v[0:3], off offset:32
	s_nop 1
	s_nop 0
	v_lshl_add_u64 v[10:11], s[14:15], 0, v[42:43]
	v_pk_mul_f32 v[12:13], v[138:139], v[50:51] op_sel_hi:[1,0]
	v_lshlrev_b64 v[10:11], 1, v[10:11]
	v_lshl_add_u64 v[44:45], s[70:71], 0, v[10:11]
	v_lshl_add_u64 v[46:47], s[2:3], 0, v[10:11]
	v_cvt_f32_f16_sdwa v51, v122 dst_sel:DWORD dst_unused:UNUSED_PAD src0_sel:WORD_1
	v_cvt_f32_f16_e32 v50, v122
	s_add_u32 s14, s20, s0
	s_addc_u32 s15, s21, s1
	v_pk_fma_f32 v[0:1], v[200:201], v[14:15], v[232:233]
	v_pk_fma_f32 v[2:3], v[202:203], v[12:13], v[234:235]
	global_store_dwordx4 v[8:9], v[0:3], off offset:48
	s_nop 1
	global_load_dwordx4 v[4:7], v[44:45], off offset:2064
	s_nop 0
	global_load_dwordx4 v[0:3], v[46:47], off offset:2064
	global_load_dwordx4 v[28:31], v[44:45], off
	global_load_dwordx4 v[24:27], v[46:47], off
	global_load_dwordx4 v[20:23], v[44:45], off offset:16
	global_load_dwordx4 v[16:19], v[46:47], off offset:16
	global_load_dwordx4 v[12:15], v[44:45], off offset:2048
	global_load_dwordx4 v[8:11], v[46:47], off offset:2048
	v_cvt_f32_f16_sdwa v45, v125 dst_sel:DWORD dst_unused:UNUSED_PAD src0_sel:WORD_1
	v_cvt_f32_f16_e32 v44, v125
	v_cvt_f32_f16_sdwa v47, v124 dst_sel:DWORD dst_unused:UNUSED_PAD src0_sel:WORD_1
	v_cvt_f32_f16_e32 v46, v124
	s_waitcnt vmcnt(6)
	v_and_b32_e32 v123, 0xffff0000, v2
	v_lshlrev_b32_e32 v122, 16, v2
	s_waitcnt vmcnt(5)
	v_lshlrev_b32_e32 v124, 16, v28
	v_and_b32_e32 v125, 0xffff0000, v28
	s_waitcnt vmcnt(4)
	v_lshlrev_b32_e32 v126, 16, v24
	v_and_b32_e32 v121, 0xffff0000, v6
	v_lshlrev_b32_e32 v120, 16, v6
	v_and_b32_e32 v127, 0xffff0000, v24
	v_and_b32_e32 v129, 0xffff0000, v7
	v_lshlrev_b32_e32 v128, 16, v7
	v_and_b32_e32 v7, 0xffff0000, v3
	v_lshlrev_b32_e32 v6, 16, v3
	v_lshlrev_b32_e32 v2, 16, v30
	v_and_b32_e32 v3, 0xffff0000, v30
	v_lshlrev_b32_e32 v130, 16, v26
	v_and_b32_e32 v131, 0xffff0000, v26
	v_lshlrev_b32_e32 v30, 16, v31
	v_and_b32_e32 v31, 0xffff0000, v31
	v_lshlrev_b32_e32 v26, 16, v27
	v_and_b32_e32 v27, 0xffff0000, v27
	v_lshlrev_b32_e32 v166, 16, v4
	v_and_b32_e32 v167, 0xffff0000, v4
	v_lshlrev_b32_e32 v168, 16, v0
	v_and_b32_e32 v169, 0xffff0000, v0
	v_lshlrev_b32_e32 v4, 16, v5
	v_and_b32_e32 v5, 0xffff0000, v5
	v_lshlrev_b32_e32 v0, 16, v1
	v_and_b32_e32 v1, 0xffff0000, v1
	v_pk_fma_f32 v[120:121], v[120:121], s[6:7], v[122:123] op_sel_hi:[1,0,1]
	v_pk_fma_f32 v[122:123], v[124:125], s[6:7], v[126:127] op_sel_hi:[1,0,1]
	v_lshlrev_b32_e32 v28, 16, v29
	v_and_b32_e32 v29, 0xffff0000, v29
	v_lshlrev_b32_e32 v24, 16, v25
	v_and_b32_e32 v25, 0xffff0000, v25
	v_pk_fma_f32 v[6:7], v[128:129], s[6:7], v[6:7] op_sel_hi:[1,0,1]
	v_pk_fma_f32 v[26:27], v[30:31], s[6:7], v[26:27] op_sel_hi:[1,0,1]
	v_pk_fma_f32 v[0:1], v[4:5], s[6:7], v[0:1] op_sel_hi:[1,0,1]
	v_pk_add_f32 v[30:31], v[120:121], v[44:45]
	v_pk_add_f32 v[44:45], v[122:123], v[46:47]
	v_pk_fma_f32 v[24:25], v[28:29], s[6:7], v[24:25] op_sel_hi:[1,0,1]
	v_pk_add_f32 v[46:47], v[6:7], v[50:51]
	v_pk_add_f32 v[50:51], v[0:1], v[64:65]
	v_add_f32_e32 v0, 0, v44
	v_pk_add_f32 v[24:25], v[24:25], v[48:49]
	v_add_f32_e32 v0, v45, v0
	v_pk_fma_f32 v[2:3], v[2:3], s[6:7], v[130:131] op_sel_hi:[1,0,1]
	v_add_f32_e32 v0, v24, v0
	v_pk_add_f32 v[48:49], v[2:3], v[52:53]
	v_add_f32_e32 v0, v25, v0
	v_add_f32_e32 v0, v48, v0
	s_waitcnt vmcnt(3)
	v_lshlrev_b32_e32 v132, 16, v20
	v_and_b32_e32 v133, 0xffff0000, v20
	s_waitcnt vmcnt(2)
	v_lshlrev_b32_e32 v134, 16, v16
	v_and_b32_e32 v135, 0xffff0000, v16
	v_pk_add_f32 v[26:27], v[26:27], v[54:55]
	v_add_f32_e32 v0, v49, v0
	v_pk_fma_f32 v[28:29], v[132:133], s[6:7], v[134:135] op_sel_hi:[1,0,1]
	v_add_f32_e32 v0, v26, v0
	v_lshlrev_b32_e32 v20, 16, v21
	v_and_b32_e32 v21, 0xffff0000, v21
	v_lshlrev_b32_e32 v16, 16, v17
	v_and_b32_e32 v17, 0xffff0000, v17
	v_pk_add_f32 v[28:29], v[28:29], v[104:105]
	v_add_f32_e32 v0, v27, v0
	v_pk_fma_f32 v[16:17], v[20:21], s[6:7], v[16:17] op_sel_hi:[1,0,1]
	v_add_f32_e32 v0, v28, v0
	v_lshlrev_b32_e32 v136, 16, v22
	v_and_b32_e32 v137, 0xffff0000, v22
	v_lshlrev_b32_e32 v138, 16, v18
	v_and_b32_e32 v139, 0xffff0000, v18
	v_pk_add_f32 v[16:17], v[16:17], v[106:107]
	v_add_f32_e32 v0, v29, v0
	v_pk_fma_f32 v[20:21], v[136:137], s[6:7], v[138:139] op_sel_hi:[1,0,1]
	v_add_f32_e32 v0, v16, v0
	v_lshlrev_b32_e32 v22, 16, v23
	v_and_b32_e32 v23, 0xffff0000, v23
	v_lshlrev_b32_e32 v18, 16, v19
	v_and_b32_e32 v19, 0xffff0000, v19
	v_pk_add_f32 v[20:21], v[20:21], v[108:109]
	v_add_f32_e32 v0, v17, v0
	v_pk_fma_f32 v[18:19], v[22:23], s[6:7], v[18:19] op_sel_hi:[1,0,1]
	v_add_f32_e32 v0, v20, v0
	s_waitcnt vmcnt(1)
	v_lshlrev_b32_e32 v150, 16, v12
	v_and_b32_e32 v151, 0xffff0000, v12
	s_waitcnt vmcnt(0)
	v_lshlrev_b32_e32 v152, 16, v8
	v_and_b32_e32 v153, 0xffff0000, v8
	v_pk_add_f32 v[18:19], v[18:19], v[110:111]
	v_add_f32_e32 v0, v21, v0
	v_pk_fma_f32 v[22:23], v[150:151], s[6:7], v[152:153] op_sel_hi:[1,0,1]
	v_add_f32_e32 v0, v18, v0
	v_lshlrev_b32_e32 v12, 16, v13
	v_and_b32_e32 v13, 0xffff0000, v13
	v_lshlrev_b32_e32 v8, 16, v9
	v_and_b32_e32 v9, 0xffff0000, v9
	v_pk_add_f32 v[22:23], v[22:23], v[114:115]
	v_add_f32_e32 v0, v19, v0
	v_pk_fma_f32 v[8:9], v[12:13], s[6:7], v[8:9] op_sel_hi:[1,0,1]
	v_add_f32_e32 v0, v22, v0
	v_lshlrev_b32_e32 v154, 16, v14
	v_and_b32_e32 v155, 0xffff0000, v14
	v_lshlrev_b32_e32 v164, 16, v10
	v_and_b32_e32 v165, 0xffff0000, v10
	v_pk_add_f32 v[8:9], v[8:9], v[112:113]
	v_add_f32_e32 v0, v23, v0
	v_pk_fma_f32 v[12:13], v[154:155], s[6:7], v[164:165] op_sel_hi:[1,0,1]
	v_add_f32_e32 v0, v8, v0
	v_lshlrev_b32_e32 v14, 16, v15
	v_and_b32_e32 v15, 0xffff0000, v15
	v_lshlrev_b32_e32 v10, 16, v11
	v_and_b32_e32 v11, 0xffff0000, v11
	v_pk_add_f32 v[12:13], v[12:13], v[116:117]
	v_add_f32_e32 v0, v9, v0
	v_pk_fma_f32 v[10:11], v[14:15], s[6:7], v[10:11] op_sel_hi:[1,0,1]
	v_add_f32_e32 v0, v12, v0
	v_pk_add_f32 v[10:11], v[10:11], v[66:67]
	v_add_f32_e32 v0, v13, v0
	v_pk_fma_f32 v[14:15], v[166:167], s[6:7], v[168:169] op_sel_hi:[1,0,1]
	v_add_f32_e32 v0, v10, v0
	v_pk_add_f32 v[14:15], v[14:15], v[118:119]
	v_add_f32_e32 v0, v11, v0
	v_add_f32_e32 v0, v14, v0
	v_add_f32_e32 v0, v15, v0
	v_add_f32_e32 v0, v50, v0
	v_add_f32_e32 v0, v51, v0
	v_add_f32_e32 v0, v30, v0
	v_add_f32_e32 v0, v31, v0
	v_add_f32_e32 v0, v46, v0
	v_add_f32_e32 v0, v47, v0
	s_nop 1
	v_mov_b32_dpp v1, v0 quad_perm:[1,0,3,2] row_mask:0xf bank_mask:0xf
	s_waitcnt lgkmcnt(0)
	v_add_f32_e32 v0, v0, v1
	s_nop 1
	v_mov_b32_dpp v1, v0 quad_perm:[2,3,0,1] row_mask:0xf bank_mask:0xf
	s_waitcnt lgkmcnt(0)
	v_add_f32_e32 v0, v0, v1
	s_nop 1
	v_mov_b32_dpp v1, v0 row_half_mirror row_mask:0xf bank_mask:0xf
	s_waitcnt lgkmcnt(0)
	v_add_f32_e32 v0, v0, v1
	s_nop 1
	v_mov_b32_dpp v1, v0 row_mirror row_mask:0xf bank_mask:0xf
	s_waitcnt lgkmcnt(0)
	v_add_f32_e32 v0, v0, v1
	v_mov_b32_e32 v1, v0
	v_mov_b32_e32 v244, v0
	s_nop 1
	v_permlane16_swap_b32 v1, v244
	s_nop 1
	s_waitcnt lgkmcnt(0)
	v_add_f32_e32 v52, v1, v244
	v_mov_b32_e32 v53, v52
	v_mov_b32_e32 v244, v52
	s_nop 1
	v_permlane32_swap_b32 v53, v244
	s_nop 1
	s_waitcnt lgkmcnt(0)
	v_add_f32_e32 v52, v53, v244
	v_mul_f32_e32 v52, 0x3a000000, v52
	v_pk_add_f32 v[44:45], v[44:45], v[52:53] op_sel_hi:[1,0] neg_lo:[0,1] neg_hi:[0,1]
	v_pk_add_f32 v[24:25], v[24:25], v[52:53] op_sel_hi:[1,0] neg_lo:[0,1] neg_hi:[0,1]
	v_pk_add_f32 v[48:49], v[48:49], v[52:53] op_sel_hi:[1,0] neg_lo:[0,1] neg_hi:[0,1]
	v_pk_add_f32 v[26:27], v[26:27], v[52:53] op_sel_hi:[1,0] neg_lo:[0,1] neg_hi:[0,1]
	v_pk_add_f32 v[28:29], v[28:29], v[52:53] op_sel_hi:[1,0] neg_lo:[0,1] neg_hi:[0,1]
	v_pk_add_f32 v[16:17], v[16:17], v[52:53] op_sel_hi:[1,0] neg_lo:[0,1] neg_hi:[0,1]
	v_pk_add_f32 v[20:21], v[20:21], v[52:53] op_sel_hi:[1,0] neg_lo:[0,1] neg_hi:[0,1]
	v_pk_add_f32 v[18:19], v[18:19], v[52:53] op_sel_hi:[1,0] neg_lo:[0,1] neg_hi:[0,1]
	v_pk_add_f32 v[22:23], v[22:23], v[52:53] op_sel_hi:[1,0] neg_lo:[0,1] neg_hi:[0,1]
	v_pk_add_f32 v[8:9], v[8:9], v[52:53] op_sel_hi:[1,0] neg_lo:[0,1] neg_hi:[0,1]
	v_pk_add_f32 v[12:13], v[12:13], v[52:53] op_sel_hi:[1,0] neg_lo:[0,1] neg_hi:[0,1]
	v_pk_add_f32 v[10:11], v[10:11], v[52:53] op_sel_hi:[1,0] neg_lo:[0,1] neg_hi:[0,1]
	v_pk_add_f32 v[14:15], v[14:15], v[52:53] op_sel_hi:[1,0] neg_lo:[0,1] neg_hi:[0,1]
	v_pk_add_f32 v[50:51], v[50:51], v[52:53] op_sel_hi:[1,0] neg_lo:[0,1] neg_hi:[0,1]
	v_pk_add_f32 v[46:47], v[46:47], v[52:53] op_sel_hi:[1,0] neg_lo:[0,1] neg_hi:[0,1]
	v_pk_add_f32 v[30:31], v[30:31], v[52:53] op_sel_hi:[1,0] neg_lo:[0,1] neg_hi:[0,1]
	v_pk_mul_f32 v[52:53], v[44:45], v[44:45]
	v_pk_mul_f32 v[54:55], v[24:25], v[24:25]
	v_add_f32_e32 v52, v52, v53
	v_add_f32_e32 v52, v54, v52
	v_pk_mul_f32 v[64:65], v[48:49], v[48:49]
	v_add_f32_e32 v52, v55, v52
	v_add_f32_e32 v52, v64, v52
	v_pk_mul_f32 v[66:67], v[26:27], v[26:27]
	v_add_f32_e32 v52, v65, v52
	v_add_f32_e32 v52, v66, v52
	v_pk_mul_f32 v[104:105], v[28:29], v[28:29]
	v_add_f32_e32 v52, v67, v52
	v_add_f32_e32 v52, v104, v52
	v_pk_mul_f32 v[106:107], v[16:17], v[16:17]
	v_add_f32_e32 v52, v105, v52
	v_add_f32_e32 v52, v106, v52
	v_pk_mul_f32 v[108:109], v[20:21], v[20:21]
	v_add_f32_e32 v52, v107, v52
	v_add_f32_e32 v52, v108, v52
	v_pk_mul_f32 v[110:111], v[18:19], v[18:19]
	v_add_f32_e32 v52, v109, v52
	v_add_f32_e32 v52, v110, v52
	v_pk_mul_f32 v[112:113], v[22:23], v[22:23]
	v_add_f32_e32 v52, v111, v52
	v_add_f32_e32 v52, v112, v52
	v_pk_mul_f32 v[114:115], v[8:9], v[8:9]
	v_add_f32_e32 v52, v113, v52
	v_add_f32_e32 v52, v114, v52
	v_pk_mul_f32 v[116:117], v[12:13], v[12:13]
	v_add_f32_e32 v52, v115, v52
	v_add_f32_e32 v52, v116, v52
	v_pk_mul_f32 v[118:119], v[10:11], v[10:11]
	v_add_f32_e32 v52, v117, v52
	v_add_f32_e32 v52, v118, v52
	v_pk_mul_f32 v[120:121], v[14:15], v[14:15]
	v_add_f32_e32 v52, v119, v52
	v_add_f32_e32 v52, v120, v52
	v_pk_mul_f32 v[122:123], v[50:51], v[50:51]
	v_add_f32_e32 v52, v121, v52
	v_add_f32_e32 v52, v122, v52
	v_pk_mul_f32 v[126:127], v[30:31], v[30:31]
	v_add_f32_e32 v52, v123, v52
	v_add_f32_e32 v52, v126, v52
	v_pk_mul_f32 v[124:125], v[46:47], v[46:47]
	v_add_f32_e32 v52, v127, v52
	v_add_f32_e32 v52, v124, v52
	v_add_f32_e32 v52, v125, v52
	s_nop 1
	v_mov_b32_dpp v53, v52 quad_perm:[1,0,3,2] row_mask:0xf bank_mask:0xf
	s_waitcnt lgkmcnt(0)
	v_add_f32_e32 v52, v52, v53
	s_nop 1
	v_mov_b32_dpp v53, v52 quad_perm:[2,3,0,1] row_mask:0xf bank_mask:0xf
	s_waitcnt lgkmcnt(0)
	v_add_f32_e32 v52, v52, v53
	s_nop 1
	v_mov_b32_dpp v53, v52 row_half_mirror row_mask:0xf bank_mask:0xf
	s_waitcnt lgkmcnt(0)
	v_add_f32_e32 v52, v52, v53
	s_nop 1
	v_mov_b32_dpp v53, v52 row_mirror row_mask:0xf bank_mask:0xf
	s_waitcnt lgkmcnt(0)
	v_add_f32_e32 v52, v52, v53
	v_mov_b32_e32 v53, v52
	v_mov_b32_e32 v244, v52
	s_nop 1
	v_permlane16_swap_b32 v53, v244
	s_nop 1
	s_waitcnt lgkmcnt(0)
	v_add_f32_e32 v52, v53, v244
	v_mov_b32_e32 v53, v52
	v_mov_b32_e32 v244, v52
	s_nop 1
	v_permlane32_swap_b32 v53, v244
	s_nop 1
	s_waitcnt lgkmcnt(0)
	v_add_f32_e32 v52, v53, v244
	v_fmamk_f32 v52, v52, 0x3a000000, v101
	v_mul_f32_e32 v53, 0x4f800000, v52
	v_cmp_gt_f32_e32 vcc, s7, v52
	s_nop 1
	v_cndmask_b32_e32 v52, v52, v53, vcc
	v_sqrt_f32_e32 v53, v52
	s_nop 0
	v_add_u32_e32 v54, -1, v53
	v_add_u32_e32 v55, 1, v53
	v_fma_f32 v64, -v54, v53, v52
	v_fma_f32 v65, -v55, v53, v52
	v_cmp_ge_f32_e64 s[0:1], 0, v64
	s_nop 1
	v_cndmask_b32_e64 v53, v53, v54, s[0:1]
	v_cmp_lt_f32_e64 s[0:1], 0, v65
	s_nop 1
	v_cndmask_b32_e64 v53, v53, v55, s[0:1]
	v_mul_f32_e32 v54, 0x37800000, v53
	v_cndmask_b32_e32 v53, v53, v54, vcc
	v_cmp_class_f32_e32 vcc, v52, v102
	s_nop 1
	v_cndmask_b32_e32 v54, v53, v52, vcc
	v_div_scale_f32 v55, s[0:1], v54, v54, 1.0
	v_rcp_f32_e32 v64, v55
	v_div_scale_f32 v65, vcc, 1.0, v54, 1.0
	v_lshl_add_u64 v[52:53], s[14:15], 0, v[36:37]
	v_fma_f32 v66, -v55, v64, 1.0
	v_fmac_f32_e32 v64, v66, v64
	v_mul_f32_e32 v66, v65, v64
	v_fma_f32 v67, -v55, v66, v65
	v_fmac_f32_e32 v66, v67, v64
	v_fma_f32 v55, -v55, v66, v65
	v_div_fmas_f32 v55, v55, v64, v66
	v_div_fixup_f32 v54, v55, v54, 1.0
	v_pk_mul_f32 v[44:45], v[44:45], v[54:55] op_sel_hi:[1,0]
	v_pk_mul_f32 v[24:25], v[24:25], v[54:55] op_sel_hi:[1,0]
	v_pk_fma_f32 v[0:1], v[172:173], v[44:45], v[204:205]
	v_pk_fma_f32 v[2:3], v[174:175], v[24:25], v[206:207]
	global_store_dwordx4 v[52:53], v[0:3], off
	s_nop 1
	s_nop 0
	v_pk_mul_f32 v[24:25], v[26:27], v[54:55] op_sel_hi:[1,0]
	v_pk_mul_f32 v[26:27], v[48:49], v[54:55] op_sel_hi:[1,0]
	v_pk_mul_f32 v[16:17], v[16:17], v[54:55] op_sel_hi:[1,0]
	v_pk_mul_f32 v[8:9], v[8:9], v[54:55] op_sel_hi:[1,0]
	s_or_b32 s0, s10, 2
	s_ashr_i32 s1, s0, 31
	s_lshl_b64 s[14:15], s[0:1], 11
	v_cvt_f32_f16_sdwa v49, v73 dst_sel:DWORD dst_unused:UNUSED_PAD src0_sel:WORD_1
	v_cvt_f32_f16_e32 v48, v73
	v_cvt_f32_f16_sdwa v65, v69 dst_sel:DWORD dst_unused:UNUSED_PAD src0_sel:WORD_1
	v_cvt_f32_f16_e32 v64, v69
	v_cvt_f32_f16_sdwa v67, v68 dst_sel:DWORD dst_unused:UNUSED_PAD src0_sel:WORD_1
	v_cvt_f32_f16_e32 v66, v68
	v_cvt_f32_f16_sdwa v69, v63 dst_sel:DWORD dst_unused:UNUSED_PAD src0_sel:WORD_1
	v_cvt_f32_f16_e32 v68, v63
	v_cvt_f32_f16_sdwa v63, v62 dst_sel:DWORD dst_unused:UNUSED_PAD src0_sel:WORD_1
	v_cvt_f32_f16_e32 v62, v62
	v_cvt_f32_f16_sdwa v73, v59 dst_sel:DWORD dst_unused:UNUSED_PAD src0_sel:WORD_1
	s_lshl_b64 s[0:1], s[0:1], 13
	v_pk_fma_f32 v[0:1], v[176:177], v[26:27], v[208:209]
	v_pk_fma_f32 v[2:3], v[178:179], v[24:25], v[210:211]
	global_store_dwordx4 v[52:53], v[0:3], off offset:16
	s_nop 1
	s_nop 0
	v_pk_mul_f32 v[24:25], v[28:29], v[54:55] op_sel_hi:[1,0]
	v_pk_fma_f32 v[2:3], v[182:183], v[16:17], v[214:215]
	v_pk_fma_f32 v[0:1], v[180:181], v[24:25], v[212:213]
	global_store_dwordx4 v[52:53], v[0:3], off offset:32
	s_nop 1
	s_nop 0
	v_pk_mul_f32 v[16:17], v[18:19], v[54:55] op_sel_hi:[1,0]
	v_pk_mul_f32 v[18:19], v[20:21], v[54:55] op_sel_hi:[1,0]
	v_pk_fma_f32 v[2:3], v[186:187], v[16:17], v[218:219]
	v_pk_fma_f32 v[0:1], v[184:185], v[18:19], v[216:217]
	global_store_dwordx4 v[52:53], v[0:3], off offset:48
	s_nop 1
	s_nop 0
	v_add_co_u32_e32 v16, vcc, s12, v52
	v_pk_mul_f32 v[18:19], v[22:23], v[54:55] op_sel_hi:[1,0]
	s_nop 0
	v_addc_co_u32_e32 v17, vcc, 0, v53, vcc
	v_cvt_f32_f16_sdwa v53, v71 dst_sel:DWORD dst_unused:UNUSED_PAD src0_sel:WORD_1
	v_cvt_f32_f16_e32 v52, v71
	v_cvt_f32_f16_sdwa v71, v61 dst_sel:DWORD dst_unused:UNUSED_PAD src0_sel:WORD_1
	v_pk_fma_f32 v[0:1], v[188:189], v[18:19], v[220:221]
	v_pk_fma_f32 v[2:3], v[190:191], v[8:9], v[222:223]
	global_store_dwordx4 v[16:17], v[0:3], off
	s_nop 1
	s_nop 0
	v_pk_mul_f32 v[8:9], v[10:11], v[54:55] op_sel_hi:[1,0]
	v_pk_mul_f32 v[10:11], v[12:13], v[54:55] op_sel_hi:[1,0]
	v_pk_mul_f32 v[12:13], v[30:31], v[54:55] op_sel_hi:[1,0]
	v_pk_fma_f32 v[0:1], v[192:193], v[10:11], v[224:225]
	v_pk_fma_f32 v[2:3], v[194:195], v[8:9], v[226:227]
	global_store_dwordx4 v[16:17], v[0:3], off offset:16
	s_nop 1
	s_nop 0
	v_pk_mul_f32 v[8:9], v[50:51], v[54:55] op_sel_hi:[1,0]
	v_pk_mul_f32 v[10:11], v[14:15], v[54:55] op_sel_hi:[1,0]
	v_cvt_f32_f16_sdwa v51, v72 dst_sel:DWORD dst_unused:UNUSED_PAD src0_sel:WORD_1
	v_cvt_f32_f16_e32 v50, v72
	v_cvt_f32_f16_e32 v72, v59
	v_cvt_f32_f16_sdwa v59, v58 dst_sel:DWORD dst_unused:UNUSED_PAD src0_sel:WORD_1
	v_cvt_f32_f16_e32 v58, v58
	v_pk_fma_f32 v[0:1], v[196:197], v[10:11], v[228:229]
	v_pk_fma_f32 v[2:3], v[198:199], v[8:9], v[230:231]
	global_store_dwordx4 v[16:17], v[0:3], off offset:32
	s_nop 1
	s_nop 0
	v_lshl_add_u64 v[8:9], s[14:15], 0, v[42:43]
	v_pk_mul_f32 v[10:11], v[46:47], v[54:55] op_sel_hi:[1,0]
	v_lshlrev_b64 v[8:9], 1, v[8:9]
	v_lshl_add_u64 v[44:45], s[70:71], 0, v[8:9]
	v_lshl_add_u64 v[46:47], s[2:3], 0, v[8:9]
	v_cvt_f32_f16_sdwa v55, v70 dst_sel:DWORD dst_unused:UNUSED_PAD src0_sel:WORD_1
	v_cvt_f32_f16_e32 v54, v70
	v_cvt_f32_f16_e32 v70, v61
	v_cvt_f32_f16_sdwa v61, v60 dst_sel:DWORD dst_unused:UNUSED_PAD src0_sel:WORD_1
	v_cvt_f32_f16_e32 v60, v60
	s_add_u32 s14, s20, s0
	s_addc_u32 s15, s21, s1
	v_pk_fma_f32 v[0:1], v[200:201], v[12:13], v[232:233]
	v_pk_fma_f32 v[2:3], v[202:203], v[10:11], v[234:235]
	global_store_dwordx4 v[16:17], v[0:3], off offset:48
	s_nop 1
	global_load_dwordx4 v[4:7], v[44:45], off offset:2064
	s_nop 0
	global_load_dwordx4 v[0:3], v[46:47], off offset:2064
	global_load_dwordx4 v[28:31], v[44:45], off
	global_load_dwordx4 v[24:27], v[46:47], off
	global_load_dwordx4 v[20:23], v[44:45], off offset:16
	global_load_dwordx4 v[16:19], v[46:47], off offset:16
	global_load_dwordx4 v[12:15], v[44:45], off offset:2048
	global_load_dwordx4 v[8:11], v[46:47], off offset:2048
	v_cvt_f32_f16_sdwa v45, v75 dst_sel:DWORD dst_unused:UNUSED_PAD src0_sel:WORD_1
	v_cvt_f32_f16_e32 v44, v75
	v_cvt_f32_f16_sdwa v47, v74 dst_sel:DWORD dst_unused:UNUSED_PAD src0_sel:WORD_1
	v_cvt_f32_f16_e32 v46, v74
	v_cvt_f32_f16_sdwa v75, v57 dst_sel:DWORD dst_unused:UNUSED_PAD src0_sel:WORD_1
	v_cvt_f32_f16_e32 v74, v57
	v_cvt_f32_f16_sdwa v57, v56 dst_sel:DWORD dst_unused:UNUSED_PAD src0_sel:WORD_1
	v_cvt_f32_f16_e32 v56, v56
	s_waitcnt vmcnt(6)
	v_and_b32_e32 v107, 0xffff0000, v2
	v_lshlrev_b32_e32 v106, 16, v2
	s_waitcnt vmcnt(5)
	v_lshlrev_b32_e32 v108, 16, v28
	v_and_b32_e32 v109, 0xffff0000, v28
	s_waitcnt vmcnt(4)
	v_lshlrev_b32_e32 v110, 16, v24
	v_and_b32_e32 v105, 0xffff0000, v6
	v_lshlrev_b32_e32 v104, 16, v6
	v_and_b32_e32 v111, 0xffff0000, v24
	v_and_b32_e32 v113, 0xffff0000, v7
	v_lshlrev_b32_e32 v112, 16, v7
	v_and_b32_e32 v7, 0xffff0000, v3
	v_lshlrev_b32_e32 v6, 16, v3
	v_lshlrev_b32_e32 v2, 16, v30
	v_and_b32_e32 v3, 0xffff0000, v30
	v_lshlrev_b32_e32 v114, 16, v26
	v_and_b32_e32 v115, 0xffff0000, v26
	v_lshlrev_b32_e32 v30, 16, v31
	v_and_b32_e32 v31, 0xffff0000, v31
	v_lshlrev_b32_e32 v26, 16, v27
	v_and_b32_e32 v27, 0xffff0000, v27
	v_lshlrev_b32_e32 v132, 16, v4
	v_and_b32_e32 v133, 0xffff0000, v4
	v_lshlrev_b32_e32 v134, 16, v0
	v_and_b32_e32 v135, 0xffff0000, v0
	v_lshlrev_b32_e32 v4, 16, v5
	v_and_b32_e32 v5, 0xffff0000, v5
	v_lshlrev_b32_e32 v0, 16, v1
	v_and_b32_e32 v1, 0xffff0000, v1
	v_pk_fma_f32 v[104:105], v[104:105], s[6:7], v[106:107] op_sel_hi:[1,0,1]
	v_pk_fma_f32 v[106:107], v[108:109], s[6:7], v[110:111] op_sel_hi:[1,0,1]
	v_lshlrev_b32_e32 v28, 16, v29
	v_and_b32_e32 v29, 0xffff0000, v29
	v_lshlrev_b32_e32 v24, 16, v25
	v_and_b32_e32 v25, 0xffff0000, v25
	v_pk_fma_f32 v[6:7], v[112:113], s[6:7], v[6:7] op_sel_hi:[1,0,1]
	v_pk_fma_f32 v[26:27], v[30:31], s[6:7], v[26:27] op_sel_hi:[1,0,1]
	v_pk_fma_f32 v[0:1], v[4:5], s[6:7], v[0:1] op_sel_hi:[1,0,1]
	v_pk_add_f32 v[30:31], v[104:105], v[44:45]
	v_pk_add_f32 v[44:45], v[106:107], v[46:47]
	v_pk_fma_f32 v[24:25], v[28:29], s[6:7], v[24:25] op_sel_hi:[1,0,1]
	v_pk_add_f32 v[46:47], v[6:7], v[50:51]
	v_pk_add_f32 v[50:51], v[0:1], v[56:57]
	v_add_f32_e32 v0, 0, v44
	v_pk_add_f32 v[24:25], v[24:25], v[48:49]
	v_add_f32_e32 v0, v45, v0
	v_pk_fma_f32 v[2:3], v[2:3], s[6:7], v[114:115] op_sel_hi:[1,0,1]
	v_add_f32_e32 v0, v24, v0
	v_pk_add_f32 v[48:49], v[2:3], v[52:53]
	v_add_f32_e32 v0, v25, v0
	v_add_f32_e32 v0, v48, v0
	s_waitcnt vmcnt(3)
	v_lshlrev_b32_e32 v116, 16, v20
	v_and_b32_e32 v117, 0xffff0000, v20
	s_waitcnt vmcnt(2)
	v_lshlrev_b32_e32 v118, 16, v16
	v_and_b32_e32 v119, 0xffff0000, v16
	v_pk_add_f32 v[26:27], v[26:27], v[54:55]
	v_add_f32_e32 v0, v49, v0
	v_pk_fma_f32 v[28:29], v[116:117], s[6:7], v[118:119] op_sel_hi:[1,0,1]
	v_add_f32_e32 v0, v26, v0
	v_lshlrev_b32_e32 v20, 16, v21
	v_and_b32_e32 v21, 0xffff0000, v21
	v_lshlrev_b32_e32 v16, 16, v17
	v_and_b32_e32 v17, 0xffff0000, v17
	v_pk_add_f32 v[28:29], v[28:29], v[64:65]
	v_add_f32_e32 v0, v27, v0
	v_pk_fma_f32 v[16:17], v[20:21], s[6:7], v[16:17] op_sel_hi:[1,0,1]
	v_add_f32_e32 v0, v28, v0
	v_lshlrev_b32_e32 v120, 16, v22
	v_and_b32_e32 v121, 0xffff0000, v22
	v_lshlrev_b32_e32 v122, 16, v18
	v_and_b32_e32 v123, 0xffff0000, v18
	v_pk_add_f32 v[16:17], v[16:17], v[66:67]
	v_add_f32_e32 v0, v29, v0
	v_pk_fma_f32 v[20:21], v[120:121], s[6:7], v[122:123] op_sel_hi:[1,0,1]
	v_add_f32_e32 v0, v16, v0
	v_lshlrev_b32_e32 v22, 16, v23
	v_and_b32_e32 v23, 0xffff0000, v23
	v_lshlrev_b32_e32 v18, 16, v19
	v_and_b32_e32 v19, 0xffff0000, v19
	v_pk_add_f32 v[20:21], v[20:21], v[68:69]
	v_add_f32_e32 v0, v17, v0
	v_pk_fma_f32 v[18:19], v[22:23], s[6:7], v[18:19] op_sel_hi:[1,0,1]
	v_add_f32_e32 v0, v20, v0
	s_waitcnt vmcnt(1)
	v_lshlrev_b32_e32 v124, 16, v12
	v_and_b32_e32 v125, 0xffff0000, v12
	s_waitcnt vmcnt(0)
	v_lshlrev_b32_e32 v126, 16, v8
	v_and_b32_e32 v127, 0xffff0000, v8
	v_pk_add_f32 v[18:19], v[18:19], v[62:63]
	v_add_f32_e32 v0, v21, v0
	v_pk_fma_f32 v[22:23], v[124:125], s[6:7], v[126:127] op_sel_hi:[1,0,1]
	v_add_f32_e32 v0, v18, v0
	v_lshlrev_b32_e32 v12, 16, v13
	v_and_b32_e32 v13, 0xffff0000, v13
	v_lshlrev_b32_e32 v8, 16, v9
	v_and_b32_e32 v9, 0xffff0000, v9
	v_pk_add_f32 v[22:23], v[22:23], v[70:71]
	v_add_f32_e32 v0, v19, v0
	v_pk_fma_f32 v[8:9], v[12:13], s[6:7], v[8:9] op_sel_hi:[1,0,1]
	v_add_f32_e32 v0, v22, v0
	v_lshlrev_b32_e32 v128, 16, v14
	v_and_b32_e32 v129, 0xffff0000, v14
	v_lshlrev_b32_e32 v130, 16, v10
	v_and_b32_e32 v131, 0xffff0000, v10
	v_pk_add_f32 v[8:9], v[8:9], v[60:61]
	v_add_f32_e32 v0, v23, v0
	v_pk_fma_f32 v[12:13], v[128:129], s[6:7], v[130:131] op_sel_hi:[1,0,1]
	v_add_f32_e32 v0, v8, v0
	v_lshlrev_b32_e32 v14, 16, v15
	v_and_b32_e32 v15, 0xffff0000, v15
	v_lshlrev_b32_e32 v10, 16, v11
	v_and_b32_e32 v11, 0xffff0000, v11
	v_pk_add_f32 v[12:13], v[12:13], v[72:73]
	v_add_f32_e32 v0, v9, v0
	v_pk_fma_f32 v[10:11], v[14:15], s[6:7], v[10:11] op_sel_hi:[1,0,1]
	v_add_f32_e32 v0, v12, v0
	v_pk_add_f32 v[10:11], v[10:11], v[58:59]
	v_add_f32_e32 v0, v13, v0
	v_pk_fma_f32 v[14:15], v[132:133], s[6:7], v[134:135] op_sel_hi:[1,0,1]
	v_add_f32_e32 v0, v10, v0
	v_pk_add_f32 v[14:15], v[14:15], v[74:75]
	v_add_f32_e32 v0, v11, v0
	v_add_f32_e32 v0, v14, v0
	v_add_f32_e32 v0, v15, v0
	v_add_f32_e32 v0, v50, v0
	v_add_f32_e32 v0, v51, v0
	v_add_f32_e32 v0, v30, v0
	v_add_f32_e32 v0, v31, v0
	v_add_f32_e32 v0, v46, v0
	v_add_f32_e32 v0, v47, v0
	s_nop 1
	v_mov_b32_dpp v1, v0 quad_perm:[1,0,3,2] row_mask:0xf bank_mask:0xf
	s_waitcnt lgkmcnt(0)
	v_add_f32_e32 v0, v0, v1
	s_nop 1
	v_mov_b32_dpp v1, v0 quad_perm:[2,3,0,1] row_mask:0xf bank_mask:0xf
	s_waitcnt lgkmcnt(0)
	v_add_f32_e32 v0, v0, v1
	s_nop 1
	v_mov_b32_dpp v1, v0 row_half_mirror row_mask:0xf bank_mask:0xf
	s_waitcnt lgkmcnt(0)
	v_add_f32_e32 v0, v0, v1
	s_nop 1
	v_mov_b32_dpp v1, v0 row_mirror row_mask:0xf bank_mask:0xf
	s_waitcnt lgkmcnt(0)
	v_add_f32_e32 v0, v0, v1
	v_mov_b32_e32 v1, v0
	v_mov_b32_e32 v244, v0
	s_nop 1
	v_permlane16_swap_b32 v1, v244
	s_nop 1
	s_waitcnt lgkmcnt(0)
	v_add_f32_e32 v52, v1, v244
	v_mov_b32_e32 v53, v52
	v_mov_b32_e32 v244, v52
	s_nop 1
	v_permlane32_swap_b32 v53, v244
	s_nop 1
	s_waitcnt lgkmcnt(0)
	v_add_f32_e32 v52, v53, v244
	v_mul_f32_e32 v52, 0x3a000000, v52
	v_pk_add_f32 v[44:45], v[44:45], v[52:53] op_sel_hi:[1,0] neg_lo:[0,1] neg_hi:[0,1]
	v_pk_add_f32 v[24:25], v[24:25], v[52:53] op_sel_hi:[1,0] neg_lo:[0,1] neg_hi:[0,1]
	v_pk_add_f32 v[48:49], v[48:49], v[52:53] op_sel_hi:[1,0] neg_lo:[0,1] neg_hi:[0,1]
	v_pk_add_f32 v[26:27], v[26:27], v[52:53] op_sel_hi:[1,0] neg_lo:[0,1] neg_hi:[0,1]
	v_pk_add_f32 v[28:29], v[28:29], v[52:53] op_sel_hi:[1,0] neg_lo:[0,1] neg_hi:[0,1]
	v_pk_add_f32 v[16:17], v[16:17], v[52:53] op_sel_hi:[1,0] neg_lo:[0,1] neg_hi:[0,1]
	v_pk_add_f32 v[20:21], v[20:21], v[52:53] op_sel_hi:[1,0] neg_lo:[0,1] neg_hi:[0,1]
	v_pk_add_f32 v[18:19], v[18:19], v[52:53] op_sel_hi:[1,0] neg_lo:[0,1] neg_hi:[0,1]
	v_pk_add_f32 v[22:23], v[22:23], v[52:53] op_sel_hi:[1,0] neg_lo:[0,1] neg_hi:[0,1]
	v_pk_add_f32 v[8:9], v[8:9], v[52:53] op_sel_hi:[1,0] neg_lo:[0,1] neg_hi:[0,1]
	v_pk_add_f32 v[12:13], v[12:13], v[52:53] op_sel_hi:[1,0] neg_lo:[0,1] neg_hi:[0,1]
	v_pk_add_f32 v[10:11], v[10:11], v[52:53] op_sel_hi:[1,0] neg_lo:[0,1] neg_hi:[0,1]
	v_pk_add_f32 v[14:15], v[14:15], v[52:53] op_sel_hi:[1,0] neg_lo:[0,1] neg_hi:[0,1]
	v_pk_add_f32 v[50:51], v[50:51], v[52:53] op_sel_hi:[1,0] neg_lo:[0,1] neg_hi:[0,1]
	v_pk_add_f32 v[46:47], v[46:47], v[52:53] op_sel_hi:[1,0] neg_lo:[0,1] neg_hi:[0,1]
	v_pk_add_f32 v[30:31], v[30:31], v[52:53] op_sel_hi:[1,0] neg_lo:[0,1] neg_hi:[0,1]
	v_pk_mul_f32 v[52:53], v[44:45], v[44:45]
	v_pk_mul_f32 v[54:55], v[24:25], v[24:25]
	v_add_f32_e32 v52, v52, v53
	v_add_f32_e32 v52, v54, v52
	v_pk_mul_f32 v[56:57], v[48:49], v[48:49]
	v_add_f32_e32 v52, v55, v52
	v_add_f32_e32 v52, v56, v52
	v_pk_mul_f32 v[58:59], v[26:27], v[26:27]
	v_add_f32_e32 v52, v57, v52
	v_add_f32_e32 v52, v58, v52
	v_pk_mul_f32 v[60:61], v[28:29], v[28:29]
	v_add_f32_e32 v52, v59, v52
	v_add_f32_e32 v52, v60, v52
	v_pk_mul_f32 v[62:63], v[16:17], v[16:17]
	v_add_f32_e32 v52, v61, v52
	v_add_f32_e32 v52, v62, v52
	v_pk_mul_f32 v[64:65], v[20:21], v[20:21]
	v_add_f32_e32 v52, v63, v52
	v_add_f32_e32 v52, v64, v52
	v_pk_mul_f32 v[66:67], v[18:19], v[18:19]
	v_add_f32_e32 v52, v65, v52
	v_add_f32_e32 v52, v66, v52
	v_pk_mul_f32 v[68:69], v[22:23], v[22:23]
	v_add_f32_e32 v52, v67, v52
	v_add_f32_e32 v52, v68, v52
	v_pk_mul_f32 v[70:71], v[8:9], v[8:9]
	v_add_f32_e32 v52, v69, v52
	v_add_f32_e32 v52, v70, v52
	v_pk_mul_f32 v[72:73], v[12:13], v[12:13]
	v_add_f32_e32 v52, v71, v52
	v_add_f32_e32 v52, v72, v52
	v_pk_mul_f32 v[74:75], v[10:11], v[10:11]
	v_add_f32_e32 v52, v73, v52
	v_add_f32_e32 v52, v74, v52
	v_pk_mul_f32 v[104:105], v[14:15], v[14:15]
	v_add_f32_e32 v52, v75, v52
	v_add_f32_e32 v52, v104, v52
	v_pk_mul_f32 v[106:107], v[50:51], v[50:51]
	v_add_f32_e32 v52, v105, v52
	v_add_f32_e32 v52, v106, v52
	v_pk_mul_f32 v[110:111], v[30:31], v[30:31]
	v_add_f32_e32 v52, v107, v52
	v_add_f32_e32 v52, v110, v52
	v_pk_mul_f32 v[108:109], v[46:47], v[46:47]
	v_add_f32_e32 v52, v111, v52
	v_add_f32_e32 v52, v108, v52
	v_add_f32_e32 v52, v109, v52
	s_nop 1
	v_mov_b32_dpp v53, v52 quad_perm:[1,0,3,2] row_mask:0xf bank_mask:0xf
	v_cvt_f32_f16_sdwa v73, v141 dst_sel:DWORD dst_unused:UNUSED_PAD src0_sel:WORD_1
	v_cvt_f32_f16_e32 v72, v141
	v_cvt_f32_f16_sdwa v61, v147 dst_sel:DWORD dst_unused:UNUSED_PAD src0_sel:WORD_1
	v_cvt_f32_f16_e32 v60, v147
	s_waitcnt lgkmcnt(0)
	v_add_f32_e32 v52, v52, v53
	s_nop 1
	v_mov_b32_dpp v53, v52 quad_perm:[2,3,0,1] row_mask:0xf bank_mask:0xf
	v_cvt_f32_f16_sdwa v63, v146 dst_sel:DWORD dst_unused:UNUSED_PAD src0_sel:WORD_1
	v_cvt_f32_f16_e32 v62, v146
	v_cvt_f32_f16_sdwa v65, v145 dst_sel:DWORD dst_unused:UNUSED_PAD src0_sel:WORD_1
	v_cvt_f32_f16_e32 v64, v145
	s_waitcnt lgkmcnt(0)
	v_add_f32_e32 v52, v52, v53
	s_nop 1
	v_mov_b32_dpp v53, v52 row_half_mirror row_mask:0xf bank_mask:0xf
	v_cvt_f32_f16_sdwa v67, v144 dst_sel:DWORD dst_unused:UNUSED_PAD src0_sel:WORD_1
	v_cvt_f32_f16_e32 v66, v144
	v_cvt_f32_f16_sdwa v69, v143 dst_sel:DWORD dst_unused:UNUSED_PAD src0_sel:WORD_1
	v_cvt_f32_f16_e32 v68, v143
	s_waitcnt lgkmcnt(0)
	v_add_f32_e32 v52, v52, v53
	s_nop 1
	v_mov_b32_dpp v53, v52 row_mirror row_mask:0xf bank_mask:0xf
	v_cvt_f32_f16_sdwa v71, v142 dst_sel:DWORD dst_unused:UNUSED_PAD src0_sel:WORD_1
	v_cvt_f32_f16_e32 v70, v142
	s_waitcnt lgkmcnt(0)
	v_add_f32_e32 v52, v52, v53
	v_mov_b32_e32 v53, v52
	v_mov_b32_e32 v244, v52
	s_nop 1
	v_permlane16_swap_b32 v53, v244
	s_nop 1
	s_waitcnt lgkmcnt(0)
	v_add_f32_e32 v52, v53, v244
	v_mov_b32_e32 v53, v52
	v_mov_b32_e32 v244, v52
	s_nop 1
	v_permlane32_swap_b32 v53, v244
	s_nop 1
	s_waitcnt lgkmcnt(0)
	v_add_f32_e32 v52, v53, v244
	v_fmamk_f32 v52, v52, 0x3a000000, v101
	v_mul_f32_e32 v53, 0x4f800000, v52
	v_cmp_gt_f32_e32 vcc, s7, v52
	s_nop 1
	v_cndmask_b32_e32 v52, v52, v53, vcc
	v_sqrt_f32_e32 v53, v52
	s_nop 0
	v_add_u32_e32 v54, -1, v53
	v_add_u32_e32 v55, 1, v53
	v_fma_f32 v56, -v54, v53, v52
	v_fma_f32 v57, -v55, v53, v52
	v_cmp_ge_f32_e64 s[0:1], 0, v56
	s_nop 1
	v_cndmask_b32_e64 v53, v53, v54, s[0:1]
	v_cmp_lt_f32_e64 s[0:1], 0, v57
	s_nop 1
	v_cndmask_b32_e64 v53, v53, v55, s[0:1]
	v_mul_f32_e32 v54, 0x37800000, v53
	v_cndmask_b32_e32 v53, v53, v54, vcc
	v_cmp_class_f32_e32 vcc, v52, v102
	s_nop 1
	v_cndmask_b32_e32 v54, v53, v52, vcc
	v_div_scale_f32 v55, s[0:1], v54, v54, 1.0
	v_rcp_f32_e32 v56, v55
	v_div_scale_f32 v57, vcc, 1.0, v54, 1.0
	v_lshl_add_u64 v[52:53], s[14:15], 0, v[36:37]
	v_fma_f32 v58, -v55, v56, 1.0
	v_fmac_f32_e32 v56, v58, v56
	v_mul_f32_e32 v58, v57, v56
	v_fma_f32 v59, -v55, v58, v57
	v_fmac_f32_e32 v58, v59, v56
	v_fma_f32 v55, -v55, v58, v57
	v_div_fmas_f32 v55, v55, v56, v58
	v_div_fixup_f32 v54, v55, v54, 1.0
	v_pk_mul_f32 v[44:45], v[44:45], v[54:55] op_sel_hi:[1,0]
	v_pk_mul_f32 v[24:25], v[24:25], v[54:55] op_sel_hi:[1,0]
	v_pk_fma_f32 v[0:1], v[172:173], v[44:45], v[204:205]
	v_pk_fma_f32 v[2:3], v[174:175], v[24:25], v[206:207]
	global_store_dwordx4 v[52:53], v[0:3], off
	s_nop 1
	s_nop 0
	v_pk_mul_f32 v[24:25], v[26:27], v[54:55] op_sel_hi:[1,0]
	v_pk_mul_f32 v[26:27], v[48:49], v[54:55] op_sel_hi:[1,0]
	v_pk_mul_f32 v[16:17], v[16:17], v[54:55] op_sel_hi:[1,0]
	v_pk_mul_f32 v[8:9], v[8:9], v[54:55] op_sel_hi:[1,0]
	s_or_b32 s0, s10, 3
	s_ashr_i32 s1, s0, 31
	s_lshl_b64 s[10:11], s[0:1], 11
	v_cvt_f32_f16_sdwa v49, v148 dst_sel:DWORD dst_unused:UNUSED_PAD src0_sel:WORD_1
	v_cvt_f32_f16_e32 v48, v148
	v_cvt_f32_f16_sdwa v57, v157 dst_sel:DWORD dst_unused:UNUSED_PAD src0_sel:WORD_1
	v_cvt_f32_f16_e32 v56, v157
	v_cvt_f32_f16_sdwa v59, v156 dst_sel:DWORD dst_unused:UNUSED_PAD src0_sel:WORD_1
	v_cvt_f32_f16_e32 v58, v156
	s_lshl_b64 s[0:1], s[0:1], 13
	v_pk_fma_f32 v[0:1], v[176:177], v[26:27], v[208:209]
	v_pk_fma_f32 v[2:3], v[178:179], v[24:25], v[210:211]
	global_store_dwordx4 v[52:53], v[0:3], off offset:16
	s_nop 1
	s_nop 0
	v_pk_mul_f32 v[24:25], v[28:29], v[54:55] op_sel_hi:[1,0]
	v_pk_fma_f32 v[2:3], v[182:183], v[16:17], v[214:215]
	v_pk_fma_f32 v[0:1], v[180:181], v[24:25], v[212:213]
	global_store_dwordx4 v[52:53], v[0:3], off offset:32
	s_nop 1
	s_nop 0
	v_pk_mul_f32 v[16:17], v[18:19], v[54:55] op_sel_hi:[1,0]
	v_pk_mul_f32 v[18:19], v[20:21], v[54:55] op_sel_hi:[1,0]
	v_pk_fma_f32 v[2:3], v[186:187], v[16:17], v[218:219]
	v_pk_fma_f32 v[0:1], v[184:185], v[18:19], v[216:217]
	global_store_dwordx4 v[52:53], v[0:3], off offset:48
	s_nop 1
	s_nop 0
	v_add_co_u32_e32 v16, vcc, s12, v52
	v_pk_mul_f32 v[18:19], v[22:23], v[54:55] op_sel_hi:[1,0]
	s_nop 0
	v_addc_co_u32_e32 v17, vcc, 0, v53, vcc
	v_cvt_f32_f16_sdwa v53, v159 dst_sel:DWORD dst_unused:UNUSED_PAD src0_sel:WORD_1
	v_cvt_f32_f16_e32 v52, v159
	v_pk_fma_f32 v[0:1], v[188:189], v[18:19], v[220:221]
	v_pk_fma_f32 v[2:3], v[190:191], v[8:9], v[222:223]
	global_store_dwordx4 v[16:17], v[0:3], off
	s_nop 1
	s_nop 0
	v_pk_mul_f32 v[8:9], v[10:11], v[54:55] op_sel_hi:[1,0]
	v_pk_mul_f32 v[10:11], v[12:13], v[54:55] op_sel_hi:[1,0]
	v_pk_mul_f32 v[12:13], v[30:31], v[54:55] op_sel_hi:[1,0]
	v_pk_fma_f32 v[0:1], v[192:193], v[10:11], v[224:225]
	v_pk_fma_f32 v[2:3], v[194:195], v[8:9], v[226:227]
	global_store_dwordx4 v[16:17], v[0:3], off offset:16
	s_nop 1
	s_nop 0
	v_pk_mul_f32 v[8:9], v[50:51], v[54:55] op_sel_hi:[1,0]
	v_pk_mul_f32 v[10:11], v[14:15], v[54:55] op_sel_hi:[1,0]
	v_cvt_f32_f16_sdwa v51, v160 dst_sel:DWORD dst_unused:UNUSED_PAD src0_sel:WORD_1
	v_cvt_f32_f16_e32 v50, v160
	v_pk_fma_f32 v[0:1], v[196:197], v[10:11], v[228:229]
	v_pk_fma_f32 v[2:3], v[198:199], v[8:9], v[230:231]
	global_store_dwordx4 v[16:17], v[0:3], off offset:32
	s_nop 1
	s_nop 0
	v_lshl_add_u64 v[8:9], s[10:11], 0, v[42:43]
	v_pk_mul_f32 v[10:11], v[46:47], v[54:55] op_sel_hi:[1,0]
	v_lshlrev_b64 v[8:9], 1, v[8:9]
	v_lshl_add_u64 v[42:43], s[70:71], 0, v[8:9]
	v_lshl_add_u64 v[44:45], s[2:3], 0, v[8:9]
	v_cvt_f32_f16_sdwa v47, v161 dst_sel:DWORD dst_unused:UNUSED_PAD src0_sel:WORD_1
	v_cvt_f32_f16_e32 v46, v161
	v_cvt_f32_f16_sdwa v55, v158 dst_sel:DWORD dst_unused:UNUSED_PAD src0_sel:WORD_1
	v_cvt_f32_f16_e32 v54, v158
	s_add_u32 s10, s20, s0
	s_addc_u32 s11, s21, s1
	v_lshl_add_u64 v[36:37], s[10:11], 0, v[36:37]
	s_mov_b32 s10, 1
	v_pk_fma_f32 v[0:1], v[200:201], v[12:13], v[232:233]
	v_pk_fma_f32 v[2:3], v[202:203], v[10:11], v[234:235]
	global_store_dwordx4 v[16:17], v[0:3], off offset:48
	s_nop 1
	global_load_dwordx4 v[4:7], v[42:43], off offset:2064
	s_nop 0
	global_load_dwordx4 v[0:3], v[44:45], off offset:2064
	global_load_dwordx4 v[28:31], v[42:43], off
	global_load_dwordx4 v[24:27], v[44:45], off
	global_load_dwordx4 v[20:23], v[42:43], off offset:16
	global_load_dwordx4 v[16:19], v[44:45], off offset:16
	global_load_dwordx4 v[12:15], v[42:43], off offset:2048
	global_load_dwordx4 v[8:11], v[44:45], off offset:2048
	v_cvt_f32_f16_sdwa v43, v149 dst_sel:DWORD dst_unused:UNUSED_PAD src0_sel:WORD_1
	v_cvt_f32_f16_e32 v42, v149
	v_cvt_f32_f16_sdwa v45, v162 dst_sel:DWORD dst_unused:UNUSED_PAD src0_sel:WORD_1
	v_cvt_f32_f16_e32 v44, v162
	s_waitcnt vmcnt(6)
	v_and_b32_e32 v105, 0xffff0000, v2
	v_lshlrev_b32_e32 v104, 16, v2
	s_waitcnt vmcnt(5)
	v_lshlrev_b32_e32 v106, 16, v28
	v_and_b32_e32 v107, 0xffff0000, v28
	s_waitcnt vmcnt(4)
	v_lshlrev_b32_e32 v108, 16, v24
	v_and_b32_e32 v75, 0xffff0000, v6
	v_lshlrev_b32_e32 v74, 16, v6
	v_and_b32_e32 v109, 0xffff0000, v24
	v_and_b32_e32 v111, 0xffff0000, v7
	v_lshlrev_b32_e32 v110, 16, v7
	v_and_b32_e32 v7, 0xffff0000, v3
	v_lshlrev_b32_e32 v6, 16, v3
	v_lshlrev_b32_e32 v2, 16, v30
	v_and_b32_e32 v3, 0xffff0000, v30
	v_lshlrev_b32_e32 v112, 16, v26
	v_and_b32_e32 v113, 0xffff0000, v26
	v_lshlrev_b32_e32 v30, 16, v31
	v_and_b32_e32 v31, 0xffff0000, v31
	v_lshlrev_b32_e32 v26, 16, v27
	v_and_b32_e32 v27, 0xffff0000, v27
	v_lshlrev_b32_e32 v130, 16, v4
	v_and_b32_e32 v131, 0xffff0000, v4
	v_lshlrev_b32_e32 v132, 16, v0
	v_and_b32_e32 v133, 0xffff0000, v0
	v_lshlrev_b32_e32 v4, 16, v5
	v_and_b32_e32 v5, 0xffff0000, v5
	v_lshlrev_b32_e32 v0, 16, v1
	v_and_b32_e32 v1, 0xffff0000, v1
	v_pk_fma_f32 v[74:75], v[74:75], s[6:7], v[104:105] op_sel_hi:[1,0,1]
	v_pk_fma_f32 v[104:105], v[106:107], s[6:7], v[108:109] op_sel_hi:[1,0,1]
	v_lshlrev_b32_e32 v28, 16, v29
	v_and_b32_e32 v29, 0xffff0000, v29
	v_lshlrev_b32_e32 v24, 16, v25
	v_and_b32_e32 v25, 0xffff0000, v25
	v_pk_fma_f32 v[6:7], v[110:111], s[6:7], v[6:7] op_sel_hi:[1,0,1]
	v_pk_fma_f32 v[26:27], v[30:31], s[6:7], v[26:27] op_sel_hi:[1,0,1]
	v_pk_fma_f32 v[0:1], v[4:5], s[6:7], v[0:1] op_sel_hi:[1,0,1]
	v_pk_add_f32 v[30:31], v[74:75], v[42:43]
	v_pk_add_f32 v[42:43], v[104:105], v[44:45]
	v_pk_fma_f32 v[24:25], v[28:29], s[6:7], v[24:25] op_sel_hi:[1,0,1]
	v_pk_add_f32 v[44:45], v[6:7], v[48:49]
	v_pk_add_f32 v[48:49], v[0:1], v[72:73]
	v_add_f32_e32 v0, 0, v42
	v_pk_add_f32 v[24:25], v[24:25], v[46:47]
	v_add_f32_e32 v0, v43, v0
	v_pk_fma_f32 v[2:3], v[2:3], s[6:7], v[112:113] op_sel_hi:[1,0,1]
	v_add_f32_e32 v0, v24, v0
	v_pk_add_f32 v[46:47], v[2:3], v[50:51]
	v_add_f32_e32 v0, v25, v0
	v_add_f32_e32 v0, v46, v0
	s_waitcnt vmcnt(3)
	v_lshlrev_b32_e32 v114, 16, v20
	v_and_b32_e32 v115, 0xffff0000, v20
	s_waitcnt vmcnt(2)
	v_lshlrev_b32_e32 v116, 16, v16
	v_and_b32_e32 v117, 0xffff0000, v16
	v_pk_add_f32 v[26:27], v[26:27], v[52:53]
	v_add_f32_e32 v0, v47, v0
	v_pk_fma_f32 v[28:29], v[114:115], s[6:7], v[116:117] op_sel_hi:[1,0,1]
	v_add_f32_e32 v0, v26, v0
	v_lshlrev_b32_e32 v20, 16, v21
	v_and_b32_e32 v21, 0xffff0000, v21
	v_lshlrev_b32_e32 v16, 16, v17
	v_and_b32_e32 v17, 0xffff0000, v17
	v_pk_add_f32 v[28:29], v[28:29], v[54:55]
	v_add_f32_e32 v0, v27, v0
	v_pk_fma_f32 v[16:17], v[20:21], s[6:7], v[16:17] op_sel_hi:[1,0,1]
	v_add_f32_e32 v0, v28, v0
	v_lshlrev_b32_e32 v118, 16, v22
	v_and_b32_e32 v119, 0xffff0000, v22
	v_lshlrev_b32_e32 v120, 16, v18
	v_and_b32_e32 v121, 0xffff0000, v18
	v_pk_add_f32 v[16:17], v[16:17], v[56:57]
	v_add_f32_e32 v0, v29, v0
	v_pk_fma_f32 v[20:21], v[118:119], s[6:7], v[120:121] op_sel_hi:[1,0,1]
	v_add_f32_e32 v0, v16, v0
	v_lshlrev_b32_e32 v22, 16, v23
	v_and_b32_e32 v23, 0xffff0000, v23
	v_lshlrev_b32_e32 v18, 16, v19
	v_and_b32_e32 v19, 0xffff0000, v19
	v_pk_add_f32 v[20:21], v[20:21], v[58:59]
	v_add_f32_e32 v0, v17, v0
	v_pk_fma_f32 v[18:19], v[22:23], s[6:7], v[18:19] op_sel_hi:[1,0,1]
	v_add_f32_e32 v0, v20, v0
	s_waitcnt vmcnt(1)
	v_lshlrev_b32_e32 v122, 16, v12
	v_and_b32_e32 v123, 0xffff0000, v12
	s_waitcnt vmcnt(0)
	v_lshlrev_b32_e32 v124, 16, v8
	v_and_b32_e32 v125, 0xffff0000, v8
	v_pk_add_f32 v[18:19], v[18:19], v[60:61]
	v_add_f32_e32 v0, v21, v0
	v_pk_fma_f32 v[22:23], v[122:123], s[6:7], v[124:125] op_sel_hi:[1,0,1]
	v_add_f32_e32 v0, v18, v0
	v_lshlrev_b32_e32 v12, 16, v13
	v_and_b32_e32 v13, 0xffff0000, v13
	v_lshlrev_b32_e32 v8, 16, v9
	v_and_b32_e32 v9, 0xffff0000, v9
	v_pk_add_f32 v[22:23], v[22:23], v[62:63]
	v_add_f32_e32 v0, v19, v0
	v_pk_fma_f32 v[8:9], v[12:13], s[6:7], v[8:9] op_sel_hi:[1,0,1]
	v_add_f32_e32 v0, v22, v0
	v_lshlrev_b32_e32 v126, 16, v14
	v_and_b32_e32 v127, 0xffff0000, v14
	v_lshlrev_b32_e32 v128, 16, v10
	v_and_b32_e32 v129, 0xffff0000, v10
	v_pk_add_f32 v[8:9], v[8:9], v[64:65]
	v_add_f32_e32 v0, v23, v0
	v_pk_fma_f32 v[12:13], v[126:127], s[6:7], v[128:129] op_sel_hi:[1,0,1]
	v_add_f32_e32 v0, v8, v0
	v_lshlrev_b32_e32 v14, 16, v15
	v_and_b32_e32 v15, 0xffff0000, v15
	v_lshlrev_b32_e32 v10, 16, v11
	v_and_b32_e32 v11, 0xffff0000, v11
	v_pk_add_f32 v[12:13], v[12:13], v[66:67]
	v_add_f32_e32 v0, v9, v0
	v_pk_fma_f32 v[10:11], v[14:15], s[6:7], v[10:11] op_sel_hi:[1,0,1]
	v_add_f32_e32 v0, v12, v0
	v_pk_add_f32 v[10:11], v[10:11], v[68:69]
	v_add_f32_e32 v0, v13, v0
	v_pk_fma_f32 v[14:15], v[130:131], s[6:7], v[132:133] op_sel_hi:[1,0,1]
	v_add_f32_e32 v0, v10, v0
	v_pk_add_f32 v[14:15], v[14:15], v[70:71]
	v_add_f32_e32 v0, v11, v0
	v_add_f32_e32 v0, v14, v0
	v_add_f32_e32 v0, v15, v0
	v_add_f32_e32 v0, v48, v0
	v_add_f32_e32 v0, v49, v0
	v_add_f32_e32 v0, v30, v0
	v_add_f32_e32 v0, v31, v0
	v_add_f32_e32 v0, v44, v0
	v_add_f32_e32 v0, v45, v0
	s_nop 1
	v_mov_b32_dpp v1, v0 quad_perm:[1,0,3,2] row_mask:0xf bank_mask:0xf
	s_waitcnt lgkmcnt(0)
	v_add_f32_e32 v0, v0, v1
	s_nop 1
	v_mov_b32_dpp v1, v0 quad_perm:[2,3,0,1] row_mask:0xf bank_mask:0xf
	s_waitcnt lgkmcnt(0)
	v_add_f32_e32 v0, v0, v1
	s_nop 1
	v_mov_b32_dpp v1, v0 row_half_mirror row_mask:0xf bank_mask:0xf
	s_waitcnt lgkmcnt(0)
	v_add_f32_e32 v0, v0, v1
	s_nop 1
	v_mov_b32_dpp v1, v0 row_mirror row_mask:0xf bank_mask:0xf
	s_waitcnt lgkmcnt(0)
	v_add_f32_e32 v0, v0, v1
	v_mov_b32_e32 v1, v0
	v_mov_b32_e32 v244, v0
	s_nop 1
	v_permlane16_swap_b32 v1, v244
	s_nop 1
	s_waitcnt lgkmcnt(0)
	v_add_f32_e32 v50, v1, v244
	v_mov_b32_e32 v51, v50
	v_mov_b32_e32 v244, v50
	s_nop 1
	v_permlane32_swap_b32 v51, v244
	s_nop 1
	s_waitcnt lgkmcnt(0)
	v_add_f32_e32 v50, v51, v244
	v_mul_f32_e32 v50, 0x3a000000, v50
	v_pk_add_f32 v[42:43], v[42:43], v[50:51] op_sel_hi:[1,0] neg_lo:[0,1] neg_hi:[0,1]
	v_pk_add_f32 v[24:25], v[24:25], v[50:51] op_sel_hi:[1,0] neg_lo:[0,1] neg_hi:[0,1]
	v_pk_add_f32 v[46:47], v[46:47], v[50:51] op_sel_hi:[1,0] neg_lo:[0,1] neg_hi:[0,1]
	v_pk_add_f32 v[26:27], v[26:27], v[50:51] op_sel_hi:[1,0] neg_lo:[0,1] neg_hi:[0,1]
	v_pk_add_f32 v[28:29], v[28:29], v[50:51] op_sel_hi:[1,0] neg_lo:[0,1] neg_hi:[0,1]
	v_pk_add_f32 v[16:17], v[16:17], v[50:51] op_sel_hi:[1,0] neg_lo:[0,1] neg_hi:[0,1]
	v_pk_add_f32 v[20:21], v[20:21], v[50:51] op_sel_hi:[1,0] neg_lo:[0,1] neg_hi:[0,1]
	v_pk_add_f32 v[18:19], v[18:19], v[50:51] op_sel_hi:[1,0] neg_lo:[0,1] neg_hi:[0,1]
	v_pk_add_f32 v[22:23], v[22:23], v[50:51] op_sel_hi:[1,0] neg_lo:[0,1] neg_hi:[0,1]
	v_pk_add_f32 v[8:9], v[8:9], v[50:51] op_sel_hi:[1,0] neg_lo:[0,1] neg_hi:[0,1]
	v_pk_add_f32 v[12:13], v[12:13], v[50:51] op_sel_hi:[1,0] neg_lo:[0,1] neg_hi:[0,1]
	v_pk_add_f32 v[10:11], v[10:11], v[50:51] op_sel_hi:[1,0] neg_lo:[0,1] neg_hi:[0,1]
	v_pk_add_f32 v[14:15], v[14:15], v[50:51] op_sel_hi:[1,0] neg_lo:[0,1] neg_hi:[0,1]
	v_pk_add_f32 v[48:49], v[48:49], v[50:51] op_sel_hi:[1,0] neg_lo:[0,1] neg_hi:[0,1]
	v_pk_add_f32 v[44:45], v[44:45], v[50:51] op_sel_hi:[1,0] neg_lo:[0,1] neg_hi:[0,1]
	v_pk_add_f32 v[30:31], v[30:31], v[50:51] op_sel_hi:[1,0] neg_lo:[0,1] neg_hi:[0,1]
	v_pk_mul_f32 v[50:51], v[42:43], v[42:43]
	v_pk_mul_f32 v[52:53], v[24:25], v[24:25]
	v_add_f32_e32 v50, v50, v51
	v_add_f32_e32 v50, v52, v50
	v_pk_mul_f32 v[54:55], v[46:47], v[46:47]
	v_add_f32_e32 v50, v53, v50
	v_add_f32_e32 v50, v54, v50
	v_pk_mul_f32 v[56:57], v[26:27], v[26:27]
	v_add_f32_e32 v50, v55, v50
	v_add_f32_e32 v50, v56, v50
	v_pk_mul_f32 v[58:59], v[28:29], v[28:29]
	v_add_f32_e32 v50, v57, v50
	v_add_f32_e32 v50, v58, v50
	v_pk_mul_f32 v[60:61], v[16:17], v[16:17]
	v_add_f32_e32 v50, v59, v50
	v_add_f32_e32 v50, v60, v50
	v_pk_mul_f32 v[62:63], v[20:21], v[20:21]
	v_add_f32_e32 v50, v61, v50
	v_add_f32_e32 v50, v62, v50
	v_pk_mul_f32 v[64:65], v[18:19], v[18:19]
	v_add_f32_e32 v50, v63, v50
	v_add_f32_e32 v50, v64, v50
	v_pk_mul_f32 v[66:67], v[22:23], v[22:23]
	v_add_f32_e32 v50, v65, v50
	v_add_f32_e32 v50, v66, v50
	v_pk_mul_f32 v[68:69], v[8:9], v[8:9]
	v_add_f32_e32 v50, v67, v50
	v_add_f32_e32 v50, v68, v50
	v_pk_mul_f32 v[70:71], v[12:13], v[12:13]
	v_add_f32_e32 v50, v69, v50
	v_add_f32_e32 v50, v70, v50
	v_pk_mul_f32 v[72:73], v[10:11], v[10:11]
	v_add_f32_e32 v50, v71, v50
	v_add_f32_e32 v50, v72, v50
	v_pk_mul_f32 v[74:75], v[14:15], v[14:15]
	v_add_f32_e32 v50, v73, v50
	v_add_f32_e32 v50, v74, v50
	v_pk_mul_f32 v[104:105], v[48:49], v[48:49]
	v_add_f32_e32 v50, v75, v50
	v_add_f32_e32 v50, v104, v50
	v_pk_mul_f32 v[108:109], v[30:31], v[30:31]
	v_add_f32_e32 v50, v105, v50
	v_add_f32_e32 v50, v108, v50
	v_pk_mul_f32 v[106:107], v[44:45], v[44:45]
	v_add_f32_e32 v50, v109, v50
	v_add_f32_e32 v50, v106, v50
	v_add_f32_e32 v50, v107, v50
	s_nop 1
	v_mov_b32_dpp v51, v50 quad_perm:[1,0,3,2] row_mask:0xf bank_mask:0xf
	s_waitcnt lgkmcnt(0)
	v_add_f32_e32 v50, v50, v51
	s_nop 1
	v_mov_b32_dpp v51, v50 quad_perm:[2,3,0,1] row_mask:0xf bank_mask:0xf
	s_waitcnt lgkmcnt(0)
	v_add_f32_e32 v50, v50, v51
	s_nop 1
	v_mov_b32_dpp v51, v50 row_half_mirror row_mask:0xf bank_mask:0xf
	s_waitcnt lgkmcnt(0)
	v_add_f32_e32 v50, v50, v51
	s_nop 1
	v_mov_b32_dpp v51, v50 row_mirror row_mask:0xf bank_mask:0xf
	s_waitcnt lgkmcnt(0)
	v_add_f32_e32 v50, v50, v51
	v_mov_b32_e32 v51, v50
	v_mov_b32_e32 v244, v50
	s_nop 1
	v_permlane16_swap_b32 v51, v244
	s_nop 1
	s_waitcnt lgkmcnt(0)
	v_add_f32_e32 v50, v51, v244
	v_mov_b32_e32 v51, v50
	v_mov_b32_e32 v244, v50
	s_nop 1
	v_permlane32_swap_b32 v51, v244
	s_nop 1
	s_waitcnt lgkmcnt(0)
	v_add_f32_e32 v50, v51, v244
	v_fmamk_f32 v50, v50, 0x3a000000, v101
	v_mul_f32_e32 v51, 0x4f800000, v50
	v_cmp_gt_f32_e32 vcc, s7, v50
	s_nop 1
	v_cndmask_b32_e32 v50, v50, v51, vcc
	v_sqrt_f32_e32 v51, v50
	s_nop 0
	v_add_u32_e32 v52, -1, v51
	v_add_u32_e32 v53, 1, v51
	v_fma_f32 v54, -v52, v51, v50
	v_fma_f32 v55, -v53, v51, v50
	v_cmp_ge_f32_e64 s[0:1], 0, v54
	s_nop 1
	v_cndmask_b32_e64 v51, v51, v52, s[0:1]
	v_cmp_lt_f32_e64 s[0:1], 0, v55
	s_nop 1
	v_cndmask_b32_e64 v51, v51, v53, s[0:1]
	v_mul_f32_e32 v52, 0x37800000, v51
	v_cndmask_b32_e32 v51, v51, v52, vcc
	v_cmp_class_f32_e32 vcc, v50, v102
	s_nop 1
	v_cndmask_b32_e32 v50, v51, v50, vcc
	v_div_scale_f32 v51, s[0:1], v50, v50, 1.0
	v_rcp_f32_e32 v52, v51
	v_div_scale_f32 v53, vcc, 1.0, v50, 1.0
	s_mov_b64 s[0:1], 0
	v_fma_f32 v54, -v51, v52, 1.0
	v_fmac_f32_e32 v52, v54, v52
	v_mul_f32_e32 v54, v53, v52
	v_fma_f32 v55, -v51, v54, v53
	v_fmac_f32_e32 v54, v55, v52
	v_fma_f32 v51, -v51, v54, v53
	v_div_fmas_f32 v51, v51, v52, v54
	v_div_fixup_f32 v50, v51, v50, 1.0
	v_pk_mul_f32 v[42:43], v[42:43], v[50:51] op_sel_hi:[1,0]
	v_pk_mul_f32 v[24:25], v[24:25], v[50:51] op_sel_hi:[1,0]
	v_pk_fma_f32 v[0:1], v[172:173], v[42:43], v[204:205]
	v_pk_fma_f32 v[2:3], v[174:175], v[24:25], v[206:207]
	global_store_dwordx4 v[36:37], v[0:3], off
	s_nop 1
	s_nop 0
	v_pk_mul_f32 v[24:25], v[26:27], v[50:51] op_sel_hi:[1,0]
	v_pk_mul_f32 v[26:27], v[46:47], v[50:51] op_sel_hi:[1,0]
	v_pk_mul_f32 v[16:17], v[16:17], v[50:51] op_sel_hi:[1,0]
	v_pk_mul_f32 v[8:9], v[8:9], v[50:51] op_sel_hi:[1,0]
	v_pk_fma_f32 v[0:1], v[176:177], v[26:27], v[208:209]
	v_pk_fma_f32 v[2:3], v[178:179], v[24:25], v[210:211]
	global_store_dwordx4 v[36:37], v[0:3], off offset:16
	s_nop 1
	s_nop 0
	v_pk_mul_f32 v[24:25], v[28:29], v[50:51] op_sel_hi:[1,0]
	v_pk_fma_f32 v[2:3], v[182:183], v[16:17], v[214:215]
	v_pk_fma_f32 v[0:1], v[180:181], v[24:25], v[212:213]
	global_store_dwordx4 v[36:37], v[0:3], off offset:32
	s_nop 1
	s_nop 0
	v_pk_mul_f32 v[16:17], v[18:19], v[50:51] op_sel_hi:[1,0]
	v_pk_mul_f32 v[18:19], v[20:21], v[50:51] op_sel_hi:[1,0]
	v_pk_fma_f32 v[2:3], v[186:187], v[16:17], v[218:219]
	v_pk_fma_f32 v[0:1], v[184:185], v[18:19], v[216:217]
	global_store_dwordx4 v[36:37], v[0:3], off offset:48
	s_nop 1
	s_nop 0
	v_add_co_u32_e32 v16, vcc, s12, v36
	v_pk_mul_f32 v[18:19], v[22:23], v[50:51] op_sel_hi:[1,0]
	s_nop 0
	v_addc_co_u32_e32 v17, vcc, 0, v37, vcc
	s_and_b64 vcc, exec, s[8:9]
	v_pk_fma_f32 v[0:1], v[188:189], v[18:19], v[220:221]
	v_pk_fma_f32 v[2:3], v[190:191], v[8:9], v[222:223]
	global_store_dwordx4 v[16:17], v[0:3], off
	s_nop 1
	s_nop 0
	v_pk_mul_f32 v[8:9], v[10:11], v[50:51] op_sel_hi:[1,0]
	v_pk_mul_f32 v[10:11], v[12:13], v[50:51] op_sel_hi:[1,0]
	v_pk_fma_f32 v[2:3], v[194:195], v[8:9], v[226:227]
	v_pk_fma_f32 v[0:1], v[192:193], v[10:11], v[224:225]
	global_store_dwordx4 v[16:17], v[0:3], off offset:16
	s_nop 1
	s_nop 0
	v_pk_mul_f32 v[8:9], v[48:49], v[50:51] op_sel_hi:[1,0]
	v_pk_mul_f32 v[10:11], v[14:15], v[50:51] op_sel_hi:[1,0]
	v_pk_fma_f32 v[2:3], v[198:199], v[8:9], v[230:231]
	v_pk_fma_f32 v[0:1], v[196:197], v[10:11], v[228:229]
	global_store_dwordx4 v[16:17], v[0:3], off offset:32
	s_nop 1
	s_nop 0
	v_pk_mul_f32 v[8:9], v[44:45], v[50:51] op_sel_hi:[1,0]
	v_pk_mul_f32 v[10:11], v[30:31], v[50:51] op_sel_hi:[1,0]
	v_pk_fma_f32 v[2:3], v[202:203], v[8:9], v[234:235]
	v_pk_fma_f32 v[0:1], v[200:201], v[10:11], v[232:233]
	global_store_dwordx4 v[16:17], v[0:3], off offset:48
	s_nop 1
	s_waitcnt vmcnt(0)
	s_cbranch_vccz .LBB0_1012
